# hand-written row-norm phases: 8-row units per wave, params hoisted into VGPRs, 3-row-ahead prefetch, DPP wave reductions
# speedup vs baseline: 1.0462x; 1.0396x over previous
; template <bool BR, bool WH> ...
;     const int gw = F.bid * 8 + F.wave, NGW = F.G * 8, lane = F.lane;
;     f32x4 xc[4], xn[4]; u32x2 bc[4], bn[4];
;     ...
;     if (gw >= nrows) return;
; __global__ void __launch_bounds__(512, 2) fwd_kernel(Params prm) {
;     ...
;         if (ph == 1) { norm_phase<false, true>(F, MT, prm.in[0], prm.in[2], nullptr, nullptr, nullptr, nullptr, 0, nullptr, nullptr, prm.in[6], MOD, 1024, 0, RY); continue; }
;         const int l = (ph - 2) / 9, sp = (ph - 2) % 9;
;         const bool lastl = (l == 1);
;         bf16_t* Hl = l == 0 ? RY : RX; bf16_t* XRb = l == 0 ? RX : RY;
;         bf16_t* HF = Hl; bf16_t* Gb = XRb; bf16_t* H2 = RX;
;         const int Mg = lastl ? ML : MT;
;         const float* xres_lat = l == 0 ? prm.in[0] : prm.out; const float* xres_ctx = l == 0 ? prm.in[2] : ctxres;
;         const float* modl = MOD + (size_t)l * 5 * 6144;
;         switch (sp) {
;         case 0: { pg8::PlainOrder S; S.tm.init(MT, INW, F.G, F.bid); S.A = (const char*)Hl; S.B = (const char*)(ws + OFF_W + W_WIN); S.tsA = (size_t)256 * 1024 * 2; S.tsB = (size_t)256 * 1024 * 2; S.nt = 16;
;                   pg8::EpiInProj E{XRb, GRb, Qb, KVb, GLb, (const float*)(ws + OFF_TAB)}; pg8::gemm_phase<false>(F.lds, F.tid, 1024, 1024, 1024, S, E); } break;
;         case 1: { rglru_phase<1>(F, l, XRb, GRb); } break;
;         case 2: { attn_phase(F, l, Qb, Qb, KVb, !lastl); __syncthreads(); rglru_phase<2>(F, l, XRb, GRb, lastl); } break;
;         case 3: { pg8::ChainOrder S; S.tm.init(ML, 1024, F.G, F.bid); S.G = F.G; S.c = F.bid; S.nslice = lastl ? 0 : 64;
;                   S.A0 = (const char*)GRb; S.B0 = (const char*)(ws + OFF_W + W_WOR); S.A1 = (const char*)Qb; S.B1 = (const char*)(ws + OFF_W + W_WOA);
;                   S.tsA = (size_t)256 * 1024 * 2; S.tsB = (size_t)256 * 1024 * 2; S.nt = 16;
;                   pg8::EpiMerge E{GLb, Gb, Hl};
;                   pg8::gemm_phase<true>(F.lds, F.tid, 1024, 1024, 1024, S, E); } break;
;         case 4: { if (!lastl) {
;                       const bf16_t* SLg = Hl; bf16_t* Gc = Gb + (size_t)ML * 1024;
;                       for (int i = F.bid * 512 + F.tid; i < 1024 * 1024 / 8; i += F.G * 512) { f32x4 a0 = {0.f, 0.f, 0.f, 0.f}, a1 = a0;
; #pragma unroll
;                           for (int sl = 0; sl < 4; ++sl) { const u32x4 w = *(const u32x4*)(SLg + (size_t)sl * (1024 * 1024) + (size_t)i * 8);
.Lnrm_ph1:
	v_mbcnt_lo_u32_b32 v1, -1, 0
	v_mbcnt_hi_u32_b32 v1, -1, v1
	v_readlane_b32 s0, v252, 1
	v_readlane_b32 s1, v252, 2
	v_lshlrev_b32_e32 v0, 4, v1
	v_lshlrev_b32_e32 v1, 3, v1
	v_mov_b32_e32 v2, 0x3a800000
	v_mov_b32_e32 v3, 0x358637bd
	s_load_dwordx2 s[40:41], s[0:1], 0xc8
	s_load_dwordx2 s[42:43], s[0:1], 0xc0
	s_load_dword s27, s[0:1], 0xd8
	v_readlane_b32 s2, v252, 7
	v_readlane_b32 s88, v252, 0
	s_waitcnt lgkmcnt(0)
	s_mul_i32 s2, s2, s27
	s_add_u32 s2, s2, s88
	s_lshl_b32 s27, s27, 3
	s_load_dwordx2 s[44:45], s[0:1], 0x0
	s_load_dwordx2 s[48:49], s[0:1], 0x10
	s_load_dwordx2 s[24:25], s[0:1], 0x30
	s_waitcnt lgkmcnt(0)
	s_add_u32 s56, s40, 0xd57c000
	s_addc_u32 s57, s41, 0
	s_movk_i32 s59, 0x1000
	s_mov_b32 s73, 0
	s_branch .Lnrm_bodyA
.Lnrm_sp5a:
	v_mbcnt_lo_u32_b32 v1, -1, 0
	v_mbcnt_hi_u32_b32 v1, -1, v1
	v_readlane_b32 s0, v252, 1
	v_readlane_b32 s1, v252, 2
	v_lshlrev_b32_e32 v0, 4, v1
	v_lshlrev_b32_e32 v1, 3, v1
	v_mov_b32_e32 v2, 0x3a800000
	v_mov_b32_e32 v3, 0x358637bd
	s_load_dwordx2 s[40:41], s[0:1], 0xc8
	s_load_dwordx2 s[42:43], s[0:1], 0xc0
	s_load_dword s27, s[0:1], 0xd8
	v_readlane_b32 s2, v252, 7
	v_readlane_b32 s88, v252, 0
	s_waitcnt lgkmcnt(0)
	s_mul_i32 s2, s2, s27
	s_add_u32 s2, s2, s88
	s_lshl_b32 s27, s27, 3
	s_load_dwordx2 s[44:45], s[0:1], 0x0
	s_load_dwordx2 s[48:49], s[0:1], 0x10
	s_load_dwordx2 s[90:91], s[0:1], 0x38
	s_load_dwordx2 s[24:25], s[0:1], 0x40
	s_waitcnt lgkmcnt(0)
	s_add_u32 s54, s40, 0x917c000
	s_addc_u32 s55, s41, 0
	s_add_u32 s56, s40, 0x1a7c000
	s_addc_u32 s57, s41, 0
	s_movk_i32 s8, 0x2000
	s_movk_i32 s59, 0x4000
	s_movk_i32 s73, 0x3000
	s_branch .Lnrm_bodyB_ctx
.Lnrm_sp5b:
	v_mbcnt_lo_u32_b32 v1, -1, 0
	v_mbcnt_hi_u32_b32 v1, -1, v1
	v_readlane_b32 s0, v252, 1
	v_readlane_b32 s1, v252, 2
	v_lshlrev_b32_e32 v0, 4, v1
	v_lshlrev_b32_e32 v1, 3, v1
	v_mov_b32_e32 v2, 0x3a800000
	v_mov_b32_e32 v3, 0x358637bd
	s_load_dwordx2 s[40:41], s[0:1], 0xc8
	s_load_dwordx2 s[42:43], s[0:1], 0xc0
	s_load_dword s27, s[0:1], 0xd8
	v_readlane_b32 s2, v252, 7
	v_readlane_b32 s88, v252, 0
	s_waitcnt lgkmcnt(0)
	s_mul_i32 s2, s2, s27
	s_add_u32 s2, s2, s88
	s_lshl_b32 s27, s27, 3
	s_load_dwordx2 s[90:91], s[0:1], 0x38
	s_load_dwordx2 s[24:25], s[0:1], 0x40
	s_waitcnt lgkmcnt(0)
	s_mov_b64 s[44:45], s[42:43]
	s_add_u32 s90, s90, 0x1000
	s_addc_u32 s91, s91, 0
	s_add_u32 s24, s24, 0x1000
	s_addc_u32 s25, s25, 0
	s_add_u32 s54, s40, 0x917c000
	s_addc_u32 s55, s41, 0
	s_add_u32 s56, s40, 0x1a7c000
	s_addc_u32 s57, s41, 0
	s_mov_b32 s8, 0x20000
	s_mov_b32 s59, 0x22000
	s_mov_b32 s73, 0x21000
	s_branch .Lnrm_bodyB_lat
.Lnrm_sp8a:
	v_mbcnt_lo_u32_b32 v1, -1, 0
	v_mbcnt_hi_u32_b32 v1, -1, v1
	v_readlane_b32 s0, v252, 1
	v_readlane_b32 s1, v252, 2
	v_lshlrev_b32_e32 v0, 4, v1
	v_lshlrev_b32_e32 v1, 3, v1
	v_mov_b32_e32 v2, 0x3a800000
	v_mov_b32_e32 v3, 0x358637bd
	s_load_dwordx2 s[40:41], s[0:1], 0xc8
	s_load_dwordx2 s[42:43], s[0:1], 0xc0
	s_load_dword s27, s[0:1], 0xd8
	v_readlane_b32 s2, v252, 7
	v_readlane_b32 s88, v252, 0
	s_waitcnt lgkmcnt(0)
	s_mul_i32 s2, s2, s27
	s_add_u32 s2, s2, s88
	s_lshl_b32 s27, s27, 3
	s_load_dwordx2 s[90:91], s[0:1], 0x48
	s_load_dwordx2 s[24:25], s[0:1], 0x30
	s_waitcnt lgkmcnt(0)
	s_mov_b64 s[44:45], s[42:43]
	s_add_u32 s48, s40, 0x1200000
	s_addc_u32 s49, s41, 0
	s_add_u32 s24, s24, 0x1000
	s_addc_u32 s25, s25, 0
	s_add_u32 s54, s40, 0xb37c000
	s_addc_u32 s55, s41, 0
	s_add_u32 s56, s40, 0x1a7c000
	s_addc_u32 s57, s41, 0
	s_movk_i32 s8, 0x5000
	s_mov_b32 s59, 0x1f000
	s_mov_b32 s73, 0x1e000
	s_branch .Lnrm_bodyB_ctx
.Lnrm_sp8b:
	v_mbcnt_lo_u32_b32 v1, -1, 0
	v_mbcnt_hi_u32_b32 v1, -1, v1
	v_readlane_b32 s0, v252, 1
	v_readlane_b32 s1, v252, 2
	v_lshlrev_b32_e32 v0, 4, v1
	v_lshlrev_b32_e32 v1, 3, v1
	v_mov_b32_e32 v2, 0x3a800000
	v_mov_b32_e32 v3, 0x358637bd
	s_load_dwordx2 s[40:41], s[0:1], 0xc8
	s_load_dwordx2 s[42:43], s[0:1], 0xc0
	s_load_dword s27, s[0:1], 0xd8
	v_readlane_b32 s2, v252, 7
	v_readlane_b32 s88, v252, 0
	s_waitcnt lgkmcnt(0)
	s_mul_i32 s2, s2, s27
	s_add_u32 s2, s2, s88
	s_lshl_b32 s27, s27, 3
	s_load_dwordx2 s[90:91], s[0:1], 0x48
	s_waitcnt lgkmcnt(0)
	s_mov_b64 s[44:45], s[42:43]
	s_add_u32 s90, s90, 0x1000
	s_addc_u32 s91, s91, 0
	s_add_u32 s54, s40, 0xb37c000
	s_addc_u32 s55, s41, 0
	s_mov_b32 s8, 0x23000
	s_branch .Lnrm_bodyC
.Lnrm_bodyA:
	s_mov_b32 s32, s2
; __device__ __forceinline__ unsigned cvt_pk_bf16(float lo, float hi) { unsigned r; asm volatile("v_cvt_pk_bf16_f32 %0, %1, %2" : "=v"(r) : "v"(lo), "v"(hi)); return r; }
; __device__ __forceinline__ float bflo(unsigned w) { return __uint_as_float(w << 16); }
; __device__ __forceinline__ float bfhi(unsigned w) { return __uint_as_float(w & 0xffff0000u); }
; template <bool BR, bool WH> ...
;     ...
;     for (int row = gw; row < nrows; row += NGW) {
;         const bool hn = row + NGW < nrows;
;         if (hn) NORM_LOAD(row + NGW, xn, bn);
;         const int mrow = row < ML ? (row >> 12) : 4;
;         f32x4 x[4];
; #pragma unroll
;         for (int j = 0; j < 4; ++j) x[j] = xc[j];
;         if (BR) {
;             f32x4 m[4]; float s = 0.f;
; #pragma unroll
;             for (int j = 0; j < 4; ++j) { m[j] = (f32x4){bflo(bc[j].x), bfhi(bc[j].x), bflo(bc[j].y), bfhi(bc[j].y)};
;                 s += (m[j][0] * m[j][0] + m[j][1] * m[j][1]) + (m[j][2] * m[j][2] + m[j][3] * m[j][3]); }
;             const float rs = rsqrtf(wave_sum(s, lane) * (1.f / 1024.f) + EPS);
;             float* xo = row < ML ? xout_lat + (size_t)row * 1024 : xout_ctx + (size_t)(row - ML) * 1024;
; #pragma unroll
;             for (int j = 0; j < 4; ++j) { const f32x4 gp = *(const f32x4*)(g_post + 4 * lane + 256 * j), ga = *(const f32x4*)(mod_g + (size_t)mrow * 6144 + gate_off + 4 * lane + 256 * j);
;                 x[j] = x[j] + ga * ((m[j] * rs) * gp); __builtin_nontemporal_store(x[j], (f32x4*)(xo + 4 * lane + 256 * j)); }
;         }
;         if (WH) {
;             float s = 0.f;
; #pragma unroll
;             for (int j = 0; j < 4; ++j) s += (x[j][0] * x[j][0] + x[j][1] * x[j][1]) + (x[j][2] * x[j][2] + x[j][3] * x[j][3]);
;             const float rs = rsqrtf(wave_sum(s, lane) * (1.f / 1024.f) + EPS);
; #pragma unroll
;             for (int j = 0; j < 4; ++j) { const f32x4 gp = *(const f32x4*)(g_pre + 4 * lane + 256 * j), sc = *(const f32x4*)(mod_h + (size_t)mrow * 6144 + sc_off + 4 * lane + 256 * j),
;                     sh = *(const f32x4*)(mod_h + (size_t)mrow * 6144 + sh_off + 4 * lane + 256 * j);
;                 const f32x4 hv = ((x[j] * rs) * gp) * (sc + 1.0f) + sh;
;                 u32x2 w; w.x = cvt_pk_bf16(hv[0], hv[1]); w.y = cvt_pk_bf16(hv[2], hv[3]);
;                 *(u32x2*)(Hout + (size_t)row * 1024 + 4 * lane + 256 * j) = w; }
;         }
.Lnrm_A_ctx_loop:
	s_cmpk_lt_u32 s32, 0x400
	s_cbranch_scc0 .Lnrm_A_ctx_done
	s_lshl_b32 s97, s32, 12
	s_add_u32 s4, s48, s97
	s_addc_u32 s5, s49, 0
	s_lshl_b32 s97, s32, 11
	s_add_u32 s16, s56, s97
	s_addc_u32 s17, s57, 0
	s_add_u32 s16, s16, 0x2000000
	s_addc_u32 s17, s17, 0
	global_load_dwordx4 v[106:109], v0, s[4:5] offset:0 nt
	global_load_dwordx4 v[110:113], v0, s[4:5] offset:1024 nt
	global_load_dwordx4 v[114:117], v0, s[4:5] offset:2048 nt
	global_load_dwordx4 v[118:121], v0, s[4:5] offset:3072 nt
	s_mov_b32 s88, 0x18000
	global_load_dwordx4 v[192:195], v0, s[24:25] offset:0
	global_load_dwordx4 v[196:199], v0, s[24:25] offset:1024
	global_load_dwordx4 v[200:203], v0, s[24:25] offset:2048
	global_load_dwordx4 v[204:207], v0, s[24:25] offset:3072
	s_add_u32 s100, s88, s59
	s_add_u32 s100, s100, s40
	s_addc_u32 s101, s41, 0
	s_add_u32 s100, s100, 0x1600000
	s_addc_u32 s101, s101, 0
	global_load_dwordx4 v[208:211], v0, s[100:101] offset:0
	global_load_dwordx4 v[212:215], v0, s[100:101] offset:1024
	global_load_dwordx4 v[220:223], v0, s[100:101] offset:2048
	global_load_dwordx4 v[224:227], v0, s[100:101] offset:3072
	s_add_u32 s100, s88, s73
	s_add_u32 s100, s100, s40
	s_addc_u32 s101, s41, 0
	s_add_u32 s100, s100, 0x1600000
	s_addc_u32 s101, s101, 0
	global_load_dwordx4 v[228:231], v0, s[100:101] offset:0
	global_load_dwordx4 v[232:235], v0, s[100:101] offset:1024
	global_load_dwordx4 v[236:239], v0, s[100:101] offset:2048
	global_load_dwordx4 v[26:29], v0, s[100:101] offset:3072
	s_waitcnt vmcnt(0)
	v_pk_add_f32 v[208:209], v[208:209], 1.0 op_sel_hi:[1,0]
	v_pk_add_f32 v[210:211], v[210:211], 1.0 op_sel_hi:[1,0]
	v_pk_add_f32 v[212:213], v[212:213], 1.0 op_sel_hi:[1,0]
	v_pk_add_f32 v[214:215], v[214:215], 1.0 op_sel_hi:[1,0]
	v_pk_add_f32 v[220:221], v[220:221], 1.0 op_sel_hi:[1,0]
	v_pk_add_f32 v[222:223], v[222:223], 1.0 op_sel_hi:[1,0]
	v_pk_add_f32 v[224:225], v[224:225], 1.0 op_sel_hi:[1,0]
	v_pk_add_f32 v[226:227], v[226:227], 1.0 op_sel_hi:[1,0]
	v_mul_f32_e32 v6, v106, v106
	v_mul_f32_e32 v7, v107, v107
	v_fmac_f32_e32 v6, v108, v108
	v_fmac_f32_e32 v7, v109, v109
	v_fmac_f32_e32 v6, v110, v110
	v_fmac_f32_e32 v7, v111, v111
	v_fmac_f32_e32 v6, v112, v112
	v_fmac_f32_e32 v7, v113, v113
	v_fmac_f32_e32 v6, v114, v114
	v_fmac_f32_e32 v7, v115, v115
	v_fmac_f32_e32 v6, v116, v116
	v_fmac_f32_e32 v7, v117, v117
	v_fmac_f32_e32 v6, v118, v118
	v_fmac_f32_e32 v7, v119, v119
	v_fmac_f32_e32 v6, v120, v120
	v_fmac_f32_e32 v7, v121, v121
	v_add_f32_e32 v6, v6, v7
	s_nop 1
	v_add_f32_dpp v8, v6, v6 quad_perm:[1,0,3,2] row_mask:0xf bank_mask:0xf
	s_nop 1
	v_add_f32_dpp v8, v8, v8 quad_perm:[2,3,0,1] row_mask:0xf bank_mask:0xf
	s_nop 1
	v_add_f32_dpp v8, v8, v8 row_half_mirror row_mask:0xf bank_mask:0xf
	s_nop 1
	v_add_f32_dpp v8, v8, v8 row_mirror row_mask:0xf bank_mask:0xf
	s_nop 1
	v_add_f32_dpp v8, v8, v8 row_bcast:15 row_mask:0xa bank_mask:0xf
	s_nop 1
	v_add_f32_dpp v8, v8, v8 row_bcast:31 row_mask:0xc bank_mask:0xf
	s_nop 1
	v_readlane_b32 s84, v8, 63
	s_nop 1
	v_fma_f32 v4, s84, v2, v3
	v_rsq_f32_e32 v4, v4
	s_nop 0
	v_pk_mul_f32 v[34:35], v[106:107], v[4:5] op_sel_hi:[1,0]
	v_pk_mul_f32 v[36:37], v[108:109], v[4:5] op_sel_hi:[1,0]
	v_pk_mul_f32 v[38:39], v[110:111], v[4:5] op_sel_hi:[1,0]
	v_pk_mul_f32 v[40:41], v[112:113], v[4:5] op_sel_hi:[1,0]
	v_pk_mul_f32 v[42:43], v[114:115], v[4:5] op_sel_hi:[1,0]
	v_pk_mul_f32 v[44:45], v[116:117], v[4:5] op_sel_hi:[1,0]
	v_pk_mul_f32 v[46:47], v[118:119], v[4:5] op_sel_hi:[1,0]
	v_pk_mul_f32 v[48:49], v[120:121], v[4:5] op_sel_hi:[1,0]
	v_pk_mul_f32 v[34:35], v[34:35], v[192:193]
	v_pk_mul_f32 v[36:37], v[36:37], v[194:195]
	v_pk_mul_f32 v[38:39], v[38:39], v[196:197]
	v_pk_mul_f32 v[40:41], v[40:41], v[198:199]
	v_pk_mul_f32 v[42:43], v[42:43], v[200:201]
	v_pk_mul_f32 v[44:45], v[44:45], v[202:203]
	v_pk_mul_f32 v[46:47], v[46:47], v[204:205]
	v_pk_mul_f32 v[48:49], v[48:49], v[206:207]
	v_pk_fma_f32 v[34:35], v[34:35], v[208:209], v[228:229]
	v_pk_fma_f32 v[36:37], v[36:37], v[210:211], v[230:231]
	v_pk_fma_f32 v[38:39], v[38:39], v[212:213], v[232:233]
	v_pk_fma_f32 v[40:41], v[40:41], v[214:215], v[234:235]
	v_pk_fma_f32 v[42:43], v[42:43], v[220:221], v[236:237]
	v_pk_fma_f32 v[44:45], v[44:45], v[222:223], v[238:239]
	v_pk_fma_f32 v[46:47], v[46:47], v[224:225], v[26:27]
	v_pk_fma_f32 v[48:49], v[48:49], v[226:227], v[28:29]
	v_cvt_pk_bf16_f32 v50, v34, v35
	v_cvt_pk_bf16_f32 v51, v36, v37
	v_cvt_pk_bf16_f32 v52, v38, v39
	v_cvt_pk_bf16_f32 v53, v40, v41
	v_cvt_pk_bf16_f32 v54, v42, v43
	v_cvt_pk_bf16_f32 v55, v44, v45
	v_cvt_pk_bf16_f32 v56, v46, v47
	v_cvt_pk_bf16_f32 v57, v48, v49
	global_store_dwordx2 v1, v[50:51], s[16:17] offset:0
	global_store_dwordx2 v1, v[52:53], s[16:17] offset:512
	global_store_dwordx2 v1, v[54:55], s[16:17] offset:1024
	global_store_dwordx2 v1, v[56:57], s[16:17] offset:1536
	s_add_u32 s32, s32, s27
	s_branch .Lnrm_A_ctx_loop

; __device__ __forceinline__ unsigned cvt_pk_bf16(float lo, float hi) { unsigned r; asm volatile("v_cvt_pk_bf16_f32 %0, %1, %2" : "=v"(r) : "v"(lo), "v"(hi)); return r; }
; __device__ __forceinline__ float bflo(unsigned w) { return __uint_as_float(w << 16); }
; __device__ __forceinline__ float bfhi(unsigned w) { return __uint_as_float(w & 0xffff0000u); }
; template <bool BR, bool WH> ...
;     ...
;     NORM_LOAD(gw, xc, bc);
;     for (int row = gw; row < nrows; row += NGW) {
;         const bool hn = row + NGW < nrows;
;         if (hn) NORM_LOAD(row + NGW, xn, bn);
;         const int mrow = row < ML ? (row >> 12) : 4;
;         f32x4 x[4];
; #pragma unroll
;         for (int j = 0; j < 4; ++j) x[j] = xc[j];
;         if (BR) {
;             f32x4 m[4]; float s = 0.f;
; #pragma unroll
;             for (int j = 0; j < 4; ++j) { m[j] = (f32x4){bflo(bc[j].x), bfhi(bc[j].x), bflo(bc[j].y), bfhi(bc[j].y)};
;                 s += (m[j][0] * m[j][0] + m[j][1] * m[j][1]) + (m[j][2] * m[j][2] + m[j][3] * m[j][3]); }
;             const float rs = rsqrtf(wave_sum(s, lane) * (1.f / 1024.f) + EPS);
;             float* xo = row < ML ? xout_lat + (size_t)row * 1024 : xout_ctx + (size_t)(row - ML) * 1024;
; #pragma unroll
;             for (int j = 0; j < 4; ++j) { const f32x4 gp = *(const f32x4*)(g_post + 4 * lane + 256 * j), ga = *(const f32x4*)(mod_g + (size_t)mrow * 6144 + gate_off + 4 * lane + 256 * j);
;                 x[j] = x[j] + ga * ((m[j] * rs) * gp); __builtin_nontemporal_store(x[j], (f32x4*)(xo + 4 * lane + 256 * j)); }
;         }
;         if (WH) {
;             float s = 0.f;
; #pragma unroll
;             for (int j = 0; j < 4; ++j) s += (x[j][0] * x[j][0] + x[j][1] * x[j][1]) + (x[j][2] * x[j][2] + x[j][3] * x[j][3]);
;             const float rs = rsqrtf(wave_sum(s, lane) * (1.f / 1024.f) + EPS);
; #pragma unroll
;             for (int j = 0; j < 4; ++j) { const f32x4 gp = *(const f32x4*)(g_pre + 4 * lane + 256 * j), sc = *(const f32x4*)(mod_h + (size_t)mrow * 6144 + sc_off + 4 * lane + 256 * j),
;                     sh = *(const f32x4*)(mod_h + (size_t)mrow * 6144 + sh_off + 4 * lane + 256 * j);
;                 const f32x4 hv = ((x[j] * rs) * gp) * (sc + 1.0f) + sh;
;                 u32x2 w; w.x = cvt_pk_bf16(hv[0], hv[1]); w.y = cvt_pk_bf16(hv[2], hv[3]);
;                 *(u32x2*)(Hout + (size_t)row * 1024 + 4 * lane + 256 * j) = w; }
;         }
.Lnrm_A_lat_loop:
	s_cmpk_lt_u32 s32, 0x800
	s_cbranch_scc0 .LBB0_8
	s_lshl_b32 s97, s32, 15
	s_add_u32 s4, s44, s97
	s_addc_u32 s5, s45, 0
	s_lshl_b32 s97, s32, 14
	s_add_u32 s16, s56, s97
	s_addc_u32 s17, s57, 0
	s_lshr_b32 s88, s32, 9
	s_mul_i32 s88, s88, 0x6000
	global_load_dwordx4 v[58:61], v0, s[4:5] offset:0 nt
	global_load_dwordx4 v[62:65], v0, s[4:5] offset:1024 nt
	global_load_dwordx4 v[66:69], v0, s[4:5] offset:2048 nt
	global_load_dwordx4 v[70:73], v0, s[4:5] offset:3072 nt
	s_add_u32 s4, s4, 0x1000
	s_addc_u32 s5, s5, 0
	global_load_dwordx4 v[192:195], v0, s[24:25] offset:0
	global_load_dwordx4 v[196:199], v0, s[24:25] offset:1024
	global_load_dwordx4 v[200:203], v0, s[24:25] offset:2048
	global_load_dwordx4 v[204:207], v0, s[24:25] offset:3072
	s_add_u32 s100, s88, s59
	s_add_u32 s100, s100, s40
	s_addc_u32 s101, s41, 0
	s_add_u32 s100, s100, 0x1600000
	s_addc_u32 s101, s101, 0
	global_load_dwordx4 v[208:211], v0, s[100:101] offset:0
	global_load_dwordx4 v[212:215], v0, s[100:101] offset:1024
	global_load_dwordx4 v[220:223], v0, s[100:101] offset:2048
	global_load_dwordx4 v[224:227], v0, s[100:101] offset:3072
	s_add_u32 s100, s88, s73
	s_add_u32 s100, s100, s40
	s_addc_u32 s101, s41, 0
	s_add_u32 s100, s100, 0x1600000
	s_addc_u32 s101, s101, 0
	global_load_dwordx4 v[228:231], v0, s[100:101] offset:0
	global_load_dwordx4 v[232:235], v0, s[100:101] offset:1024
	global_load_dwordx4 v[236:239], v0, s[100:101] offset:2048
	global_load_dwordx4 v[26:29], v0, s[100:101] offset:3072
	global_load_dwordx4 v[74:77], v0, s[4:5] offset:0 nt
	global_load_dwordx4 v[78:81], v0, s[4:5] offset:1024 nt
	global_load_dwordx4 v[82:85], v0, s[4:5] offset:2048 nt
	global_load_dwordx4 v[86:89], v0, s[4:5] offset:3072 nt
	s_add_u32 s4, s4, 0x1000
	s_addc_u32 s5, s5, 0
	global_load_dwordx4 v[90:93], v0, s[4:5] offset:0 nt
	global_load_dwordx4 v[94:97], v0, s[4:5] offset:1024 nt
	global_load_dwordx4 v[98:101], v0, s[4:5] offset:2048 nt
	global_load_dwordx4 v[102:105], v0, s[4:5] offset:3072 nt
	s_add_u32 s4, s4, 0x1000
	s_addc_u32 s5, s5, 0
	global_load_dwordx4 v[106:109], v0, s[4:5] offset:0 nt
	global_load_dwordx4 v[110:113], v0, s[4:5] offset:1024 nt
	global_load_dwordx4 v[114:117], v0, s[4:5] offset:2048 nt
	global_load_dwordx4 v[118:121], v0, s[4:5] offset:3072 nt
	s_add_u32 s4, s4, 0x1000
	s_addc_u32 s5, s5, 0
	s_waitcnt vmcnt(12)
	v_pk_add_f32 v[208:209], v[208:209], 1.0 op_sel_hi:[1,0]
	v_pk_add_f32 v[210:211], v[210:211], 1.0 op_sel_hi:[1,0]
	v_pk_add_f32 v[212:213], v[212:213], 1.0 op_sel_hi:[1,0]
	v_pk_add_f32 v[214:215], v[214:215], 1.0 op_sel_hi:[1,0]
	v_pk_add_f32 v[220:221], v[220:221], 1.0 op_sel_hi:[1,0]
	v_pk_add_f32 v[222:223], v[222:223], 1.0 op_sel_hi:[1,0]
	v_pk_add_f32 v[224:225], v[224:225], 1.0 op_sel_hi:[1,0]
	v_pk_add_f32 v[226:227], v[226:227], 1.0 op_sel_hi:[1,0]
	v_mul_f32_e32 v6, v58, v58
	v_mul_f32_e32 v7, v59, v59
	v_fmac_f32_e32 v6, v60, v60
	v_fmac_f32_e32 v7, v61, v61
	v_fmac_f32_e32 v6, v62, v62
	v_fmac_f32_e32 v7, v63, v63
	v_fmac_f32_e32 v6, v64, v64
	v_fmac_f32_e32 v7, v65, v65
	v_fmac_f32_e32 v6, v66, v66
	v_fmac_f32_e32 v7, v67, v67
	v_fmac_f32_e32 v6, v68, v68
	v_fmac_f32_e32 v7, v69, v69
	v_fmac_f32_e32 v6, v70, v70
	v_fmac_f32_e32 v7, v71, v71
	v_fmac_f32_e32 v6, v72, v72
	v_fmac_f32_e32 v7, v73, v73
	v_add_f32_e32 v6, v6, v7
	s_nop 1
	v_add_f32_dpp v8, v6, v6 quad_perm:[1,0,3,2] row_mask:0xf bank_mask:0xf
	s_nop 1
	v_add_f32_dpp v8, v8, v8 quad_perm:[2,3,0,1] row_mask:0xf bank_mask:0xf
	s_nop 1
	v_add_f32_dpp v8, v8, v8 row_half_mirror row_mask:0xf bank_mask:0xf
	s_nop 1
	v_add_f32_dpp v8, v8, v8 row_mirror row_mask:0xf bank_mask:0xf
	s_nop 1
	v_add_f32_dpp v8, v8, v8 row_bcast:15 row_mask:0xa bank_mask:0xf
	s_nop 1
	v_add_f32_dpp v8, v8, v8 row_bcast:31 row_mask:0xc bank_mask:0xf
	s_nop 1
	v_readlane_b32 s84, v8, 63
	s_nop 1
	v_fma_f32 v4, s84, v2, v3
	v_rsq_f32_e32 v4, v4
	s_nop 0
	v_pk_mul_f32 v[34:35], v[58:59], v[4:5] op_sel_hi:[1,0]
	v_pk_mul_f32 v[36:37], v[60:61], v[4:5] op_sel_hi:[1,0]
	v_pk_mul_f32 v[38:39], v[62:63], v[4:5] op_sel_hi:[1,0]
	v_pk_mul_f32 v[40:41], v[64:65], v[4:5] op_sel_hi:[1,0]
	v_pk_mul_f32 v[42:43], v[66:67], v[4:5] op_sel_hi:[1,0]
	v_pk_mul_f32 v[44:45], v[68:69], v[4:5] op_sel_hi:[1,0]
	v_pk_mul_f32 v[46:47], v[70:71], v[4:5] op_sel_hi:[1,0]
	v_pk_mul_f32 v[48:49], v[72:73], v[4:5] op_sel_hi:[1,0]
	v_pk_mul_f32 v[34:35], v[34:35], v[192:193]
	v_pk_mul_f32 v[36:37], v[36:37], v[194:195]
	v_pk_mul_f32 v[38:39], v[38:39], v[196:197]
	v_pk_mul_f32 v[40:41], v[40:41], v[198:199]
	v_pk_mul_f32 v[42:43], v[42:43], v[200:201]
	v_pk_mul_f32 v[44:45], v[44:45], v[202:203]
	v_pk_mul_f32 v[46:47], v[46:47], v[204:205]
	v_pk_mul_f32 v[48:49], v[48:49], v[206:207]
	v_pk_fma_f32 v[34:35], v[34:35], v[208:209], v[228:229]
	v_pk_fma_f32 v[36:37], v[36:37], v[210:211], v[230:231]
	v_pk_fma_f32 v[38:39], v[38:39], v[212:213], v[232:233]
	v_pk_fma_f32 v[40:41], v[40:41], v[214:215], v[234:235]
	v_pk_fma_f32 v[42:43], v[42:43], v[220:221], v[236:237]
	v_pk_fma_f32 v[44:45], v[44:45], v[222:223], v[238:239]
	v_pk_fma_f32 v[46:47], v[46:47], v[224:225], v[26:27]
	v_pk_fma_f32 v[48:49], v[48:49], v[226:227], v[28:29]
	v_cvt_pk_bf16_f32 v50, v34, v35
	v_cvt_pk_bf16_f32 v51, v36, v37
	v_cvt_pk_bf16_f32 v52, v38, v39
	v_cvt_pk_bf16_f32 v53, v40, v41
	v_cvt_pk_bf16_f32 v54, v42, v43
	v_cvt_pk_bf16_f32 v55, v44, v45
	v_cvt_pk_bf16_f32 v56, v46, v47
	v_cvt_pk_bf16_f32 v57, v48, v49
	global_store_dwordx2 v1, v[50:51], s[16:17] offset:0
	global_store_dwordx2 v1, v[52:53], s[16:17] offset:512
	global_store_dwordx2 v1, v[54:55], s[16:17] offset:1024
	global_store_dwordx2 v1, v[56:57], s[16:17] offset:1536
	s_add_u32 s16, s16, 0x800
	s_addc_u32 s17, s17, 0
	global_load_dwordx4 v[58:61], v0, s[4:5] offset:0 nt
	global_load_dwordx4 v[62:65], v0, s[4:5] offset:1024 nt
	global_load_dwordx4 v[66:69], v0, s[4:5] offset:2048 nt
	global_load_dwordx4 v[70:73], v0, s[4:5] offset:3072 nt
	s_add_u32 s4, s4, 0x1000
	s_addc_u32 s5, s5, 0
	s_waitcnt vmcnt(16)
; __device__ __forceinline__ unsigned cvt_pk_bf16(float lo, float hi) { unsigned r; asm volatile("v_cvt_pk_bf16_f32 %0, %1, %2" : "=v"(r) : "v"(lo), "v"(hi)); return r; }
; template <bool BR, bool WH> ...
;     ...
;         if (WH) {
;             float s = 0.f;
; #pragma unroll
;             for (int j = 0; j < 4; ++j) s += (x[j][0] * x[j][0] + x[j][1] * x[j][1]) + (x[j][2] * x[j][2] + x[j][3] * x[j][3]);
;             const float rs = rsqrtf(wave_sum(s, lane) * (1.f / 1024.f) + EPS);
; #pragma unroll
;             for (int j = 0; j < 4; ++j) { const f32x4 gp = *(const f32x4*)(g_pre + 4 * lane + 256 * j), sc = *(const f32x4*)(mod_h + (size_t)mrow * 6144 + sc_off + 4 * lane + 256 * j),
;                     sh = *(const f32x4*)(mod_h + (size_t)mrow * 6144 + sh_off + 4 * lane + 256 * j);
;                 const f32x4 hv = ((x[j] * rs) * gp) * (sc + 1.0f) + sh;
;                 u32x2 w; w.x = cvt_pk_bf16(hv[0], hv[1]); w.y = cvt_pk_bf16(hv[2], hv[3]);
;                 *(u32x2*)(Hout + (size_t)row * 1024 + 4 * lane + 256 * j) = w; }
;         }
	v_mul_f32_e32 v6, v74, v74
	v_mul_f32_e32 v7, v75, v75
	v_fmac_f32_e32 v6, v76, v76
	v_fmac_f32_e32 v7, v77, v77
	v_fmac_f32_e32 v6, v78, v78
	v_fmac_f32_e32 v7, v79, v79
	v_fmac_f32_e32 v6, v80, v80
	v_fmac_f32_e32 v7, v81, v81
	v_fmac_f32_e32 v6, v82, v82
	v_fmac_f32_e32 v7, v83, v83
	v_fmac_f32_e32 v6, v84, v84
	v_fmac_f32_e32 v7, v85, v85
	v_fmac_f32_e32 v6, v86, v86
	v_fmac_f32_e32 v7, v87, v87
	v_fmac_f32_e32 v6, v88, v88
	v_fmac_f32_e32 v7, v89, v89
	v_add_f32_e32 v6, v6, v7
	s_nop 1
	v_add_f32_dpp v8, v6, v6 quad_perm:[1,0,3,2] row_mask:0xf bank_mask:0xf
	s_nop 1
	v_add_f32_dpp v8, v8, v8 quad_perm:[2,3,0,1] row_mask:0xf bank_mask:0xf
	s_nop 1
	v_add_f32_dpp v8, v8, v8 row_half_mirror row_mask:0xf bank_mask:0xf
	s_nop 1
	v_add_f32_dpp v8, v8, v8 row_mirror row_mask:0xf bank_mask:0xf
	s_nop 1
	v_add_f32_dpp v8, v8, v8 row_bcast:15 row_mask:0xa bank_mask:0xf
	s_nop 1
	v_add_f32_dpp v8, v8, v8 row_bcast:31 row_mask:0xc bank_mask:0xf
	s_nop 1
	v_readlane_b32 s84, v8, 63
	s_nop 1
	v_fma_f32 v4, s84, v2, v3
	v_rsq_f32_e32 v4, v4
	s_nop 0
	v_pk_mul_f32 v[34:35], v[74:75], v[4:5] op_sel_hi:[1,0]
	v_pk_mul_f32 v[36:37], v[76:77], v[4:5] op_sel_hi:[1,0]
	v_pk_mul_f32 v[38:39], v[78:79], v[4:5] op_sel_hi:[1,0]
	v_pk_mul_f32 v[40:41], v[80:81], v[4:5] op_sel_hi:[1,0]
	v_pk_mul_f32 v[42:43], v[82:83], v[4:5] op_sel_hi:[1,0]
	v_pk_mul_f32 v[44:45], v[84:85], v[4:5] op_sel_hi:[1,0]
	v_pk_mul_f32 v[46:47], v[86:87], v[4:5] op_sel_hi:[1,0]
	v_pk_mul_f32 v[48:49], v[88:89], v[4:5] op_sel_hi:[1,0]
	v_pk_mul_f32 v[34:35], v[34:35], v[192:193]
	v_pk_mul_f32 v[36:37], v[36:37], v[194:195]
	v_pk_mul_f32 v[38:39], v[38:39], v[196:197]
	v_pk_mul_f32 v[40:41], v[40:41], v[198:199]
	v_pk_mul_f32 v[42:43], v[42:43], v[200:201]
	v_pk_mul_f32 v[44:45], v[44:45], v[202:203]
	v_pk_mul_f32 v[46:47], v[46:47], v[204:205]
	v_pk_mul_f32 v[48:49], v[48:49], v[206:207]
	v_pk_fma_f32 v[34:35], v[34:35], v[208:209], v[228:229]
	v_pk_fma_f32 v[36:37], v[36:37], v[210:211], v[230:231]
	v_pk_fma_f32 v[38:39], v[38:39], v[212:213], v[232:233]
	v_pk_fma_f32 v[40:41], v[40:41], v[214:215], v[234:235]
	v_pk_fma_f32 v[42:43], v[42:43], v[220:221], v[236:237]
	v_pk_fma_f32 v[44:45], v[44:45], v[222:223], v[238:239]
	v_pk_fma_f32 v[46:47], v[46:47], v[224:225], v[26:27]
	v_pk_fma_f32 v[48:49], v[48:49], v[226:227], v[28:29]
	v_cvt_pk_bf16_f32 v50, v34, v35
	v_cvt_pk_bf16_f32 v51, v36, v37
	v_cvt_pk_bf16_f32 v52, v38, v39
	v_cvt_pk_bf16_f32 v53, v40, v41
	v_cvt_pk_bf16_f32 v54, v42, v43
	v_cvt_pk_bf16_f32 v55, v44, v45
	v_cvt_pk_bf16_f32 v56, v46, v47
	v_cvt_pk_bf16_f32 v57, v48, v49
	global_store_dwordx2 v1, v[50:51], s[16:17] offset:0
	global_store_dwordx2 v1, v[52:53], s[16:17] offset:512
	global_store_dwordx2 v1, v[54:55], s[16:17] offset:1024
	global_store_dwordx2 v1, v[56:57], s[16:17] offset:1536
	s_add_u32 s16, s16, 0x800
	s_addc_u32 s17, s17, 0
	global_load_dwordx4 v[74:77], v0, s[4:5] offset:0 nt
	global_load_dwordx4 v[78:81], v0, s[4:5] offset:1024 nt
	global_load_dwordx4 v[82:85], v0, s[4:5] offset:2048 nt
	global_load_dwordx4 v[86:89], v0, s[4:5] offset:3072 nt
	s_add_u32 s4, s4, 0x1000
	s_addc_u32 s5, s5, 0
	s_waitcnt vmcnt(20)
	v_mul_f32_e32 v6, v90, v90
	v_mul_f32_e32 v7, v91, v91
	v_fmac_f32_e32 v6, v92, v92
	v_fmac_f32_e32 v7, v93, v93
	v_fmac_f32_e32 v6, v94, v94
	v_fmac_f32_e32 v7, v95, v95
	v_fmac_f32_e32 v6, v96, v96
	v_fmac_f32_e32 v7, v97, v97
	v_fmac_f32_e32 v6, v98, v98
	v_fmac_f32_e32 v7, v99, v99
	v_fmac_f32_e32 v6, v100, v100
	v_fmac_f32_e32 v7, v101, v101
	v_fmac_f32_e32 v6, v102, v102
	v_fmac_f32_e32 v7, v103, v103
	v_fmac_f32_e32 v6, v104, v104
	v_fmac_f32_e32 v7, v105, v105
	v_add_f32_e32 v6, v6, v7
	s_nop 1
	v_add_f32_dpp v8, v6, v6 quad_perm:[1,0,3,2] row_mask:0xf bank_mask:0xf
	s_nop 1
	v_add_f32_dpp v8, v8, v8 quad_perm:[2,3,0,1] row_mask:0xf bank_mask:0xf
	s_nop 1
	v_add_f32_dpp v8, v8, v8 row_half_mirror row_mask:0xf bank_mask:0xf
	s_nop 1
	v_add_f32_dpp v8, v8, v8 row_mirror row_mask:0xf bank_mask:0xf
	s_nop 1
	v_add_f32_dpp v8, v8, v8 row_bcast:15 row_mask:0xa bank_mask:0xf
	s_nop 1
	v_add_f32_dpp v8, v8, v8 row_bcast:31 row_mask:0xc bank_mask:0xf
	s_nop 1
	v_readlane_b32 s84, v8, 63
	s_nop 1
	v_fma_f32 v4, s84, v2, v3
	v_rsq_f32_e32 v4, v4
	s_nop 0
	v_pk_mul_f32 v[34:35], v[90:91], v[4:5] op_sel_hi:[1,0]
	v_pk_mul_f32 v[36:37], v[92:93], v[4:5] op_sel_hi:[1,0]
	v_pk_mul_f32 v[38:39], v[94:95], v[4:5] op_sel_hi:[1,0]
	v_pk_mul_f32 v[40:41], v[96:97], v[4:5] op_sel_hi:[1,0]
	v_pk_mul_f32 v[42:43], v[98:99], v[4:5] op_sel_hi:[1,0]
	v_pk_mul_f32 v[44:45], v[100:101], v[4:5] op_sel_hi:[1,0]
	v_pk_mul_f32 v[46:47], v[102:103], v[4:5] op_sel_hi:[1,0]
	v_pk_mul_f32 v[48:49], v[104:105], v[4:5] op_sel_hi:[1,0]
	v_pk_mul_f32 v[34:35], v[34:35], v[192:193]
	v_pk_mul_f32 v[36:37], v[36:37], v[194:195]
	v_pk_mul_f32 v[38:39], v[38:39], v[196:197]
	v_pk_mul_f32 v[40:41], v[40:41], v[198:199]
	v_pk_mul_f32 v[42:43], v[42:43], v[200:201]
	v_pk_mul_f32 v[44:45], v[44:45], v[202:203]
	v_pk_mul_f32 v[46:47], v[46:47], v[204:205]
	v_pk_mul_f32 v[48:49], v[48:49], v[206:207]
	v_pk_fma_f32 v[34:35], v[34:35], v[208:209], v[228:229]
	v_pk_fma_f32 v[36:37], v[36:37], v[210:211], v[230:231]
	v_pk_fma_f32 v[38:39], v[38:39], v[212:213], v[232:233]
	v_pk_fma_f32 v[40:41], v[40:41], v[214:215], v[234:235]
	v_pk_fma_f32 v[42:43], v[42:43], v[220:221], v[236:237]
	v_pk_fma_f32 v[44:45], v[44:45], v[222:223], v[238:239]
	v_pk_fma_f32 v[46:47], v[46:47], v[224:225], v[26:27]
	v_pk_fma_f32 v[48:49], v[48:49], v[226:227], v[28:29]
	v_cvt_pk_bf16_f32 v50, v34, v35
	v_cvt_pk_bf16_f32 v51, v36, v37
	v_cvt_pk_bf16_f32 v52, v38, v39
	v_cvt_pk_bf16_f32 v53, v40, v41
	v_cvt_pk_bf16_f32 v54, v42, v43
	v_cvt_pk_bf16_f32 v55, v44, v45
	v_cvt_pk_bf16_f32 v56, v46, v47
	v_cvt_pk_bf16_f32 v57, v48, v49
	global_store_dwordx2 v1, v[50:51], s[16:17] offset:0
	global_store_dwordx2 v1, v[52:53], s[16:17] offset:512
	global_store_dwordx2 v1, v[54:55], s[16:17] offset:1024
	global_store_dwordx2 v1, v[56:57], s[16:17] offset:1536
	s_add_u32 s16, s16, 0x800
	s_addc_u32 s17, s17, 0
	global_load_dwordx4 v[90:93], v0, s[4:5] offset:0 nt
	global_load_dwordx4 v[94:97], v0, s[4:5] offset:1024 nt
	global_load_dwordx4 v[98:101], v0, s[4:5] offset:2048 nt
	global_load_dwordx4 v[102:105], v0, s[4:5] offset:3072 nt
	s_add_u32 s4, s4, 0x1000
	s_addc_u32 s5, s5, 0
	s_waitcnt vmcnt(24)
; __device__ __forceinline__ unsigned cvt_pk_bf16(float lo, float hi) { unsigned r; asm volatile("v_cvt_pk_bf16_f32 %0, %1, %2" : "=v"(r) : "v"(lo), "v"(hi)); return r; }
; template <bool BR, bool WH> ...
;     ...
;         if (WH) {
;             float s = 0.f;
; #pragma unroll
;             for (int j = 0; j < 4; ++j) s += (x[j][0] * x[j][0] + x[j][1] * x[j][1]) + (x[j][2] * x[j][2] + x[j][3] * x[j][3]);
;             const float rs = rsqrtf(wave_sum(s, lane) * (1.f / 1024.f) + EPS);
; #pragma unroll
;             for (int j = 0; j < 4; ++j) { const f32x4 gp = *(const f32x4*)(g_pre + 4 * lane + 256 * j), sc = *(const f32x4*)(mod_h + (size_t)mrow * 6144 + sc_off + 4 * lane + 256 * j),
;                     sh = *(const f32x4*)(mod_h + (size_t)mrow * 6144 + sh_off + 4 * lane + 256 * j);
;                 const f32x4 hv = ((x[j] * rs) * gp) * (sc + 1.0f) + sh;
;                 u32x2 w; w.x = cvt_pk_bf16(hv[0], hv[1]); w.y = cvt_pk_bf16(hv[2], hv[3]);
;                 *(u32x2*)(Hout + (size_t)row * 1024 + 4 * lane + 256 * j) = w; }
;         }
	v_mul_f32_e32 v6, v106, v106
	v_mul_f32_e32 v7, v107, v107
	v_fmac_f32_e32 v6, v108, v108
	v_fmac_f32_e32 v7, v109, v109
	v_fmac_f32_e32 v6, v110, v110
	v_fmac_f32_e32 v7, v111, v111
	v_fmac_f32_e32 v6, v112, v112
	v_fmac_f32_e32 v7, v113, v113
	v_fmac_f32_e32 v6, v114, v114
	v_fmac_f32_e32 v7, v115, v115
	v_fmac_f32_e32 v6, v116, v116
	v_fmac_f32_e32 v7, v117, v117
	v_fmac_f32_e32 v6, v118, v118
	v_fmac_f32_e32 v7, v119, v119
	v_fmac_f32_e32 v6, v120, v120
	v_fmac_f32_e32 v7, v121, v121
	v_add_f32_e32 v6, v6, v7
	s_nop 1
	v_add_f32_dpp v8, v6, v6 quad_perm:[1,0,3,2] row_mask:0xf bank_mask:0xf
	s_nop 1
	v_add_f32_dpp v8, v8, v8 quad_perm:[2,3,0,1] row_mask:0xf bank_mask:0xf
	s_nop 1
	v_add_f32_dpp v8, v8, v8 row_half_mirror row_mask:0xf bank_mask:0xf
	s_nop 1
	v_add_f32_dpp v8, v8, v8 row_mirror row_mask:0xf bank_mask:0xf
	s_nop 1
	v_add_f32_dpp v8, v8, v8 row_bcast:15 row_mask:0xa bank_mask:0xf
	s_nop 1
	v_add_f32_dpp v8, v8, v8 row_bcast:31 row_mask:0xc bank_mask:0xf
	s_nop 1
	v_readlane_b32 s84, v8, 63
	s_nop 1
	v_fma_f32 v4, s84, v2, v3
	v_rsq_f32_e32 v4, v4
	s_nop 0
	v_pk_mul_f32 v[34:35], v[106:107], v[4:5] op_sel_hi:[1,0]
	v_pk_mul_f32 v[36:37], v[108:109], v[4:5] op_sel_hi:[1,0]
	v_pk_mul_f32 v[38:39], v[110:111], v[4:5] op_sel_hi:[1,0]
	v_pk_mul_f32 v[40:41], v[112:113], v[4:5] op_sel_hi:[1,0]
	v_pk_mul_f32 v[42:43], v[114:115], v[4:5] op_sel_hi:[1,0]
	v_pk_mul_f32 v[44:45], v[116:117], v[4:5] op_sel_hi:[1,0]
	v_pk_mul_f32 v[46:47], v[118:119], v[4:5] op_sel_hi:[1,0]
	v_pk_mul_f32 v[48:49], v[120:121], v[4:5] op_sel_hi:[1,0]
	v_pk_mul_f32 v[34:35], v[34:35], v[192:193]
	v_pk_mul_f32 v[36:37], v[36:37], v[194:195]
	v_pk_mul_f32 v[38:39], v[38:39], v[196:197]
	v_pk_mul_f32 v[40:41], v[40:41], v[198:199]
	v_pk_mul_f32 v[42:43], v[42:43], v[200:201]
	v_pk_mul_f32 v[44:45], v[44:45], v[202:203]
	v_pk_mul_f32 v[46:47], v[46:47], v[204:205]
	v_pk_mul_f32 v[48:49], v[48:49], v[206:207]
	v_pk_fma_f32 v[34:35], v[34:35], v[208:209], v[228:229]
	v_pk_fma_f32 v[36:37], v[36:37], v[210:211], v[230:231]
	v_pk_fma_f32 v[38:39], v[38:39], v[212:213], v[232:233]
	v_pk_fma_f32 v[40:41], v[40:41], v[214:215], v[234:235]
	v_pk_fma_f32 v[42:43], v[42:43], v[220:221], v[236:237]
	v_pk_fma_f32 v[44:45], v[44:45], v[222:223], v[238:239]
	v_pk_fma_f32 v[46:47], v[46:47], v[224:225], v[26:27]
	v_pk_fma_f32 v[48:49], v[48:49], v[226:227], v[28:29]
	v_cvt_pk_bf16_f32 v50, v34, v35
	v_cvt_pk_bf16_f32 v51, v36, v37
	v_cvt_pk_bf16_f32 v52, v38, v39
	v_cvt_pk_bf16_f32 v53, v40, v41
	v_cvt_pk_bf16_f32 v54, v42, v43
	v_cvt_pk_bf16_f32 v55, v44, v45
	v_cvt_pk_bf16_f32 v56, v46, v47
	v_cvt_pk_bf16_f32 v57, v48, v49
	global_store_dwordx2 v1, v[50:51], s[16:17] offset:0
	global_store_dwordx2 v1, v[52:53], s[16:17] offset:512
	global_store_dwordx2 v1, v[54:55], s[16:17] offset:1024
	global_store_dwordx2 v1, v[56:57], s[16:17] offset:1536
	s_add_u32 s16, s16, 0x800
	s_addc_u32 s17, s17, 0
	global_load_dwordx4 v[106:109], v0, s[4:5] offset:0 nt
	global_load_dwordx4 v[110:113], v0, s[4:5] offset:1024 nt
	global_load_dwordx4 v[114:117], v0, s[4:5] offset:2048 nt
	global_load_dwordx4 v[118:121], v0, s[4:5] offset:3072 nt
	s_add_u32 s4, s4, 0x1000
	s_addc_u32 s5, s5, 0
	s_waitcnt vmcnt(24)
	v_mul_f32_e32 v6, v58, v58
	v_mul_f32_e32 v7, v59, v59
	v_fmac_f32_e32 v6, v60, v60
	v_fmac_f32_e32 v7, v61, v61
	v_fmac_f32_e32 v6, v62, v62
	v_fmac_f32_e32 v7, v63, v63
	v_fmac_f32_e32 v6, v64, v64
	v_fmac_f32_e32 v7, v65, v65
	v_fmac_f32_e32 v6, v66, v66
	v_fmac_f32_e32 v7, v67, v67
	v_fmac_f32_e32 v6, v68, v68
	v_fmac_f32_e32 v7, v69, v69
	v_fmac_f32_e32 v6, v70, v70
	v_fmac_f32_e32 v7, v71, v71
	v_fmac_f32_e32 v6, v72, v72
	v_fmac_f32_e32 v7, v73, v73
	v_add_f32_e32 v6, v6, v7
	s_nop 1
	v_add_f32_dpp v8, v6, v6 quad_perm:[1,0,3,2] row_mask:0xf bank_mask:0xf
	s_nop 1
	v_add_f32_dpp v8, v8, v8 quad_perm:[2,3,0,1] row_mask:0xf bank_mask:0xf
	s_nop 1
	v_add_f32_dpp v8, v8, v8 row_half_mirror row_mask:0xf bank_mask:0xf
	s_nop 1
	v_add_f32_dpp v8, v8, v8 row_mirror row_mask:0xf bank_mask:0xf
	s_nop 1
	v_add_f32_dpp v8, v8, v8 row_bcast:15 row_mask:0xa bank_mask:0xf
	s_nop 1
	v_add_f32_dpp v8, v8, v8 row_bcast:31 row_mask:0xc bank_mask:0xf
	s_nop 1
	v_readlane_b32 s84, v8, 63
	s_nop 1
	v_fma_f32 v4, s84, v2, v3
	v_rsq_f32_e32 v4, v4
	s_nop 0
	v_pk_mul_f32 v[34:35], v[58:59], v[4:5] op_sel_hi:[1,0]
	v_pk_mul_f32 v[36:37], v[60:61], v[4:5] op_sel_hi:[1,0]
	v_pk_mul_f32 v[38:39], v[62:63], v[4:5] op_sel_hi:[1,0]
	v_pk_mul_f32 v[40:41], v[64:65], v[4:5] op_sel_hi:[1,0]
	v_pk_mul_f32 v[42:43], v[66:67], v[4:5] op_sel_hi:[1,0]
	v_pk_mul_f32 v[44:45], v[68:69], v[4:5] op_sel_hi:[1,0]
	v_pk_mul_f32 v[46:47], v[70:71], v[4:5] op_sel_hi:[1,0]
	v_pk_mul_f32 v[48:49], v[72:73], v[4:5] op_sel_hi:[1,0]
	v_pk_mul_f32 v[34:35], v[34:35], v[192:193]
	v_pk_mul_f32 v[36:37], v[36:37], v[194:195]
	v_pk_mul_f32 v[38:39], v[38:39], v[196:197]
	v_pk_mul_f32 v[40:41], v[40:41], v[198:199]
	v_pk_mul_f32 v[42:43], v[42:43], v[200:201]
	v_pk_mul_f32 v[44:45], v[44:45], v[202:203]
	v_pk_mul_f32 v[46:47], v[46:47], v[204:205]
	v_pk_mul_f32 v[48:49], v[48:49], v[206:207]
	v_pk_fma_f32 v[34:35], v[34:35], v[208:209], v[228:229]
	v_pk_fma_f32 v[36:37], v[36:37], v[210:211], v[230:231]
	v_pk_fma_f32 v[38:39], v[38:39], v[212:213], v[232:233]
	v_pk_fma_f32 v[40:41], v[40:41], v[214:215], v[234:235]
	v_pk_fma_f32 v[42:43], v[42:43], v[220:221], v[236:237]
	v_pk_fma_f32 v[44:45], v[44:45], v[222:223], v[238:239]
	v_pk_fma_f32 v[46:47], v[46:47], v[224:225], v[26:27]
	v_pk_fma_f32 v[48:49], v[48:49], v[226:227], v[28:29]
	v_cvt_pk_bf16_f32 v50, v34, v35
	v_cvt_pk_bf16_f32 v51, v36, v37
	v_cvt_pk_bf16_f32 v52, v38, v39
	v_cvt_pk_bf16_f32 v53, v40, v41
	v_cvt_pk_bf16_f32 v54, v42, v43
	v_cvt_pk_bf16_f32 v55, v44, v45
	v_cvt_pk_bf16_f32 v56, v46, v47
	v_cvt_pk_bf16_f32 v57, v48, v49
	global_store_dwordx2 v1, v[50:51], s[16:17] offset:0
	global_store_dwordx2 v1, v[52:53], s[16:17] offset:512
	global_store_dwordx2 v1, v[54:55], s[16:17] offset:1024
	global_store_dwordx2 v1, v[56:57], s[16:17] offset:1536
	s_add_u32 s16, s16, 0x800
	s_addc_u32 s17, s17, 0
	s_waitcnt vmcnt(20)
; __device__ __forceinline__ unsigned cvt_pk_bf16(float lo, float hi) { unsigned r; asm volatile("v_cvt_pk_bf16_f32 %0, %1, %2" : "=v"(r) : "v"(lo), "v"(hi)); return r; }
; template <bool BR, bool WH> ...
;     ...
;         if (WH) {
;             float s = 0.f;
; #pragma unroll
;             for (int j = 0; j < 4; ++j) s += (x[j][0] * x[j][0] + x[j][1] * x[j][1]) + (x[j][2] * x[j][2] + x[j][3] * x[j][3]);
;             const float rs = rsqrtf(wave_sum(s, lane) * (1.f / 1024.f) + EPS);
; #pragma unroll
;             for (int j = 0; j < 4; ++j) { const f32x4 gp = *(const f32x4*)(g_pre + 4 * lane + 256 * j), sc = *(const f32x4*)(mod_h + (size_t)mrow * 6144 + sc_off + 4 * lane + 256 * j),
;                     sh = *(const f32x4*)(mod_h + (size_t)mrow * 6144 + sh_off + 4 * lane + 256 * j);
;                 const f32x4 hv = ((x[j] * rs) * gp) * (sc + 1.0f) + sh;
;                 u32x2 w; w.x = cvt_pk_bf16(hv[0], hv[1]); w.y = cvt_pk_bf16(hv[2], hv[3]);
;                 *(u32x2*)(Hout + (size_t)row * 1024 + 4 * lane + 256 * j) = w; }
;         }
	v_mul_f32_e32 v6, v74, v74
	v_mul_f32_e32 v7, v75, v75
	v_fmac_f32_e32 v6, v76, v76
	v_fmac_f32_e32 v7, v77, v77
	v_fmac_f32_e32 v6, v78, v78
	v_fmac_f32_e32 v7, v79, v79
	v_fmac_f32_e32 v6, v80, v80
	v_fmac_f32_e32 v7, v81, v81
	v_fmac_f32_e32 v6, v82, v82
	v_fmac_f32_e32 v7, v83, v83
	v_fmac_f32_e32 v6, v84, v84
	v_fmac_f32_e32 v7, v85, v85
	v_fmac_f32_e32 v6, v86, v86
	v_fmac_f32_e32 v7, v87, v87
	v_fmac_f32_e32 v6, v88, v88
	v_fmac_f32_e32 v7, v89, v89
	v_add_f32_e32 v6, v6, v7
	s_nop 1
	v_add_f32_dpp v8, v6, v6 quad_perm:[1,0,3,2] row_mask:0xf bank_mask:0xf
	s_nop 1
	v_add_f32_dpp v8, v8, v8 quad_perm:[2,3,0,1] row_mask:0xf bank_mask:0xf
	s_nop 1
	v_add_f32_dpp v8, v8, v8 row_half_mirror row_mask:0xf bank_mask:0xf
	s_nop 1
	v_add_f32_dpp v8, v8, v8 row_mirror row_mask:0xf bank_mask:0xf
	s_nop 1
	v_add_f32_dpp v8, v8, v8 row_bcast:15 row_mask:0xa bank_mask:0xf
	s_nop 1
	v_add_f32_dpp v8, v8, v8 row_bcast:31 row_mask:0xc bank_mask:0xf
	s_nop 1
	v_readlane_b32 s84, v8, 63
	s_nop 1
	v_fma_f32 v4, s84, v2, v3
	v_rsq_f32_e32 v4, v4
	s_nop 0
	v_pk_mul_f32 v[34:35], v[74:75], v[4:5] op_sel_hi:[1,0]
	v_pk_mul_f32 v[36:37], v[76:77], v[4:5] op_sel_hi:[1,0]
	v_pk_mul_f32 v[38:39], v[78:79], v[4:5] op_sel_hi:[1,0]
	v_pk_mul_f32 v[40:41], v[80:81], v[4:5] op_sel_hi:[1,0]
	v_pk_mul_f32 v[42:43], v[82:83], v[4:5] op_sel_hi:[1,0]
	v_pk_mul_f32 v[44:45], v[84:85], v[4:5] op_sel_hi:[1,0]
	v_pk_mul_f32 v[46:47], v[86:87], v[4:5] op_sel_hi:[1,0]
	v_pk_mul_f32 v[48:49], v[88:89], v[4:5] op_sel_hi:[1,0]
	v_pk_mul_f32 v[34:35], v[34:35], v[192:193]
	v_pk_mul_f32 v[36:37], v[36:37], v[194:195]
	v_pk_mul_f32 v[38:39], v[38:39], v[196:197]
	v_pk_mul_f32 v[40:41], v[40:41], v[198:199]
	v_pk_mul_f32 v[42:43], v[42:43], v[200:201]
	v_pk_mul_f32 v[44:45], v[44:45], v[202:203]
	v_pk_mul_f32 v[46:47], v[46:47], v[204:205]
	v_pk_mul_f32 v[48:49], v[48:49], v[206:207]
	v_pk_fma_f32 v[34:35], v[34:35], v[208:209], v[228:229]
	v_pk_fma_f32 v[36:37], v[36:37], v[210:211], v[230:231]
	v_pk_fma_f32 v[38:39], v[38:39], v[212:213], v[232:233]
	v_pk_fma_f32 v[40:41], v[40:41], v[214:215], v[234:235]
	v_pk_fma_f32 v[42:43], v[42:43], v[220:221], v[236:237]
	v_pk_fma_f32 v[44:45], v[44:45], v[222:223], v[238:239]
	v_pk_fma_f32 v[46:47], v[46:47], v[224:225], v[26:27]
	v_pk_fma_f32 v[48:49], v[48:49], v[226:227], v[28:29]
	v_cvt_pk_bf16_f32 v50, v34, v35
	v_cvt_pk_bf16_f32 v51, v36, v37
	v_cvt_pk_bf16_f32 v52, v38, v39
	v_cvt_pk_bf16_f32 v53, v40, v41
	v_cvt_pk_bf16_f32 v54, v42, v43
	v_cvt_pk_bf16_f32 v55, v44, v45
	v_cvt_pk_bf16_f32 v56, v46, v47
	v_cvt_pk_bf16_f32 v57, v48, v49
	global_store_dwordx2 v1, v[50:51], s[16:17] offset:0
	global_store_dwordx2 v1, v[52:53], s[16:17] offset:512
	global_store_dwordx2 v1, v[54:55], s[16:17] offset:1024
	global_store_dwordx2 v1, v[56:57], s[16:17] offset:1536
	s_add_u32 s16, s16, 0x800
	s_addc_u32 s17, s17, 0
	s_waitcnt vmcnt(16)
	v_mul_f32_e32 v6, v90, v90
	v_mul_f32_e32 v7, v91, v91
	v_fmac_f32_e32 v6, v92, v92
	v_fmac_f32_e32 v7, v93, v93
	v_fmac_f32_e32 v6, v94, v94
	v_fmac_f32_e32 v7, v95, v95
	v_fmac_f32_e32 v6, v96, v96
	v_fmac_f32_e32 v7, v97, v97
	v_fmac_f32_e32 v6, v98, v98
	v_fmac_f32_e32 v7, v99, v99
	v_fmac_f32_e32 v6, v100, v100
	v_fmac_f32_e32 v7, v101, v101
	v_fmac_f32_e32 v6, v102, v102
	v_fmac_f32_e32 v7, v103, v103
	v_fmac_f32_e32 v6, v104, v104
	v_fmac_f32_e32 v7, v105, v105
	v_add_f32_e32 v6, v6, v7
	s_nop 1
	v_add_f32_dpp v8, v6, v6 quad_perm:[1,0,3,2] row_mask:0xf bank_mask:0xf
	s_nop 1
	v_add_f32_dpp v8, v8, v8 quad_perm:[2,3,0,1] row_mask:0xf bank_mask:0xf
	s_nop 1
	v_add_f32_dpp v8, v8, v8 row_half_mirror row_mask:0xf bank_mask:0xf
	s_nop 1
	v_add_f32_dpp v8, v8, v8 row_mirror row_mask:0xf bank_mask:0xf
	s_nop 1
	v_add_f32_dpp v8, v8, v8 row_bcast:15 row_mask:0xa bank_mask:0xf
	s_nop 1
	v_add_f32_dpp v8, v8, v8 row_bcast:31 row_mask:0xc bank_mask:0xf
	s_nop 1
	v_readlane_b32 s84, v8, 63
	s_nop 1
	v_fma_f32 v4, s84, v2, v3
	v_rsq_f32_e32 v4, v4
	s_nop 0
	v_pk_mul_f32 v[34:35], v[90:91], v[4:5] op_sel_hi:[1,0]
	v_pk_mul_f32 v[36:37], v[92:93], v[4:5] op_sel_hi:[1,0]
	v_pk_mul_f32 v[38:39], v[94:95], v[4:5] op_sel_hi:[1,0]
	v_pk_mul_f32 v[40:41], v[96:97], v[4:5] op_sel_hi:[1,0]
	v_pk_mul_f32 v[42:43], v[98:99], v[4:5] op_sel_hi:[1,0]
	v_pk_mul_f32 v[44:45], v[100:101], v[4:5] op_sel_hi:[1,0]
	v_pk_mul_f32 v[46:47], v[102:103], v[4:5] op_sel_hi:[1,0]
	v_pk_mul_f32 v[48:49], v[104:105], v[4:5] op_sel_hi:[1,0]
	v_pk_mul_f32 v[34:35], v[34:35], v[192:193]
	v_pk_mul_f32 v[36:37], v[36:37], v[194:195]
	v_pk_mul_f32 v[38:39], v[38:39], v[196:197]
	v_pk_mul_f32 v[40:41], v[40:41], v[198:199]
	v_pk_mul_f32 v[42:43], v[42:43], v[200:201]
	v_pk_mul_f32 v[44:45], v[44:45], v[202:203]
	v_pk_mul_f32 v[46:47], v[46:47], v[204:205]
	v_pk_mul_f32 v[48:49], v[48:49], v[206:207]
	v_pk_fma_f32 v[34:35], v[34:35], v[208:209], v[228:229]
	v_pk_fma_f32 v[36:37], v[36:37], v[210:211], v[230:231]
	v_pk_fma_f32 v[38:39], v[38:39], v[212:213], v[232:233]
	v_pk_fma_f32 v[40:41], v[40:41], v[214:215], v[234:235]
	v_pk_fma_f32 v[42:43], v[42:43], v[220:221], v[236:237]
	v_pk_fma_f32 v[44:45], v[44:45], v[222:223], v[238:239]
	v_pk_fma_f32 v[46:47], v[46:47], v[224:225], v[26:27]
	v_pk_fma_f32 v[48:49], v[48:49], v[226:227], v[28:29]
	v_cvt_pk_bf16_f32 v50, v34, v35
	v_cvt_pk_bf16_f32 v51, v36, v37
	v_cvt_pk_bf16_f32 v52, v38, v39
	v_cvt_pk_bf16_f32 v53, v40, v41
	v_cvt_pk_bf16_f32 v54, v42, v43
	v_cvt_pk_bf16_f32 v55, v44, v45
	v_cvt_pk_bf16_f32 v56, v46, v47
	v_cvt_pk_bf16_f32 v57, v48, v49
	global_store_dwordx2 v1, v[50:51], s[16:17] offset:0
	global_store_dwordx2 v1, v[52:53], s[16:17] offset:512
	global_store_dwordx2 v1, v[54:55], s[16:17] offset:1024
	global_store_dwordx2 v1, v[56:57], s[16:17] offset:1536
	s_add_u32 s16, s16, 0x800
	s_addc_u32 s17, s17, 0
	s_waitcnt vmcnt(12)
; __device__ __forceinline__ unsigned cvt_pk_bf16(float lo, float hi) { unsigned r; asm volatile("v_cvt_pk_bf16_f32 %0, %1, %2" : "=v"(r) : "v"(lo), "v"(hi)); return r; }
; template <bool BR, bool WH> ...
;     ...
;         if (WH) {
;             float s = 0.f;
; #pragma unroll
;             for (int j = 0; j < 4; ++j) s += (x[j][0] * x[j][0] + x[j][1] * x[j][1]) + (x[j][2] * x[j][2] + x[j][3] * x[j][3]);
;             const float rs = rsqrtf(wave_sum(s, lane) * (1.f / 1024.f) + EPS);
; #pragma unroll
;             for (int j = 0; j < 4; ++j) { const f32x4 gp = *(const f32x4*)(g_pre + 4 * lane + 256 * j), sc = *(const f32x4*)(mod_h + (size_t)mrow * 6144 + sc_off + 4 * lane + 256 * j),
;                     sh = *(const f32x4*)(mod_h + (size_t)mrow * 6144 + sh_off + 4 * lane + 256 * j);
;                 const f32x4 hv = ((x[j] * rs) * gp) * (sc + 1.0f) + sh;
;                 u32x2 w; w.x = cvt_pk_bf16(hv[0], hv[1]); w.y = cvt_pk_bf16(hv[2], hv[3]);
;                 *(u32x2*)(Hout + (size_t)row * 1024 + 4 * lane + 256 * j) = w; }
;         }
;         if (!hn) break;
; #pragma unroll
;         for (int j = 0; j < 4; ++j) { xc[j] = xn[j]; bc[j] = bn[j]; }
;     }
	v_mul_f32_e32 v6, v106, v106
	v_mul_f32_e32 v7, v107, v107
	v_fmac_f32_e32 v6, v108, v108
	v_fmac_f32_e32 v7, v109, v109
	v_fmac_f32_e32 v6, v110, v110
	v_fmac_f32_e32 v7, v111, v111
	v_fmac_f32_e32 v6, v112, v112
	v_fmac_f32_e32 v7, v113, v113
	v_fmac_f32_e32 v6, v114, v114
	v_fmac_f32_e32 v7, v115, v115
	v_fmac_f32_e32 v6, v116, v116
	v_fmac_f32_e32 v7, v117, v117
	v_fmac_f32_e32 v6, v118, v118
	v_fmac_f32_e32 v7, v119, v119
	v_fmac_f32_e32 v6, v120, v120
	v_fmac_f32_e32 v7, v121, v121
	v_add_f32_e32 v6, v6, v7
	s_nop 1
	v_add_f32_dpp v8, v6, v6 quad_perm:[1,0,3,2] row_mask:0xf bank_mask:0xf
	s_nop 1
	v_add_f32_dpp v8, v8, v8 quad_perm:[2,3,0,1] row_mask:0xf bank_mask:0xf
	s_nop 1
	v_add_f32_dpp v8, v8, v8 row_half_mirror row_mask:0xf bank_mask:0xf
	s_nop 1
	v_add_f32_dpp v8, v8, v8 row_mirror row_mask:0xf bank_mask:0xf
	s_nop 1
	v_add_f32_dpp v8, v8, v8 row_bcast:15 row_mask:0xa bank_mask:0xf
	s_nop 1
	v_add_f32_dpp v8, v8, v8 row_bcast:31 row_mask:0xc bank_mask:0xf
	s_nop 1
	v_readlane_b32 s84, v8, 63
	s_nop 1
	v_fma_f32 v4, s84, v2, v3
	v_rsq_f32_e32 v4, v4
	s_nop 0
	v_pk_mul_f32 v[34:35], v[106:107], v[4:5] op_sel_hi:[1,0]
	v_pk_mul_f32 v[36:37], v[108:109], v[4:5] op_sel_hi:[1,0]
	v_pk_mul_f32 v[38:39], v[110:111], v[4:5] op_sel_hi:[1,0]
	v_pk_mul_f32 v[40:41], v[112:113], v[4:5] op_sel_hi:[1,0]
	v_pk_mul_f32 v[42:43], v[114:115], v[4:5] op_sel_hi:[1,0]
	v_pk_mul_f32 v[44:45], v[116:117], v[4:5] op_sel_hi:[1,0]
	v_pk_mul_f32 v[46:47], v[118:119], v[4:5] op_sel_hi:[1,0]
	v_pk_mul_f32 v[48:49], v[120:121], v[4:5] op_sel_hi:[1,0]
	v_pk_mul_f32 v[34:35], v[34:35], v[192:193]
	v_pk_mul_f32 v[36:37], v[36:37], v[194:195]
	v_pk_mul_f32 v[38:39], v[38:39], v[196:197]
	v_pk_mul_f32 v[40:41], v[40:41], v[198:199]
	v_pk_mul_f32 v[42:43], v[42:43], v[200:201]
	v_pk_mul_f32 v[44:45], v[44:45], v[202:203]
	v_pk_mul_f32 v[46:47], v[46:47], v[204:205]
	v_pk_mul_f32 v[48:49], v[48:49], v[206:207]
	v_pk_fma_f32 v[34:35], v[34:35], v[208:209], v[228:229]
	v_pk_fma_f32 v[36:37], v[36:37], v[210:211], v[230:231]
	v_pk_fma_f32 v[38:39], v[38:39], v[212:213], v[232:233]
	v_pk_fma_f32 v[40:41], v[40:41], v[214:215], v[234:235]
	v_pk_fma_f32 v[42:43], v[42:43], v[220:221], v[236:237]
	v_pk_fma_f32 v[44:45], v[44:45], v[222:223], v[238:239]
	v_pk_fma_f32 v[46:47], v[46:47], v[224:225], v[26:27]
	v_pk_fma_f32 v[48:49], v[48:49], v[226:227], v[28:29]
	v_cvt_pk_bf16_f32 v50, v34, v35
	v_cvt_pk_bf16_f32 v51, v36, v37
	v_cvt_pk_bf16_f32 v52, v38, v39
	v_cvt_pk_bf16_f32 v53, v40, v41
	v_cvt_pk_bf16_f32 v54, v42, v43
	v_cvt_pk_bf16_f32 v55, v44, v45
	v_cvt_pk_bf16_f32 v56, v46, v47
	v_cvt_pk_bf16_f32 v57, v48, v49
	global_store_dwordx2 v1, v[50:51], s[16:17] offset:0
	global_store_dwordx2 v1, v[52:53], s[16:17] offset:512
	global_store_dwordx2 v1, v[54:55], s[16:17] offset:1024
	global_store_dwordx2 v1, v[56:57], s[16:17] offset:1536
	s_add_u32 s16, s16, 0x800
	s_addc_u32 s17, s17, 0
	s_add_u32 s32, s32, s27
	s_branch .Lnrm_A_lat_loop

; __device__ __forceinline__ float bflo(unsigned w) { return __uint_as_float(w << 16); }
; __device__ __forceinline__ float bfhi(unsigned w) { return __uint_as_float(w & 0xffff0000u); }
; template <bool BR, bool WH> ...
;     ...
;     if (gw >= nrows) return;
;     NORM_LOAD(gw, xc, bc);
;     for (int row = gw; row < nrows; row += NGW) {
;         const bool hn = row + NGW < nrows;
;         if (hn) NORM_LOAD(row + NGW, xn, bn);
;         const int mrow = row < ML ? (row >> 12) : 4;
;         f32x4 x[4];
; #pragma unroll
;         for (int j = 0; j < 4; ++j) x[j] = xc[j];
;         if (BR) {
;             f32x4 m[4]; float s = 0.f;
; #pragma unroll
;             for (int j = 0; j < 4; ++j) { m[j] = (f32x4){bflo(bc[j].x), bfhi(bc[j].x), bflo(bc[j].y), bfhi(bc[j].y)};
;                 s += (m[j][0] * m[j][0] + m[j][1] * m[j][1]) + (m[j][2] * m[j][2] + m[j][3] * m[j][3]); }
;             const float rs = rsqrtf(wave_sum(s, lane) * (1.f / 1024.f) + EPS);
;             float* xo = row < ML ? xout_lat + (size_t)row * 1024 : xout_ctx + (size_t)(row - ML) * 1024;
; #pragma unroll
;             for (int j = 0; j < 4; ++j) { const f32x4 gp = *(const f32x4*)(g_post + 4 * lane + 256 * j), ga = *(const f32x4*)(mod_g + (size_t)mrow * 6144 + gate_off + 4 * lane + 256 * j);
;                 x[j] = x[j] + ga * ((m[j] * rs) * gp); __builtin_nontemporal_store(x[j], (f32x4*)(xo + 4 * lane + 256 * j)); }
.Lnrm_B_ctx_loop:
	s_cmpk_lt_u32 s32, 0x400
	s_cbranch_scc0 .Lnrm_B_ctx_done
	s_lshl_b32 s97, s32, 12
	s_add_u32 s4, s48, s97
	s_addc_u32 s5, s49, 0
	s_lshl_b32 s97, s32, 12
	s_add_u32 s14, s40, s97
	s_addc_u32 s15, s41, 0
	s_add_u32 s14, s14, 0x1200000
	s_addc_u32 s15, s15, 0
	s_lshl_b32 s97, s32, 11
	s_add_u32 s16, s56, s97
	s_addc_u32 s17, s57, 0
	s_add_u32 s16, s16, 0x2000000
	s_addc_u32 s17, s17, 0
	global_load_dwordx4 v[106:109], v0, s[4:5] offset:0 nt
	global_load_dwordx4 v[110:113], v0, s[4:5] offset:1024 nt
	global_load_dwordx4 v[114:117], v0, s[4:5] offset:2048 nt
	global_load_dwordx4 v[118:121], v0, s[4:5] offset:3072 nt
	s_lshl_b32 s97, s32, 11
	s_add_u32 s12, s54, s97
	s_addc_u32 s13, s55, 0
	s_add_u32 s12, s12, 0x2200000
	s_addc_u32 s13, s13, 0
	global_load_dwordx2 v[58:59], v1, s[12:13] offset:0
	global_load_dwordx2 v[60:61], v1, s[12:13] offset:512
	global_load_dwordx2 v[62:63], v1, s[12:13] offset:1024
	global_load_dwordx2 v[64:65], v1, s[12:13] offset:1536
	s_add_u32 s12, s12, 0x200000
	s_addc_u32 s13, s13, 0
	global_load_dwordx2 v[66:67], v1, s[12:13] offset:0
	global_load_dwordx2 v[68:69], v1, s[12:13] offset:512
	global_load_dwordx2 v[70:71], v1, s[12:13] offset:1024
	global_load_dwordx2 v[72:73], v1, s[12:13] offset:1536
	s_add_u32 s12, s12, 0x200000
	s_addc_u32 s13, s13, 0
	global_load_dwordx2 v[74:75], v1, s[12:13] offset:0
	global_load_dwordx2 v[76:77], v1, s[12:13] offset:512
	global_load_dwordx2 v[78:79], v1, s[12:13] offset:1024
	global_load_dwordx2 v[80:81], v1, s[12:13] offset:1536
	s_add_u32 s12, s12, 0x200000
	s_addc_u32 s13, s13, 0
	global_load_dwordx2 v[82:83], v1, s[12:13] offset:0
	global_load_dwordx2 v[84:85], v1, s[12:13] offset:512
	global_load_dwordx2 v[86:87], v1, s[12:13] offset:1024
	global_load_dwordx2 v[88:89], v1, s[12:13] offset:1536
	s_mov_b32 s88, 0x18000
	global_load_dwordx4 v[154:157], v0, s[90:91] offset:0
	global_load_dwordx4 v[158:161], v0, s[90:91] offset:1024
	global_load_dwordx4 v[162:165], v0, s[90:91] offset:2048
	global_load_dwordx4 v[166:169], v0, s[90:91] offset:3072
	s_add_u32 s98, s88, s8
	s_add_u32 s98, s98, s40
	s_addc_u32 s99, s41, 0
	s_add_u32 s98, s98, 0x1600000
	s_addc_u32 s99, s99, 0
	global_load_dwordx4 v[176:179], v0, s[98:99] offset:0
	global_load_dwordx4 v[180:183], v0, s[98:99] offset:1024
	global_load_dwordx4 v[184:187], v0, s[98:99] offset:2048
	global_load_dwordx4 v[188:191], v0, s[98:99] offset:3072
	global_load_dwordx4 v[192:195], v0, s[24:25] offset:0
	global_load_dwordx4 v[196:199], v0, s[24:25] offset:1024
	global_load_dwordx4 v[200:203], v0, s[24:25] offset:2048
	global_load_dwordx4 v[204:207], v0, s[24:25] offset:3072
	s_add_u32 s100, s88, s59
	s_add_u32 s100, s100, s40
	s_addc_u32 s101, s41, 0
	s_add_u32 s100, s100, 0x1600000
	s_addc_u32 s101, s101, 0
	global_load_dwordx4 v[208:211], v0, s[100:101] offset:0
	global_load_dwordx4 v[212:215], v0, s[100:101] offset:1024
	global_load_dwordx4 v[220:223], v0, s[100:101] offset:2048
	global_load_dwordx4 v[224:227], v0, s[100:101] offset:3072
	s_add_u32 s100, s88, s73
	s_add_u32 s100, s100, s40
	s_addc_u32 s101, s41, 0
	s_add_u32 s100, s100, 0x1600000
	s_addc_u32 s101, s101, 0
	global_load_dwordx4 v[228:231], v0, s[100:101] offset:0
	global_load_dwordx4 v[232:235], v0, s[100:101] offset:1024
	global_load_dwordx4 v[236:239], v0, s[100:101] offset:2048
	global_load_dwordx4 v[26:29], v0, s[100:101] offset:3072
	s_waitcnt vmcnt(0)
	v_pk_add_f32 v[208:209], v[208:209], 1.0 op_sel_hi:[1,0]
	v_pk_add_f32 v[210:211], v[210:211], 1.0 op_sel_hi:[1,0]
	v_pk_add_f32 v[212:213], v[212:213], 1.0 op_sel_hi:[1,0]
	v_pk_add_f32 v[214:215], v[214:215], 1.0 op_sel_hi:[1,0]
	v_pk_add_f32 v[220:221], v[220:221], 1.0 op_sel_hi:[1,0]
	v_pk_add_f32 v[222:223], v[222:223], 1.0 op_sel_hi:[1,0]
	v_pk_add_f32 v[224:225], v[224:225], 1.0 op_sel_hi:[1,0]
	v_pk_add_f32 v[226:227], v[226:227], 1.0 op_sel_hi:[1,0]
	v_lshlrev_b32_e32 v10, 16, v58
	v_and_b32_e32 v11, 0xffff0000, v58
	v_lshlrev_b32_e32 v12, 16, v59
	v_and_b32_e32 v13, 0xffff0000, v59
	v_lshlrev_b32_e32 v34, 16, v66
	v_and_b32_e32 v35, 0xffff0000, v66
	v_lshlrev_b32_e32 v36, 16, v67
	v_and_b32_e32 v37, 0xffff0000, v67
	v_add_f32_e32 v10, v10, v34
	v_add_f32_e32 v11, v11, v35
	v_add_f32_e32 v12, v12, v36
	v_add_f32_e32 v13, v13, v37
	v_lshlrev_b32_e32 v34, 16, v74
	v_and_b32_e32 v35, 0xffff0000, v74
	v_lshlrev_b32_e32 v36, 16, v75
	v_and_b32_e32 v37, 0xffff0000, v75
	v_add_f32_e32 v10, v10, v34
	v_add_f32_e32 v11, v11, v35
	v_add_f32_e32 v12, v12, v36
	v_add_f32_e32 v13, v13, v37
	v_lshlrev_b32_e32 v34, 16, v82
	v_and_b32_e32 v35, 0xffff0000, v82
	v_lshlrev_b32_e32 v36, 16, v83
	v_and_b32_e32 v37, 0xffff0000, v83
	v_add_f32_e32 v10, v10, v34
	v_add_f32_e32 v11, v11, v35
	v_add_f32_e32 v12, v12, v36
	v_add_f32_e32 v13, v13, v37
	v_cvt_pk_bf16_f32 v146, v10, v11
	v_cvt_pk_bf16_f32 v147, v12, v13
	v_lshlrev_b32_e32 v10, 16, v60
	v_and_b32_e32 v11, 0xffff0000, v60
	v_lshlrev_b32_e32 v12, 16, v61
	v_and_b32_e32 v13, 0xffff0000, v61
	v_lshlrev_b32_e32 v34, 16, v68
	v_and_b32_e32 v35, 0xffff0000, v68
	v_lshlrev_b32_e32 v36, 16, v69
	v_and_b32_e32 v37, 0xffff0000, v69
	v_add_f32_e32 v10, v10, v34
	v_add_f32_e32 v11, v11, v35
	v_add_f32_e32 v12, v12, v36
	v_add_f32_e32 v13, v13, v37
	v_lshlrev_b32_e32 v34, 16, v76
	v_and_b32_e32 v35, 0xffff0000, v76
	v_lshlrev_b32_e32 v36, 16, v77
	v_and_b32_e32 v37, 0xffff0000, v77
	v_add_f32_e32 v10, v10, v34
	v_add_f32_e32 v11, v11, v35
	v_add_f32_e32 v12, v12, v36
	v_add_f32_e32 v13, v13, v37
	v_lshlrev_b32_e32 v34, 16, v84
	v_and_b32_e32 v35, 0xffff0000, v84
	v_lshlrev_b32_e32 v36, 16, v85
	v_and_b32_e32 v37, 0xffff0000, v85
	v_add_f32_e32 v10, v10, v34
; __device__ __forceinline__ float bflo(unsigned w) { return __uint_as_float(w << 16); }
; __device__ __forceinline__ float bfhi(unsigned w) { return __uint_as_float(w & 0xffff0000u); }
; template <bool BR, bool WH> ...
;     ...
;         if (BR) {
;             f32x4 m[4]; float s = 0.f;
; #pragma unroll
;             for (int j = 0; j < 4; ++j) { m[j] = (f32x4){bflo(bc[j].x), bfhi(bc[j].x), bflo(bc[j].y), bfhi(bc[j].y)};
;                 s += (m[j][0] * m[j][0] + m[j][1] * m[j][1]) + (m[j][2] * m[j][2] + m[j][3] * m[j][3]); }
;             const float rs = rsqrtf(wave_sum(s, lane) * (1.f / 1024.f) + EPS);
;             float* xo = row < ML ? xout_lat + (size_t)row * 1024 : xout_ctx + (size_t)(row - ML) * 1024;
; #pragma unroll
;             for (int j = 0; j < 4; ++j) { const f32x4 gp = *(const f32x4*)(g_post + 4 * lane + 256 * j), ga = *(const f32x4*)(mod_g + (size_t)mrow * 6144 + gate_off + 4 * lane + 256 * j);
;                 x[j] = x[j] + ga * ((m[j] * rs) * gp); __builtin_nontemporal_store(x[j], (f32x4*)(xo + 4 * lane + 256 * j)); }
;         }
;         if (WH) {
;             float s = 0.f;
; #pragma unroll
;             for (int j = 0; j < 4; ++j) s += (x[j][0] * x[j][0] + x[j][1] * x[j][1]) + (x[j][2] * x[j][2] + x[j][3] * x[j][3]);
;             const float rs = rsqrtf(wave_sum(s, lane) * (1.f / 1024.f) + EPS);
; #pragma unroll
;             for (int j = 0; j < 4; ++j) { const f32x4 gp = *(const f32x4*)(g_pre + 4 * lane + 256 * j), sc = *(const f32x4*)(mod_h + (size_t)mrow * 6144 + sc_off + 4 * lane + 256 * j),
	v_add_f32_e32 v11, v11, v35
	v_add_f32_e32 v12, v12, v36
	v_add_f32_e32 v13, v13, v37
	v_cvt_pk_bf16_f32 v148, v10, v11
	v_cvt_pk_bf16_f32 v149, v12, v13
	v_lshlrev_b32_e32 v10, 16, v62
	v_and_b32_e32 v11, 0xffff0000, v62
	v_lshlrev_b32_e32 v12, 16, v63
	v_and_b32_e32 v13, 0xffff0000, v63
	v_lshlrev_b32_e32 v34, 16, v70
	v_and_b32_e32 v35, 0xffff0000, v70
	v_lshlrev_b32_e32 v36, 16, v71
	v_and_b32_e32 v37, 0xffff0000, v71
	v_add_f32_e32 v10, v10, v34
	v_add_f32_e32 v11, v11, v35
	v_add_f32_e32 v12, v12, v36
	v_add_f32_e32 v13, v13, v37
	v_lshlrev_b32_e32 v34, 16, v78
	v_and_b32_e32 v35, 0xffff0000, v78
	v_lshlrev_b32_e32 v36, 16, v79
	v_and_b32_e32 v37, 0xffff0000, v79
	v_add_f32_e32 v10, v10, v34
	v_add_f32_e32 v11, v11, v35
	v_add_f32_e32 v12, v12, v36
	v_add_f32_e32 v13, v13, v37
	v_lshlrev_b32_e32 v34, 16, v86
	v_and_b32_e32 v35, 0xffff0000, v86
	v_lshlrev_b32_e32 v36, 16, v87
	v_and_b32_e32 v37, 0xffff0000, v87
	v_add_f32_e32 v10, v10, v34
	v_add_f32_e32 v11, v11, v35
	v_add_f32_e32 v12, v12, v36
	v_add_f32_e32 v13, v13, v37
	v_cvt_pk_bf16_f32 v150, v10, v11
	v_cvt_pk_bf16_f32 v151, v12, v13
	v_lshlrev_b32_e32 v10, 16, v64
	v_and_b32_e32 v11, 0xffff0000, v64
	v_lshlrev_b32_e32 v12, 16, v65
	v_and_b32_e32 v13, 0xffff0000, v65
	v_lshlrev_b32_e32 v34, 16, v72
	v_and_b32_e32 v35, 0xffff0000, v72
	v_lshlrev_b32_e32 v36, 16, v73
	v_and_b32_e32 v37, 0xffff0000, v73
	v_add_f32_e32 v10, v10, v34
	v_add_f32_e32 v11, v11, v35
	v_add_f32_e32 v12, v12, v36
	v_add_f32_e32 v13, v13, v37
	v_lshlrev_b32_e32 v34, 16, v80
	v_and_b32_e32 v35, 0xffff0000, v80
	v_lshlrev_b32_e32 v36, 16, v81
	v_and_b32_e32 v37, 0xffff0000, v81
	v_add_f32_e32 v10, v10, v34
	v_add_f32_e32 v11, v11, v35
	v_add_f32_e32 v12, v12, v36
	v_add_f32_e32 v13, v13, v37
	v_lshlrev_b32_e32 v34, 16, v88
	v_and_b32_e32 v35, 0xffff0000, v88
	v_lshlrev_b32_e32 v36, 16, v89
	v_and_b32_e32 v37, 0xffff0000, v89
	v_add_f32_e32 v10, v10, v34
	v_add_f32_e32 v11, v11, v35
	v_add_f32_e32 v12, v12, v36
	v_add_f32_e32 v13, v13, v37
	v_cvt_pk_bf16_f32 v152, v10, v11
	v_cvt_pk_bf16_f32 v153, v12, v13
	v_lshlrev_b32_e32 v10, 16, v146
	v_and_b32_e32 v11, 0xffff0000, v146
	v_lshlrev_b32_e32 v12, 16, v147
	v_and_b32_e32 v13, 0xffff0000, v147
	v_lshlrev_b32_e32 v14, 16, v148
	v_and_b32_e32 v15, 0xffff0000, v148
	v_lshlrev_b32_e32 v16, 16, v149
	v_and_b32_e32 v17, 0xffff0000, v149
	v_lshlrev_b32_e32 v18, 16, v150
	v_and_b32_e32 v19, 0xffff0000, v150
	v_lshlrev_b32_e32 v20, 16, v151
	v_and_b32_e32 v21, 0xffff0000, v151
	v_lshlrev_b32_e32 v22, 16, v152
	v_and_b32_e32 v23, 0xffff0000, v152
	v_lshlrev_b32_e32 v24, 16, v153
	v_and_b32_e32 v25, 0xffff0000, v153
	v_mul_f32_e32 v6, v10, v10
	v_mul_f32_e32 v7, v11, v11
	v_fmac_f32_e32 v6, v12, v12
	v_fmac_f32_e32 v7, v13, v13
	v_fmac_f32_e32 v6, v14, v14
	v_fmac_f32_e32 v7, v15, v15
	v_fmac_f32_e32 v6, v16, v16
	v_fmac_f32_e32 v7, v17, v17
	v_fmac_f32_e32 v6, v18, v18
	v_fmac_f32_e32 v7, v19, v19
	v_fmac_f32_e32 v6, v20, v20
	v_fmac_f32_e32 v7, v21, v21
	v_fmac_f32_e32 v6, v22, v22
	v_fmac_f32_e32 v7, v23, v23
	v_fmac_f32_e32 v6, v24, v24
	v_fmac_f32_e32 v7, v25, v25
	v_add_f32_e32 v6, v6, v7
	s_nop 1
	v_add_f32_dpp v8, v6, v6 quad_perm:[1,0,3,2] row_mask:0xf bank_mask:0xf
	s_nop 1
	v_add_f32_dpp v8, v8, v8 quad_perm:[2,3,0,1] row_mask:0xf bank_mask:0xf
	s_nop 1
	v_add_f32_dpp v8, v8, v8 row_half_mirror row_mask:0xf bank_mask:0xf
	s_nop 1
	v_add_f32_dpp v8, v8, v8 row_mirror row_mask:0xf bank_mask:0xf
	s_nop 1
	v_add_f32_dpp v8, v8, v8 row_bcast:15 row_mask:0xa bank_mask:0xf
	s_nop 1
	v_add_f32_dpp v8, v8, v8 row_bcast:31 row_mask:0xc bank_mask:0xf
	s_nop 1
	v_readlane_b32 s84, v8, 63
	s_nop 1
	v_fma_f32 v4, s84, v2, v3
	v_rsq_f32_e32 v4, v4
	s_nop 0
	v_pk_mul_f32 v[34:35], v[10:11], v[4:5] op_sel_hi:[1,0]
	v_pk_mul_f32 v[36:37], v[12:13], v[4:5] op_sel_hi:[1,0]
	v_pk_mul_f32 v[38:39], v[14:15], v[4:5] op_sel_hi:[1,0]
	v_pk_mul_f32 v[40:41], v[16:17], v[4:5] op_sel_hi:[1,0]
	v_pk_mul_f32 v[42:43], v[18:19], v[4:5] op_sel_hi:[1,0]
	v_pk_mul_f32 v[44:45], v[20:21], v[4:5] op_sel_hi:[1,0]
	v_pk_mul_f32 v[46:47], v[22:23], v[4:5] op_sel_hi:[1,0]
	v_pk_mul_f32 v[48:49], v[24:25], v[4:5] op_sel_hi:[1,0]
	v_pk_mul_f32 v[34:35], v[34:35], v[154:155]
	v_pk_mul_f32 v[36:37], v[36:37], v[156:157]
	v_pk_mul_f32 v[38:39], v[38:39], v[158:159]
	v_pk_mul_f32 v[40:41], v[40:41], v[160:161]
	v_pk_mul_f32 v[42:43], v[42:43], v[162:163]
	v_pk_mul_f32 v[44:45], v[44:45], v[164:165]
	v_pk_mul_f32 v[46:47], v[46:47], v[166:167]
	v_pk_mul_f32 v[48:49], v[48:49], v[168:169]
	v_pk_fma_f32 v[106:107], v[176:177], v[34:35], v[106:107]
	v_pk_fma_f32 v[108:109], v[178:179], v[36:37], v[108:109]
	v_pk_fma_f32 v[110:111], v[180:181], v[38:39], v[110:111]
	v_pk_fma_f32 v[112:113], v[182:183], v[40:41], v[112:113]
	v_pk_fma_f32 v[114:115], v[184:185], v[42:43], v[114:115]
	v_pk_fma_f32 v[116:117], v[186:187], v[44:45], v[116:117]
	v_pk_fma_f32 v[118:119], v[188:189], v[46:47], v[118:119]
	v_pk_fma_f32 v[120:121], v[190:191], v[48:49], v[120:121]
	global_store_dwordx4 v0, v[106:109], s[14:15] offset:0 nt
	global_store_dwordx4 v0, v[110:113], s[14:15] offset:1024 nt
	global_store_dwordx4 v0, v[114:117], s[14:15] offset:2048 nt
	global_store_dwordx4 v0, v[118:121], s[14:15] offset:3072 nt
	v_mul_f32_e32 v6, v106, v106
	v_mul_f32_e32 v7, v107, v107
	v_fmac_f32_e32 v6, v108, v108
	v_fmac_f32_e32 v7, v109, v109
	v_fmac_f32_e32 v6, v110, v110
	v_fmac_f32_e32 v7, v111, v111
	v_fmac_f32_e32 v6, v112, v112
	v_fmac_f32_e32 v7, v113, v113
	v_fmac_f32_e32 v6, v114, v114
	v_fmac_f32_e32 v7, v115, v115
	v_fmac_f32_e32 v6, v116, v116
	v_fmac_f32_e32 v7, v117, v117
	v_fmac_f32_e32 v6, v118, v118
; __device__ __forceinline__ unsigned cvt_pk_bf16(float lo, float hi) { unsigned r; asm volatile("v_cvt_pk_bf16_f32 %0, %1, %2" : "=v"(r) : "v"(lo), "v"(hi)); return r; }
; template <bool BR, bool WH> ...
;     ...
;     if (gw >= nrows) return;
;     NORM_LOAD(gw, xc, bc);
;     for (int row = gw; row < nrows; row += NGW) {
;         const bool hn = row + NGW < nrows;
;         if (hn) NORM_LOAD(row + NGW, xn, bn);
;     ...
;         if (WH) {
;             float s = 0.f;
; #pragma unroll
;             for (int j = 0; j < 4; ++j) s += (x[j][0] * x[j][0] + x[j][1] * x[j][1]) + (x[j][2] * x[j][2] + x[j][3] * x[j][3]);
;             const float rs = rsqrtf(wave_sum(s, lane) * (1.f / 1024.f) + EPS);
; #pragma unroll
;             for (int j = 0; j < 4; ++j) { const f32x4 gp = *(const f32x4*)(g_pre + 4 * lane + 256 * j), sc = *(const f32x4*)(mod_h + (size_t)mrow * 6144 + sc_off + 4 * lane + 256 * j),
;                     sh = *(const f32x4*)(mod_h + (size_t)mrow * 6144 + sh_off + 4 * lane + 256 * j);
;                 const f32x4 hv = ((x[j] * rs) * gp) * (sc + 1.0f) + sh;
;                 u32x2 w; w.x = cvt_pk_bf16(hv[0], hv[1]); w.y = cvt_pk_bf16(hv[2], hv[3]);
;                 *(u32x2*)(Hout + (size_t)row * 1024 + 4 * lane + 256 * j) = w; }
;         }
	v_fmac_f32_e32 v7, v119, v119
	v_fmac_f32_e32 v6, v120, v120
	v_fmac_f32_e32 v7, v121, v121
	v_add_f32_e32 v6, v6, v7
	s_nop 1
	v_add_f32_dpp v8, v6, v6 quad_perm:[1,0,3,2] row_mask:0xf bank_mask:0xf
	s_nop 1
	v_add_f32_dpp v8, v8, v8 quad_perm:[2,3,0,1] row_mask:0xf bank_mask:0xf
	s_nop 1
	v_add_f32_dpp v8, v8, v8 row_half_mirror row_mask:0xf bank_mask:0xf
	s_nop 1
	v_add_f32_dpp v8, v8, v8 row_mirror row_mask:0xf bank_mask:0xf
	s_nop 1
	v_add_f32_dpp v8, v8, v8 row_bcast:15 row_mask:0xa bank_mask:0xf
	s_nop 1
	v_add_f32_dpp v8, v8, v8 row_bcast:31 row_mask:0xc bank_mask:0xf
	s_nop 1
	v_readlane_b32 s84, v8, 63
	s_nop 1
	v_fma_f32 v4, s84, v2, v3
	v_rsq_f32_e32 v4, v4
	s_nop 0
	v_pk_mul_f32 v[34:35], v[106:107], v[4:5] op_sel_hi:[1,0]
	v_pk_mul_f32 v[36:37], v[108:109], v[4:5] op_sel_hi:[1,0]
	v_pk_mul_f32 v[38:39], v[110:111], v[4:5] op_sel_hi:[1,0]
	v_pk_mul_f32 v[40:41], v[112:113], v[4:5] op_sel_hi:[1,0]
	v_pk_mul_f32 v[42:43], v[114:115], v[4:5] op_sel_hi:[1,0]
	v_pk_mul_f32 v[44:45], v[116:117], v[4:5] op_sel_hi:[1,0]
	v_pk_mul_f32 v[46:47], v[118:119], v[4:5] op_sel_hi:[1,0]
	v_pk_mul_f32 v[48:49], v[120:121], v[4:5] op_sel_hi:[1,0]
	v_pk_mul_f32 v[34:35], v[34:35], v[192:193]
	v_pk_mul_f32 v[36:37], v[36:37], v[194:195]
	v_pk_mul_f32 v[38:39], v[38:39], v[196:197]
	v_pk_mul_f32 v[40:41], v[40:41], v[198:199]
	v_pk_mul_f32 v[42:43], v[42:43], v[200:201]
	v_pk_mul_f32 v[44:45], v[44:45], v[202:203]
	v_pk_mul_f32 v[46:47], v[46:47], v[204:205]
	v_pk_mul_f32 v[48:49], v[48:49], v[206:207]
	v_pk_fma_f32 v[34:35], v[34:35], v[208:209], v[228:229]
	v_pk_fma_f32 v[36:37], v[36:37], v[210:211], v[230:231]
	v_pk_fma_f32 v[38:39], v[38:39], v[212:213], v[232:233]
	v_pk_fma_f32 v[40:41], v[40:41], v[214:215], v[234:235]
	v_pk_fma_f32 v[42:43], v[42:43], v[220:221], v[236:237]
	v_pk_fma_f32 v[44:45], v[44:45], v[222:223], v[238:239]
	v_pk_fma_f32 v[46:47], v[46:47], v[224:225], v[26:27]
	v_pk_fma_f32 v[48:49], v[48:49], v[226:227], v[28:29]
	v_cvt_pk_bf16_f32 v50, v34, v35
	v_cvt_pk_bf16_f32 v51, v36, v37
	v_cvt_pk_bf16_f32 v52, v38, v39
	v_cvt_pk_bf16_f32 v53, v40, v41
	v_cvt_pk_bf16_f32 v54, v42, v43
	v_cvt_pk_bf16_f32 v55, v44, v45
	v_cvt_pk_bf16_f32 v56, v46, v47
	v_cvt_pk_bf16_f32 v57, v48, v49
	global_store_dwordx2 v1, v[50:51], s[16:17] offset:0
	global_store_dwordx2 v1, v[52:53], s[16:17] offset:512
	global_store_dwordx2 v1, v[54:55], s[16:17] offset:1024
	global_store_dwordx2 v1, v[56:57], s[16:17] offset:1536
	s_add_u32 s32, s32, s27
	s_branch .Lnrm_B_ctx_loop
.Lnrm_B_ctx_done:
.Lnrm_bodyB_lat:
	s_mov_b32 s32, s2
.Lnrm_B_lat_loop:
	s_cmpk_lt_u32 s32, 0x800
	s_cbranch_scc0 .Lnrm_ret
	s_lshl_b32 s97, s32, 15
	s_add_u32 s4, s44, s97
	s_addc_u32 s5, s45, 0
	s_lshl_b32 s97, s32, 14
	s_add_u32 s12, s54, s97
	s_addc_u32 s13, s55, 0
	s_lshl_b32 s97, s32, 15
	s_add_u32 s14, s42, s97
	s_addc_u32 s15, s43, 0
	s_lshl_b32 s97, s32, 14
	s_add_u32 s16, s56, s97
	s_addc_u32 s17, s57, 0
	s_lshr_b32 s88, s32, 9
	s_mul_i32 s88, s88, 0x6000
	global_load_dwordx4 v[58:61], v0, s[4:5] offset:0 nt
	global_load_dwordx4 v[62:65], v0, s[4:5] offset:1024 nt
	global_load_dwordx4 v[66:69], v0, s[4:5] offset:2048 nt
	global_load_dwordx4 v[70:73], v0, s[4:5] offset:3072 nt
	global_load_dwordx2 v[122:123], v1, s[12:13] offset:0 nt
	global_load_dwordx2 v[124:125], v1, s[12:13] offset:512 nt
	global_load_dwordx2 v[126:127], v1, s[12:13] offset:1024 nt
	global_load_dwordx2 v[128:129], v1, s[12:13] offset:1536 nt
	s_add_u32 s4, s4, 0x1000
	s_addc_u32 s5, s5, 0
	s_add_u32 s12, s12, 0x800
	s_addc_u32 s13, s13, 0
	global_load_dwordx4 v[154:157], v0, s[90:91] offset:0
	global_load_dwordx4 v[158:161], v0, s[90:91] offset:1024
	global_load_dwordx4 v[162:165], v0, s[90:91] offset:2048
	global_load_dwordx4 v[166:169], v0, s[90:91] offset:3072
	s_add_u32 s98, s88, s8
	s_add_u32 s98, s98, s40
	s_addc_u32 s99, s41, 0
	s_add_u32 s98, s98, 0x1600000
	s_addc_u32 s99, s99, 0
	global_load_dwordx4 v[176:179], v0, s[98:99] offset:0
	global_load_dwordx4 v[180:183], v0, s[98:99] offset:1024
	global_load_dwordx4 v[184:187], v0, s[98:99] offset:2048
	global_load_dwordx4 v[188:191], v0, s[98:99] offset:3072
	global_load_dwordx4 v[192:195], v0, s[24:25] offset:0
	global_load_dwordx4 v[196:199], v0, s[24:25] offset:1024
	global_load_dwordx4 v[200:203], v0, s[24:25] offset:2048
	global_load_dwordx4 v[204:207], v0, s[24:25] offset:3072
	s_add_u32 s100, s88, s59
	s_add_u32 s100, s100, s40
	s_addc_u32 s101, s41, 0
	s_add_u32 s100, s100, 0x1600000
	s_addc_u32 s101, s101, 0
	global_load_dwordx4 v[208:211], v0, s[100:101] offset:0
	global_load_dwordx4 v[212:215], v0, s[100:101] offset:1024
	global_load_dwordx4 v[220:223], v0, s[100:101] offset:2048
	global_load_dwordx4 v[224:227], v0, s[100:101] offset:3072
	s_add_u32 s100, s88, s73
	s_add_u32 s100, s100, s40
	s_addc_u32 s101, s41, 0
	s_add_u32 s100, s100, 0x1600000
	s_addc_u32 s101, s101, 0
	global_load_dwordx4 v[228:231], v0, s[100:101] offset:0
	global_load_dwordx4 v[232:235], v0, s[100:101] offset:1024
	global_load_dwordx4 v[236:239], v0, s[100:101] offset:2048
	global_load_dwordx4 v[26:29], v0, s[100:101] offset:3072
	global_load_dwordx4 v[74:77], v0, s[4:5] offset:0 nt
	global_load_dwordx4 v[78:81], v0, s[4:5] offset:1024 nt
	global_load_dwordx4 v[82:85], v0, s[4:5] offset:2048 nt
	global_load_dwordx4 v[86:89], v0, s[4:5] offset:3072 nt
	global_load_dwordx2 v[130:131], v1, s[12:13] offset:0 nt
	global_load_dwordx2 v[132:133], v1, s[12:13] offset:512 nt
	global_load_dwordx2 v[134:135], v1, s[12:13] offset:1024 nt
	global_load_dwordx2 v[136:137], v1, s[12:13] offset:1536 nt
	s_add_u32 s4, s4, 0x1000
	s_addc_u32 s5, s5, 0
	s_add_u32 s12, s12, 0x800
	s_addc_u32 s13, s13, 0
	global_load_dwordx4 v[90:93], v0, s[4:5] offset:0 nt
	global_load_dwordx4 v[94:97], v0, s[4:5] offset:1024 nt
	global_load_dwordx4 v[98:101], v0, s[4:5] offset:2048 nt
	global_load_dwordx4 v[102:105], v0, s[4:5] offset:3072 nt
	global_load_dwordx2 v[138:139], v1, s[12:13] offset:0 nt
	global_load_dwordx2 v[140:141], v1, s[12:13] offset:512 nt
	global_load_dwordx2 v[142:143], v1, s[12:13] offset:1024 nt
	global_load_dwordx2 v[144:145], v1, s[12:13] offset:1536 nt
	s_add_u32 s4, s4, 0x1000
	s_addc_u32 s5, s5, 0
	s_add_u32 s12, s12, 0x800
	s_addc_u32 s13, s13, 0
	global_load_dwordx4 v[106:109], v0, s[4:5] offset:0 nt
	global_load_dwordx4 v[110:113], v0, s[4:5] offset:1024 nt
	global_load_dwordx4 v[114:117], v0, s[4:5] offset:2048 nt
	global_load_dwordx4 v[118:121], v0, s[4:5] offset:3072 nt
	global_load_dwordx2 v[146:147], v1, s[12:13] offset:0 nt
	global_load_dwordx2 v[148:149], v1, s[12:13] offset:512 nt
	global_load_dwordx2 v[150:151], v1, s[12:13] offset:1024 nt
	global_load_dwordx2 v[152:153], v1, s[12:13] offset:1536 nt
	s_add_u32 s4, s4, 0x1000
	s_addc_u32 s5, s5, 0
	s_add_u32 s12, s12, 0x800
	s_addc_u32 s13, s13, 0
	s_waitcnt vmcnt(24)
; __device__ __forceinline__ float bflo(unsigned w) { return __uint_as_float(w << 16); }
; __device__ __forceinline__ float bfhi(unsigned w) { return __uint_as_float(w & 0xffff0000u); }
; template <bool BR, bool WH> ...
;     ...
;         if (BR) {
;             f32x4 m[4]; float s = 0.f;
; #pragma unroll
;             for (int j = 0; j < 4; ++j) { m[j] = (f32x4){bflo(bc[j].x), bfhi(bc[j].x), bflo(bc[j].y), bfhi(bc[j].y)};
;                 s += (m[j][0] * m[j][0] + m[j][1] * m[j][1]) + (m[j][2] * m[j][2] + m[j][3] * m[j][3]); }
;             const float rs = rsqrtf(wave_sum(s, lane) * (1.f / 1024.f) + EPS);
;             float* xo = row < ML ? xout_lat + (size_t)row * 1024 : xout_ctx + (size_t)(row - ML) * 1024;
; #pragma unroll
;             for (int j = 0; j < 4; ++j) { const f32x4 gp = *(const f32x4*)(g_post + 4 * lane + 256 * j), ga = *(const f32x4*)(mod_g + (size_t)mrow * 6144 + gate_off + 4 * lane + 256 * j);
;                 x[j] = x[j] + ga * ((m[j] * rs) * gp); __builtin_nontemporal_store(x[j], (f32x4*)(xo + 4 * lane + 256 * j)); }
;         }
;         if (WH) {
;             float s = 0.f;
; #pragma unroll
;             for (int j = 0; j < 4; ++j) s += (x[j][0] * x[j][0] + x[j][1] * x[j][1]) + (x[j][2] * x[j][2] + x[j][3] * x[j][3]);
;             const float rs = rsqrtf(wave_sum(s, lane) * (1.f / 1024.f) + EPS);
; #pragma unroll
;             for (int j = 0; j < 4; ++j) { const f32x4 gp = *(const f32x4*)(g_pre + 4 * lane + 256 * j), sc = *(const f32x4*)(mod_h + (size_t)mrow * 6144 + sc_off + 4 * lane + 256 * j),
;                     sh = *(const f32x4*)(mod_h + (size_t)mrow * 6144 + sh_off + 4 * lane + 256 * j);
;                 const f32x4 hv = ((x[j] * rs) * gp) * (sc + 1.0f) + sh;
	v_pk_add_f32 v[208:209], v[208:209], 1.0 op_sel_hi:[1,0]
	v_pk_add_f32 v[210:211], v[210:211], 1.0 op_sel_hi:[1,0]
	v_pk_add_f32 v[212:213], v[212:213], 1.0 op_sel_hi:[1,0]
	v_pk_add_f32 v[214:215], v[214:215], 1.0 op_sel_hi:[1,0]
	v_pk_add_f32 v[220:221], v[220:221], 1.0 op_sel_hi:[1,0]
	v_pk_add_f32 v[222:223], v[222:223], 1.0 op_sel_hi:[1,0]
	v_pk_add_f32 v[224:225], v[224:225], 1.0 op_sel_hi:[1,0]
	v_pk_add_f32 v[226:227], v[226:227], 1.0 op_sel_hi:[1,0]
	v_lshlrev_b32_e32 v10, 16, v122
	v_and_b32_e32 v11, 0xffff0000, v122
	v_lshlrev_b32_e32 v12, 16, v123
	v_and_b32_e32 v13, 0xffff0000, v123
	v_lshlrev_b32_e32 v14, 16, v124
	v_and_b32_e32 v15, 0xffff0000, v124
	v_lshlrev_b32_e32 v16, 16, v125
	v_and_b32_e32 v17, 0xffff0000, v125
	v_lshlrev_b32_e32 v18, 16, v126
	v_and_b32_e32 v19, 0xffff0000, v126
	v_lshlrev_b32_e32 v20, 16, v127
	v_and_b32_e32 v21, 0xffff0000, v127
	v_lshlrev_b32_e32 v22, 16, v128
	v_and_b32_e32 v23, 0xffff0000, v128
	v_lshlrev_b32_e32 v24, 16, v129
	v_and_b32_e32 v25, 0xffff0000, v129
	v_mul_f32_e32 v6, v10, v10
	v_mul_f32_e32 v7, v11, v11
	v_fmac_f32_e32 v6, v12, v12
	v_fmac_f32_e32 v7, v13, v13
	v_fmac_f32_e32 v6, v14, v14
	v_fmac_f32_e32 v7, v15, v15
	v_fmac_f32_e32 v6, v16, v16
	v_fmac_f32_e32 v7, v17, v17
	v_fmac_f32_e32 v6, v18, v18
	v_fmac_f32_e32 v7, v19, v19
	v_fmac_f32_e32 v6, v20, v20
	v_fmac_f32_e32 v7, v21, v21
	v_fmac_f32_e32 v6, v22, v22
	v_fmac_f32_e32 v7, v23, v23
	v_fmac_f32_e32 v6, v24, v24
	v_fmac_f32_e32 v7, v25, v25
	v_add_f32_e32 v6, v6, v7
	s_nop 1
	v_add_f32_dpp v8, v6, v6 quad_perm:[1,0,3,2] row_mask:0xf bank_mask:0xf
	s_nop 1
	v_add_f32_dpp v8, v8, v8 quad_perm:[2,3,0,1] row_mask:0xf bank_mask:0xf
	s_nop 1
	v_add_f32_dpp v8, v8, v8 row_half_mirror row_mask:0xf bank_mask:0xf
	s_nop 1
	v_add_f32_dpp v8, v8, v8 row_mirror row_mask:0xf bank_mask:0xf
	s_nop 1
	v_add_f32_dpp v8, v8, v8 row_bcast:15 row_mask:0xa bank_mask:0xf
	s_nop 1
	v_add_f32_dpp v8, v8, v8 row_bcast:31 row_mask:0xc bank_mask:0xf
	s_nop 1
	v_readlane_b32 s84, v8, 63
	s_nop 1
	v_fma_f32 v4, s84, v2, v3
	v_rsq_f32_e32 v4, v4
	s_nop 0
	v_pk_mul_f32 v[34:35], v[10:11], v[4:5] op_sel_hi:[1,0]
	v_pk_mul_f32 v[36:37], v[12:13], v[4:5] op_sel_hi:[1,0]
	v_pk_mul_f32 v[38:39], v[14:15], v[4:5] op_sel_hi:[1,0]
	v_pk_mul_f32 v[40:41], v[16:17], v[4:5] op_sel_hi:[1,0]
	v_pk_mul_f32 v[42:43], v[18:19], v[4:5] op_sel_hi:[1,0]
	v_pk_mul_f32 v[44:45], v[20:21], v[4:5] op_sel_hi:[1,0]
	v_pk_mul_f32 v[46:47], v[22:23], v[4:5] op_sel_hi:[1,0]
	v_pk_mul_f32 v[48:49], v[24:25], v[4:5] op_sel_hi:[1,0]
	v_pk_mul_f32 v[34:35], v[34:35], v[154:155]
	v_pk_mul_f32 v[36:37], v[36:37], v[156:157]
	v_pk_mul_f32 v[38:39], v[38:39], v[158:159]
	v_pk_mul_f32 v[40:41], v[40:41], v[160:161]
	v_pk_mul_f32 v[42:43], v[42:43], v[162:163]
	v_pk_mul_f32 v[44:45], v[44:45], v[164:165]
	v_pk_mul_f32 v[46:47], v[46:47], v[166:167]
	v_pk_mul_f32 v[48:49], v[48:49], v[168:169]
	v_pk_fma_f32 v[58:59], v[176:177], v[34:35], v[58:59]
	v_pk_fma_f32 v[60:61], v[178:179], v[36:37], v[60:61]
	v_pk_fma_f32 v[62:63], v[180:181], v[38:39], v[62:63]
	v_pk_fma_f32 v[64:65], v[182:183], v[40:41], v[64:65]
	v_pk_fma_f32 v[66:67], v[184:185], v[42:43], v[66:67]
	v_pk_fma_f32 v[68:69], v[186:187], v[44:45], v[68:69]
	v_pk_fma_f32 v[70:71], v[188:189], v[46:47], v[70:71]
	v_pk_fma_f32 v[72:73], v[190:191], v[48:49], v[72:73]
	global_store_dwordx4 v0, v[58:61], s[14:15] offset:0 nt
	global_store_dwordx4 v0, v[62:65], s[14:15] offset:1024 nt
	global_store_dwordx4 v0, v[66:69], s[14:15] offset:2048 nt
	global_store_dwordx4 v0, v[70:73], s[14:15] offset:3072 nt
	s_add_u32 s14, s14, 0x1000
	s_addc_u32 s15, s15, 0
	v_mul_f32_e32 v6, v58, v58
	v_mul_f32_e32 v7, v59, v59
	v_fmac_f32_e32 v6, v60, v60
	v_fmac_f32_e32 v7, v61, v61
	v_fmac_f32_e32 v6, v62, v62
	v_fmac_f32_e32 v7, v63, v63
	v_fmac_f32_e32 v6, v64, v64
	v_fmac_f32_e32 v7, v65, v65
	v_fmac_f32_e32 v6, v66, v66
	v_fmac_f32_e32 v7, v67, v67
	v_fmac_f32_e32 v6, v68, v68
	v_fmac_f32_e32 v7, v69, v69
	v_fmac_f32_e32 v6, v70, v70
	v_fmac_f32_e32 v7, v71, v71
	v_fmac_f32_e32 v6, v72, v72
	v_fmac_f32_e32 v7, v73, v73
	v_add_f32_e32 v6, v6, v7
	s_nop 1
	v_add_f32_dpp v8, v6, v6 quad_perm:[1,0,3,2] row_mask:0xf bank_mask:0xf
	s_nop 1
	v_add_f32_dpp v8, v8, v8 quad_perm:[2,3,0,1] row_mask:0xf bank_mask:0xf
	s_nop 1
	v_add_f32_dpp v8, v8, v8 row_half_mirror row_mask:0xf bank_mask:0xf
	s_nop 1
	v_add_f32_dpp v8, v8, v8 row_mirror row_mask:0xf bank_mask:0xf
	s_nop 1
	v_add_f32_dpp v8, v8, v8 row_bcast:15 row_mask:0xa bank_mask:0xf
	s_nop 1
	v_add_f32_dpp v8, v8, v8 row_bcast:31 row_mask:0xc bank_mask:0xf
	s_nop 1
	v_readlane_b32 s84, v8, 63
	s_nop 1
	v_fma_f32 v4, s84, v2, v3
	v_rsq_f32_e32 v4, v4
	s_nop 0
	v_pk_mul_f32 v[34:35], v[58:59], v[4:5] op_sel_hi:[1,0]
	v_pk_mul_f32 v[36:37], v[60:61], v[4:5] op_sel_hi:[1,0]
	v_pk_mul_f32 v[38:39], v[62:63], v[4:5] op_sel_hi:[1,0]
	v_pk_mul_f32 v[40:41], v[64:65], v[4:5] op_sel_hi:[1,0]
	v_pk_mul_f32 v[42:43], v[66:67], v[4:5] op_sel_hi:[1,0]
	v_pk_mul_f32 v[44:45], v[68:69], v[4:5] op_sel_hi:[1,0]
	v_pk_mul_f32 v[46:47], v[70:71], v[4:5] op_sel_hi:[1,0]
	v_pk_mul_f32 v[48:49], v[72:73], v[4:5] op_sel_hi:[1,0]
	v_pk_mul_f32 v[34:35], v[34:35], v[192:193]
	v_pk_mul_f32 v[36:37], v[36:37], v[194:195]
	v_pk_mul_f32 v[38:39], v[38:39], v[196:197]
	v_pk_mul_f32 v[40:41], v[40:41], v[198:199]
	v_pk_mul_f32 v[42:43], v[42:43], v[200:201]
	v_pk_mul_f32 v[44:45], v[44:45], v[202:203]
	v_pk_mul_f32 v[46:47], v[46:47], v[204:205]
	v_pk_mul_f32 v[48:49], v[48:49], v[206:207]
	v_pk_fma_f32 v[34:35], v[34:35], v[208:209], v[228:229]
	v_pk_fma_f32 v[36:37], v[36:37], v[210:211], v[230:231]
; __device__ __forceinline__ unsigned cvt_pk_bf16(float lo, float hi) { unsigned r; asm volatile("v_cvt_pk_bf16_f32 %0, %1, %2" : "=v"(r) : "v"(lo), "v"(hi)); return r; }
; __device__ __forceinline__ float bflo(unsigned w) { return __uint_as_float(w << 16); }
; __device__ __forceinline__ float bfhi(unsigned w) { return __uint_as_float(w & 0xffff0000u); }
; template <bool BR, bool WH> ...
;     ...
;         if (BR) {
;             f32x4 m[4]; float s = 0.f;
; #pragma unroll
;             for (int j = 0; j < 4; ++j) { m[j] = (f32x4){bflo(bc[j].x), bfhi(bc[j].x), bflo(bc[j].y), bfhi(bc[j].y)};
;                 s += (m[j][0] * m[j][0] + m[j][1] * m[j][1]) + (m[j][2] * m[j][2] + m[j][3] * m[j][3]); }
;             const float rs = rsqrtf(wave_sum(s, lane) * (1.f / 1024.f) + EPS);
;             float* xo = row < ML ? xout_lat + (size_t)row * 1024 : xout_ctx + (size_t)(row - ML) * 1024;
; #pragma unroll
;             for (int j = 0; j < 4; ++j) { const f32x4 gp = *(const f32x4*)(g_post + 4 * lane + 256 * j), ga = *(const f32x4*)(mod_g + (size_t)mrow * 6144 + gate_off + 4 * lane + 256 * j);
;                 x[j] = x[j] + ga * ((m[j] * rs) * gp); __builtin_nontemporal_store(x[j], (f32x4*)(xo + 4 * lane + 256 * j)); }
;     ...
;             const float rs = rsqrtf(wave_sum(s, lane) * (1.f / 1024.f) + EPS);
; #pragma unroll
;             for (int j = 0; j < 4; ++j) { const f32x4 gp = *(const f32x4*)(g_pre + 4 * lane + 256 * j), sc = *(const f32x4*)(mod_h + (size_t)mrow * 6144 + sc_off + 4 * lane + 256 * j),
;                     sh = *(const f32x4*)(mod_h + (size_t)mrow * 6144 + sh_off + 4 * lane + 256 * j);
;                 const f32x4 hv = ((x[j] * rs) * gp) * (sc + 1.0f) + sh;
;                 u32x2 w; w.x = cvt_pk_bf16(hv[0], hv[1]); w.y = cvt_pk_bf16(hv[2], hv[3]);
;                 *(u32x2*)(Hout + (size_t)row * 1024 + 4 * lane + 256 * j) = w; }
;         }
	v_pk_fma_f32 v[38:39], v[38:39], v[212:213], v[232:233]
	v_pk_fma_f32 v[40:41], v[40:41], v[214:215], v[234:235]
	v_pk_fma_f32 v[42:43], v[42:43], v[220:221], v[236:237]
	v_pk_fma_f32 v[44:45], v[44:45], v[222:223], v[238:239]
	v_pk_fma_f32 v[46:47], v[46:47], v[224:225], v[26:27]
	v_pk_fma_f32 v[48:49], v[48:49], v[226:227], v[28:29]
	v_cvt_pk_bf16_f32 v50, v34, v35
	v_cvt_pk_bf16_f32 v51, v36, v37
	v_cvt_pk_bf16_f32 v52, v38, v39
	v_cvt_pk_bf16_f32 v53, v40, v41
	v_cvt_pk_bf16_f32 v54, v42, v43
	v_cvt_pk_bf16_f32 v55, v44, v45
	v_cvt_pk_bf16_f32 v56, v46, v47
	v_cvt_pk_bf16_f32 v57, v48, v49
	global_store_dwordx2 v1, v[50:51], s[16:17] offset:0
	global_store_dwordx2 v1, v[52:53], s[16:17] offset:512
	global_store_dwordx2 v1, v[54:55], s[16:17] offset:1024
	global_store_dwordx2 v1, v[56:57], s[16:17] offset:1536
	s_add_u32 s16, s16, 0x800
	s_addc_u32 s17, s17, 0
	global_load_dwordx4 v[58:61], v0, s[4:5] offset:0 nt
	global_load_dwordx4 v[62:65], v0, s[4:5] offset:1024 nt
	global_load_dwordx4 v[66:69], v0, s[4:5] offset:2048 nt
	global_load_dwordx4 v[70:73], v0, s[4:5] offset:3072 nt
	global_load_dwordx2 v[122:123], v1, s[12:13] offset:0 nt
	global_load_dwordx2 v[124:125], v1, s[12:13] offset:512 nt
	global_load_dwordx2 v[126:127], v1, s[12:13] offset:1024 nt
	global_load_dwordx2 v[128:129], v1, s[12:13] offset:1536 nt
	s_add_u32 s4, s4, 0x1000
	s_addc_u32 s5, s5, 0
	s_add_u32 s12, s12, 0x800
	s_addc_u32 s13, s13, 0
	s_waitcnt vmcnt(32)
	v_lshlrev_b32_e32 v10, 16, v130
	v_and_b32_e32 v11, 0xffff0000, v130
	v_lshlrev_b32_e32 v12, 16, v131
	v_and_b32_e32 v13, 0xffff0000, v131
	v_lshlrev_b32_e32 v14, 16, v132
	v_and_b32_e32 v15, 0xffff0000, v132
	v_lshlrev_b32_e32 v16, 16, v133
	v_and_b32_e32 v17, 0xffff0000, v133
	v_lshlrev_b32_e32 v18, 16, v134
	v_and_b32_e32 v19, 0xffff0000, v134
	v_lshlrev_b32_e32 v20, 16, v135
	v_and_b32_e32 v21, 0xffff0000, v135
	v_lshlrev_b32_e32 v22, 16, v136
	v_and_b32_e32 v23, 0xffff0000, v136
	v_lshlrev_b32_e32 v24, 16, v137
	v_and_b32_e32 v25, 0xffff0000, v137
	v_mul_f32_e32 v6, v10, v10
	v_mul_f32_e32 v7, v11, v11
	v_fmac_f32_e32 v6, v12, v12
	v_fmac_f32_e32 v7, v13, v13
	v_fmac_f32_e32 v6, v14, v14
	v_fmac_f32_e32 v7, v15, v15
	v_fmac_f32_e32 v6, v16, v16
	v_fmac_f32_e32 v7, v17, v17
	v_fmac_f32_e32 v6, v18, v18
	v_fmac_f32_e32 v7, v19, v19
	v_fmac_f32_e32 v6, v20, v20
	v_fmac_f32_e32 v7, v21, v21
	v_fmac_f32_e32 v6, v22, v22
	v_fmac_f32_e32 v7, v23, v23
	v_fmac_f32_e32 v6, v24, v24
	v_fmac_f32_e32 v7, v25, v25
	v_add_f32_e32 v6, v6, v7
	s_nop 1
	v_add_f32_dpp v8, v6, v6 quad_perm:[1,0,3,2] row_mask:0xf bank_mask:0xf
	s_nop 1
	v_add_f32_dpp v8, v8, v8 quad_perm:[2,3,0,1] row_mask:0xf bank_mask:0xf
	s_nop 1
	v_add_f32_dpp v8, v8, v8 row_half_mirror row_mask:0xf bank_mask:0xf
	s_nop 1
	v_add_f32_dpp v8, v8, v8 row_mirror row_mask:0xf bank_mask:0xf
	s_nop 1
	v_add_f32_dpp v8, v8, v8 row_bcast:15 row_mask:0xa bank_mask:0xf
	s_nop 1
	v_add_f32_dpp v8, v8, v8 row_bcast:31 row_mask:0xc bank_mask:0xf
	s_nop 1
	v_readlane_b32 s84, v8, 63
	s_nop 1
	v_fma_f32 v4, s84, v2, v3
	v_rsq_f32_e32 v4, v4
	s_nop 0
	v_pk_mul_f32 v[34:35], v[10:11], v[4:5] op_sel_hi:[1,0]
	v_pk_mul_f32 v[36:37], v[12:13], v[4:5] op_sel_hi:[1,0]
	v_pk_mul_f32 v[38:39], v[14:15], v[4:5] op_sel_hi:[1,0]
	v_pk_mul_f32 v[40:41], v[16:17], v[4:5] op_sel_hi:[1,0]
	v_pk_mul_f32 v[42:43], v[18:19], v[4:5] op_sel_hi:[1,0]
	v_pk_mul_f32 v[44:45], v[20:21], v[4:5] op_sel_hi:[1,0]
	v_pk_mul_f32 v[46:47], v[22:23], v[4:5] op_sel_hi:[1,0]
	v_pk_mul_f32 v[48:49], v[24:25], v[4:5] op_sel_hi:[1,0]
	v_pk_mul_f32 v[34:35], v[34:35], v[154:155]
	v_pk_mul_f32 v[36:37], v[36:37], v[156:157]
	v_pk_mul_f32 v[38:39], v[38:39], v[158:159]
	v_pk_mul_f32 v[40:41], v[40:41], v[160:161]
	v_pk_mul_f32 v[42:43], v[42:43], v[162:163]
	v_pk_mul_f32 v[44:45], v[44:45], v[164:165]
	v_pk_mul_f32 v[46:47], v[46:47], v[166:167]
	v_pk_mul_f32 v[48:49], v[48:49], v[168:169]
	v_pk_fma_f32 v[74:75], v[176:177], v[34:35], v[74:75]
	v_pk_fma_f32 v[76:77], v[178:179], v[36:37], v[76:77]
	v_pk_fma_f32 v[78:79], v[180:181], v[38:39], v[78:79]
	v_pk_fma_f32 v[80:81], v[182:183], v[40:41], v[80:81]
	v_pk_fma_f32 v[82:83], v[184:185], v[42:43], v[82:83]
	v_pk_fma_f32 v[84:85], v[186:187], v[44:45], v[84:85]
	v_pk_fma_f32 v[86:87], v[188:189], v[46:47], v[86:87]
	v_pk_fma_f32 v[88:89], v[190:191], v[48:49], v[88:89]
	global_store_dwordx4 v0, v[74:77], s[14:15] offset:0 nt
	global_store_dwordx4 v0, v[78:81], s[14:15] offset:1024 nt
	global_store_dwordx4 v0, v[82:85], s[14:15] offset:2048 nt
	global_store_dwordx4 v0, v[86:89], s[14:15] offset:3072 nt
	s_add_u32 s14, s14, 0x1000
	s_addc_u32 s15, s15, 0
	v_mul_f32_e32 v6, v74, v74
	v_mul_f32_e32 v7, v75, v75
	v_fmac_f32_e32 v6, v76, v76
	v_fmac_f32_e32 v7, v77, v77
	v_fmac_f32_e32 v6, v78, v78
	v_fmac_f32_e32 v7, v79, v79
	v_fmac_f32_e32 v6, v80, v80
	v_fmac_f32_e32 v7, v81, v81
	v_fmac_f32_e32 v6, v82, v82
	v_fmac_f32_e32 v7, v83, v83
	v_fmac_f32_e32 v6, v84, v84
	v_fmac_f32_e32 v7, v85, v85
	v_fmac_f32_e32 v6, v86, v86
	v_fmac_f32_e32 v7, v87, v87
	v_fmac_f32_e32 v6, v88, v88
	v_fmac_f32_e32 v7, v89, v89
	v_add_f32_e32 v6, v6, v7
	s_nop 1
	v_add_f32_dpp v8, v6, v6 quad_perm:[1,0,3,2] row_mask:0xf bank_mask:0xf
	s_nop 1
	v_add_f32_dpp v8, v8, v8 quad_perm:[2,3,0,1] row_mask:0xf bank_mask:0xf
	s_nop 1
	v_add_f32_dpp v8, v8, v8 row_half_mirror row_mask:0xf bank_mask:0xf
	s_nop 1
	v_add_f32_dpp v8, v8, v8 row_mirror row_mask:0xf bank_mask:0xf
	s_nop 1
	v_add_f32_dpp v8, v8, v8 row_bcast:15 row_mask:0xa bank_mask:0xf
	s_nop 1
	v_add_f32_dpp v8, v8, v8 row_bcast:31 row_mask:0xc bank_mask:0xf
	s_nop 1
	v_readlane_b32 s84, v8, 63
	s_nop 1
	v_fma_f32 v4, s84, v2, v3
; __device__ __forceinline__ unsigned cvt_pk_bf16(float lo, float hi) { unsigned r; asm volatile("v_cvt_pk_bf16_f32 %0, %1, %2" : "=v"(r) : "v"(lo), "v"(hi)); return r; }
; __device__ __forceinline__ float bflo(unsigned w) { return __uint_as_float(w << 16); }
; __device__ __forceinline__ float bfhi(unsigned w) { return __uint_as_float(w & 0xffff0000u); }
; template <bool BR, bool WH> ...
;     ...
;         if (BR) {
;             f32x4 m[4]; float s = 0.f;
; #pragma unroll
;             for (int j = 0; j < 4; ++j) { m[j] = (f32x4){bflo(bc[j].x), bfhi(bc[j].x), bflo(bc[j].y), bfhi(bc[j].y)};
;                 s += (m[j][0] * m[j][0] + m[j][1] * m[j][1]) + (m[j][2] * m[j][2] + m[j][3] * m[j][3]); }
;             const float rs = rsqrtf(wave_sum(s, lane) * (1.f / 1024.f) + EPS);
;             float* xo = row < ML ? xout_lat + (size_t)row * 1024 : xout_ctx + (size_t)(row - ML) * 1024;
; #pragma unroll
;             for (int j = 0; j < 4; ++j) { const f32x4 gp = *(const f32x4*)(g_post + 4 * lane + 256 * j), ga = *(const f32x4*)(mod_g + (size_t)mrow * 6144 + gate_off + 4 * lane + 256 * j);
;                 x[j] = x[j] + ga * ((m[j] * rs) * gp); __builtin_nontemporal_store(x[j], (f32x4*)(xo + 4 * lane + 256 * j)); }
;         }
;         if (WH) {
;             float s = 0.f;
; #pragma unroll
;             for (int j = 0; j < 4; ++j) s += (x[j][0] * x[j][0] + x[j][1] * x[j][1]) + (x[j][2] * x[j][2] + x[j][3] * x[j][3]);
;             const float rs = rsqrtf(wave_sum(s, lane) * (1.f / 1024.f) + EPS);
; #pragma unroll
;             for (int j = 0; j < 4; ++j) { const f32x4 gp = *(const f32x4*)(g_pre + 4 * lane + 256 * j), sc = *(const f32x4*)(mod_h + (size_t)mrow * 6144 + sc_off + 4 * lane + 256 * j),
;                     sh = *(const f32x4*)(mod_h + (size_t)mrow * 6144 + sh_off + 4 * lane + 256 * j);
;                 const f32x4 hv = ((x[j] * rs) * gp) * (sc + 1.0f) + sh;
;                 u32x2 w; w.x = cvt_pk_bf16(hv[0], hv[1]); w.y = cvt_pk_bf16(hv[2], hv[3]);
;                 *(u32x2*)(Hout + (size_t)row * 1024 + 4 * lane + 256 * j) = w; }
;         }
	v_rsq_f32_e32 v4, v4
	s_nop 0
	v_pk_mul_f32 v[34:35], v[74:75], v[4:5] op_sel_hi:[1,0]
	v_pk_mul_f32 v[36:37], v[76:77], v[4:5] op_sel_hi:[1,0]
	v_pk_mul_f32 v[38:39], v[78:79], v[4:5] op_sel_hi:[1,0]
	v_pk_mul_f32 v[40:41], v[80:81], v[4:5] op_sel_hi:[1,0]
	v_pk_mul_f32 v[42:43], v[82:83], v[4:5] op_sel_hi:[1,0]
	v_pk_mul_f32 v[44:45], v[84:85], v[4:5] op_sel_hi:[1,0]
	v_pk_mul_f32 v[46:47], v[86:87], v[4:5] op_sel_hi:[1,0]
	v_pk_mul_f32 v[48:49], v[88:89], v[4:5] op_sel_hi:[1,0]
	v_pk_mul_f32 v[34:35], v[34:35], v[192:193]
	v_pk_mul_f32 v[36:37], v[36:37], v[194:195]
	v_pk_mul_f32 v[38:39], v[38:39], v[196:197]
	v_pk_mul_f32 v[40:41], v[40:41], v[198:199]
	v_pk_mul_f32 v[42:43], v[42:43], v[200:201]
	v_pk_mul_f32 v[44:45], v[44:45], v[202:203]
	v_pk_mul_f32 v[46:47], v[46:47], v[204:205]
	v_pk_mul_f32 v[48:49], v[48:49], v[206:207]
	v_pk_fma_f32 v[34:35], v[34:35], v[208:209], v[228:229]
	v_pk_fma_f32 v[36:37], v[36:37], v[210:211], v[230:231]
	v_pk_fma_f32 v[38:39], v[38:39], v[212:213], v[232:233]
	v_pk_fma_f32 v[40:41], v[40:41], v[214:215], v[234:235]
	v_pk_fma_f32 v[42:43], v[42:43], v[220:221], v[236:237]
	v_pk_fma_f32 v[44:45], v[44:45], v[222:223], v[238:239]
	v_pk_fma_f32 v[46:47], v[46:47], v[224:225], v[26:27]
	v_pk_fma_f32 v[48:49], v[48:49], v[226:227], v[28:29]
	v_cvt_pk_bf16_f32 v50, v34, v35
	v_cvt_pk_bf16_f32 v51, v36, v37
	v_cvt_pk_bf16_f32 v52, v38, v39
	v_cvt_pk_bf16_f32 v53, v40, v41
	v_cvt_pk_bf16_f32 v54, v42, v43
	v_cvt_pk_bf16_f32 v55, v44, v45
	v_cvt_pk_bf16_f32 v56, v46, v47
	v_cvt_pk_bf16_f32 v57, v48, v49
	global_store_dwordx2 v1, v[50:51], s[16:17] offset:0
	global_store_dwordx2 v1, v[52:53], s[16:17] offset:512
	global_store_dwordx2 v1, v[54:55], s[16:17] offset:1024
	global_store_dwordx2 v1, v[56:57], s[16:17] offset:1536
	s_add_u32 s16, s16, 0x800
	s_addc_u32 s17, s17, 0
	global_load_dwordx4 v[74:77], v0, s[4:5] offset:0 nt
	global_load_dwordx4 v[78:81], v0, s[4:5] offset:1024 nt
	global_load_dwordx4 v[82:85], v0, s[4:5] offset:2048 nt
	global_load_dwordx4 v[86:89], v0, s[4:5] offset:3072 nt
	global_load_dwordx2 v[130:131], v1, s[12:13] offset:0 nt
	global_load_dwordx2 v[132:133], v1, s[12:13] offset:512 nt
	global_load_dwordx2 v[134:135], v1, s[12:13] offset:1024 nt
	global_load_dwordx2 v[136:137], v1, s[12:13] offset:1536 nt
	s_add_u32 s4, s4, 0x1000
	s_addc_u32 s5, s5, 0
	s_add_u32 s12, s12, 0x800
	s_addc_u32 s13, s13, 0
	s_waitcnt vmcnt(40)
	v_lshlrev_b32_e32 v10, 16, v138
	v_and_b32_e32 v11, 0xffff0000, v138
	v_lshlrev_b32_e32 v12, 16, v139
	v_and_b32_e32 v13, 0xffff0000, v139
	v_lshlrev_b32_e32 v14, 16, v140
	v_and_b32_e32 v15, 0xffff0000, v140
	v_lshlrev_b32_e32 v16, 16, v141
	v_and_b32_e32 v17, 0xffff0000, v141
	v_lshlrev_b32_e32 v18, 16, v142
	v_and_b32_e32 v19, 0xffff0000, v142
	v_lshlrev_b32_e32 v20, 16, v143
	v_and_b32_e32 v21, 0xffff0000, v143
	v_lshlrev_b32_e32 v22, 16, v144
	v_and_b32_e32 v23, 0xffff0000, v144
	v_lshlrev_b32_e32 v24, 16, v145
	v_and_b32_e32 v25, 0xffff0000, v145
	v_mul_f32_e32 v6, v10, v10
	v_mul_f32_e32 v7, v11, v11
	v_fmac_f32_e32 v6, v12, v12
	v_fmac_f32_e32 v7, v13, v13
	v_fmac_f32_e32 v6, v14, v14
	v_fmac_f32_e32 v7, v15, v15
	v_fmac_f32_e32 v6, v16, v16
	v_fmac_f32_e32 v7, v17, v17
	v_fmac_f32_e32 v6, v18, v18
	v_fmac_f32_e32 v7, v19, v19
	v_fmac_f32_e32 v6, v20, v20
	v_fmac_f32_e32 v7, v21, v21
	v_fmac_f32_e32 v6, v22, v22
	v_fmac_f32_e32 v7, v23, v23
	v_fmac_f32_e32 v6, v24, v24
	v_fmac_f32_e32 v7, v25, v25
	v_add_f32_e32 v6, v6, v7
	s_nop 1
	v_add_f32_dpp v8, v6, v6 quad_perm:[1,0,3,2] row_mask:0xf bank_mask:0xf
	s_nop 1
	v_add_f32_dpp v8, v8, v8 quad_perm:[2,3,0,1] row_mask:0xf bank_mask:0xf
	s_nop 1
	v_add_f32_dpp v8, v8, v8 row_half_mirror row_mask:0xf bank_mask:0xf
	s_nop 1
	v_add_f32_dpp v8, v8, v8 row_mirror row_mask:0xf bank_mask:0xf
	s_nop 1
	v_add_f32_dpp v8, v8, v8 row_bcast:15 row_mask:0xa bank_mask:0xf
	s_nop 1
	v_add_f32_dpp v8, v8, v8 row_bcast:31 row_mask:0xc bank_mask:0xf
	s_nop 1
	v_readlane_b32 s84, v8, 63
	s_nop 1
	v_fma_f32 v4, s84, v2, v3
	v_rsq_f32_e32 v4, v4
	s_nop 0
	v_pk_mul_f32 v[34:35], v[10:11], v[4:5] op_sel_hi:[1,0]
	v_pk_mul_f32 v[36:37], v[12:13], v[4:5] op_sel_hi:[1,0]
	v_pk_mul_f32 v[38:39], v[14:15], v[4:5] op_sel_hi:[1,0]
	v_pk_mul_f32 v[40:41], v[16:17], v[4:5] op_sel_hi:[1,0]
	v_pk_mul_f32 v[42:43], v[18:19], v[4:5] op_sel_hi:[1,0]
	v_pk_mul_f32 v[44:45], v[20:21], v[4:5] op_sel_hi:[1,0]
	v_pk_mul_f32 v[46:47], v[22:23], v[4:5] op_sel_hi:[1,0]
	v_pk_mul_f32 v[48:49], v[24:25], v[4:5] op_sel_hi:[1,0]
	v_pk_mul_f32 v[34:35], v[34:35], v[154:155]
	v_pk_mul_f32 v[36:37], v[36:37], v[156:157]
	v_pk_mul_f32 v[38:39], v[38:39], v[158:159]
	v_pk_mul_f32 v[40:41], v[40:41], v[160:161]
	v_pk_mul_f32 v[42:43], v[42:43], v[162:163]
	v_pk_mul_f32 v[44:45], v[44:45], v[164:165]
	v_pk_mul_f32 v[46:47], v[46:47], v[166:167]
	v_pk_mul_f32 v[48:49], v[48:49], v[168:169]
	v_pk_fma_f32 v[90:91], v[176:177], v[34:35], v[90:91]
	v_pk_fma_f32 v[92:93], v[178:179], v[36:37], v[92:93]
	v_pk_fma_f32 v[94:95], v[180:181], v[38:39], v[94:95]
	v_pk_fma_f32 v[96:97], v[182:183], v[40:41], v[96:97]
	v_pk_fma_f32 v[98:99], v[184:185], v[42:43], v[98:99]
	v_pk_fma_f32 v[100:101], v[186:187], v[44:45], v[100:101]
	v_pk_fma_f32 v[102:103], v[188:189], v[46:47], v[102:103]
	v_pk_fma_f32 v[104:105], v[190:191], v[48:49], v[104:105]
	global_store_dwordx4 v0, v[90:93], s[14:15] offset:0 nt
	global_store_dwordx4 v0, v[94:97], s[14:15] offset:1024 nt
	global_store_dwordx4 v0, v[98:101], s[14:15] offset:2048 nt
	global_store_dwordx4 v0, v[102:105], s[14:15] offset:3072 nt
	s_add_u32 s14, s14, 0x1000
	s_addc_u32 s15, s15, 0
	v_mul_f32_e32 v6, v90, v90
; __device__ __forceinline__ unsigned cvt_pk_bf16(float lo, float hi) { unsigned r; asm volatile("v_cvt_pk_bf16_f32 %0, %1, %2" : "=v"(r) : "v"(lo), "v"(hi)); return r; }
; __device__ __forceinline__ float bflo(unsigned w) { return __uint_as_float(w << 16); }
; __device__ __forceinline__ float bfhi(unsigned w) { return __uint_as_float(w & 0xffff0000u); }
; template <bool BR, bool WH> ...
;     ...
;         if (BR) {
;             f32x4 m[4]; float s = 0.f;
; #pragma unroll
;             for (int j = 0; j < 4; ++j) { m[j] = (f32x4){bflo(bc[j].x), bfhi(bc[j].x), bflo(bc[j].y), bfhi(bc[j].y)};
;                 s += (m[j][0] * m[j][0] + m[j][1] * m[j][1]) + (m[j][2] * m[j][2] + m[j][3] * m[j][3]); }
;             const float rs = rsqrtf(wave_sum(s, lane) * (1.f / 1024.f) + EPS);
;             float* xo = row < ML ? xout_lat + (size_t)row * 1024 : xout_ctx + (size_t)(row - ML) * 1024;
; #pragma unroll
;             for (int j = 0; j < 4; ++j) { const f32x4 gp = *(const f32x4*)(g_post + 4 * lane + 256 * j), ga = *(const f32x4*)(mod_g + (size_t)mrow * 6144 + gate_off + 4 * lane + 256 * j);
;                 x[j] = x[j] + ga * ((m[j] * rs) * gp); __builtin_nontemporal_store(x[j], (f32x4*)(xo + 4 * lane + 256 * j)); }
;         }
;         if (WH) {
;             float s = 0.f;
; #pragma unroll
;             for (int j = 0; j < 4; ++j) s += (x[j][0] * x[j][0] + x[j][1] * x[j][1]) + (x[j][2] * x[j][2] + x[j][3] * x[j][3]);
;             const float rs = rsqrtf(wave_sum(s, lane) * (1.f / 1024.f) + EPS);
; #pragma unroll
;             for (int j = 0; j < 4; ++j) { const f32x4 gp = *(const f32x4*)(g_pre + 4 * lane + 256 * j), sc = *(const f32x4*)(mod_h + (size_t)mrow * 6144 + sc_off + 4 * lane + 256 * j),
;                     sh = *(const f32x4*)(mod_h + (size_t)mrow * 6144 + sh_off + 4 * lane + 256 * j);
;                 const f32x4 hv = ((x[j] * rs) * gp) * (sc + 1.0f) + sh;
;                 u32x2 w; w.x = cvt_pk_bf16(hv[0], hv[1]); w.y = cvt_pk_bf16(hv[2], hv[3]);
;                 *(u32x2*)(Hout + (size_t)row * 1024 + 4 * lane + 256 * j) = w; }
;         }
	v_mul_f32_e32 v7, v91, v91
	v_fmac_f32_e32 v6, v92, v92
	v_fmac_f32_e32 v7, v93, v93
	v_fmac_f32_e32 v6, v94, v94
	v_fmac_f32_e32 v7, v95, v95
	v_fmac_f32_e32 v6, v96, v96
	v_fmac_f32_e32 v7, v97, v97
	v_fmac_f32_e32 v6, v98, v98
	v_fmac_f32_e32 v7, v99, v99
	v_fmac_f32_e32 v6, v100, v100
	v_fmac_f32_e32 v7, v101, v101
	v_fmac_f32_e32 v6, v102, v102
	v_fmac_f32_e32 v7, v103, v103
	v_fmac_f32_e32 v6, v104, v104
	v_fmac_f32_e32 v7, v105, v105
	v_add_f32_e32 v6, v6, v7
	s_nop 1
	v_add_f32_dpp v8, v6, v6 quad_perm:[1,0,3,2] row_mask:0xf bank_mask:0xf
	s_nop 1
	v_add_f32_dpp v8, v8, v8 quad_perm:[2,3,0,1] row_mask:0xf bank_mask:0xf
	s_nop 1
	v_add_f32_dpp v8, v8, v8 row_half_mirror row_mask:0xf bank_mask:0xf
	s_nop 1
	v_add_f32_dpp v8, v8, v8 row_mirror row_mask:0xf bank_mask:0xf
	s_nop 1
	v_add_f32_dpp v8, v8, v8 row_bcast:15 row_mask:0xa bank_mask:0xf
	s_nop 1
	v_add_f32_dpp v8, v8, v8 row_bcast:31 row_mask:0xc bank_mask:0xf
	s_nop 1
	v_readlane_b32 s84, v8, 63
	s_nop 1
	v_fma_f32 v4, s84, v2, v3
	v_rsq_f32_e32 v4, v4
	s_nop 0
	v_pk_mul_f32 v[34:35], v[90:91], v[4:5] op_sel_hi:[1,0]
	v_pk_mul_f32 v[36:37], v[92:93], v[4:5] op_sel_hi:[1,0]
	v_pk_mul_f32 v[38:39], v[94:95], v[4:5] op_sel_hi:[1,0]
	v_pk_mul_f32 v[40:41], v[96:97], v[4:5] op_sel_hi:[1,0]
	v_pk_mul_f32 v[42:43], v[98:99], v[4:5] op_sel_hi:[1,0]
	v_pk_mul_f32 v[44:45], v[100:101], v[4:5] op_sel_hi:[1,0]
	v_pk_mul_f32 v[46:47], v[102:103], v[4:5] op_sel_hi:[1,0]
	v_pk_mul_f32 v[48:49], v[104:105], v[4:5] op_sel_hi:[1,0]
	v_pk_mul_f32 v[34:35], v[34:35], v[192:193]
	v_pk_mul_f32 v[36:37], v[36:37], v[194:195]
	v_pk_mul_f32 v[38:39], v[38:39], v[196:197]
	v_pk_mul_f32 v[40:41], v[40:41], v[198:199]
	v_pk_mul_f32 v[42:43], v[42:43], v[200:201]
	v_pk_mul_f32 v[44:45], v[44:45], v[202:203]
	v_pk_mul_f32 v[46:47], v[46:47], v[204:205]
	v_pk_mul_f32 v[48:49], v[48:49], v[206:207]
	v_pk_fma_f32 v[34:35], v[34:35], v[208:209], v[228:229]
	v_pk_fma_f32 v[36:37], v[36:37], v[210:211], v[230:231]
	v_pk_fma_f32 v[38:39], v[38:39], v[212:213], v[232:233]
	v_pk_fma_f32 v[40:41], v[40:41], v[214:215], v[234:235]
	v_pk_fma_f32 v[42:43], v[42:43], v[220:221], v[236:237]
	v_pk_fma_f32 v[44:45], v[44:45], v[222:223], v[238:239]
	v_pk_fma_f32 v[46:47], v[46:47], v[224:225], v[26:27]
	v_pk_fma_f32 v[48:49], v[48:49], v[226:227], v[28:29]
	v_cvt_pk_bf16_f32 v50, v34, v35
	v_cvt_pk_bf16_f32 v51, v36, v37
	v_cvt_pk_bf16_f32 v52, v38, v39
	v_cvt_pk_bf16_f32 v53, v40, v41
	v_cvt_pk_bf16_f32 v54, v42, v43
	v_cvt_pk_bf16_f32 v55, v44, v45
	v_cvt_pk_bf16_f32 v56, v46, v47
	v_cvt_pk_bf16_f32 v57, v48, v49
	global_store_dwordx2 v1, v[50:51], s[16:17] offset:0
	global_store_dwordx2 v1, v[52:53], s[16:17] offset:512
	global_store_dwordx2 v1, v[54:55], s[16:17] offset:1024
	global_store_dwordx2 v1, v[56:57], s[16:17] offset:1536
	s_add_u32 s16, s16, 0x800
	s_addc_u32 s17, s17, 0
	global_load_dwordx4 v[90:93], v0, s[4:5] offset:0 nt
	global_load_dwordx4 v[94:97], v0, s[4:5] offset:1024 nt
	global_load_dwordx4 v[98:101], v0, s[4:5] offset:2048 nt
	global_load_dwordx4 v[102:105], v0, s[4:5] offset:3072 nt
	global_load_dwordx2 v[138:139], v1, s[12:13] offset:0 nt
	global_load_dwordx2 v[140:141], v1, s[12:13] offset:512 nt
	global_load_dwordx2 v[142:143], v1, s[12:13] offset:1024 nt
	global_load_dwordx2 v[144:145], v1, s[12:13] offset:1536 nt
	s_add_u32 s4, s4, 0x1000
	s_addc_u32 s5, s5, 0
	s_add_u32 s12, s12, 0x800
	s_addc_u32 s13, s13, 0
	s_waitcnt vmcnt(48)
	v_lshlrev_b32_e32 v10, 16, v146
	v_and_b32_e32 v11, 0xffff0000, v146
	v_lshlrev_b32_e32 v12, 16, v147
	v_and_b32_e32 v13, 0xffff0000, v147
	v_lshlrev_b32_e32 v14, 16, v148
	v_and_b32_e32 v15, 0xffff0000, v148
	v_lshlrev_b32_e32 v16, 16, v149
	v_and_b32_e32 v17, 0xffff0000, v149
	v_lshlrev_b32_e32 v18, 16, v150
	v_and_b32_e32 v19, 0xffff0000, v150
	v_lshlrev_b32_e32 v20, 16, v151
	v_and_b32_e32 v21, 0xffff0000, v151
	v_lshlrev_b32_e32 v22, 16, v152
	v_and_b32_e32 v23, 0xffff0000, v152
	v_lshlrev_b32_e32 v24, 16, v153
	v_and_b32_e32 v25, 0xffff0000, v153
	v_mul_f32_e32 v6, v10, v10
	v_mul_f32_e32 v7, v11, v11
	v_fmac_f32_e32 v6, v12, v12
	v_fmac_f32_e32 v7, v13, v13
	v_fmac_f32_e32 v6, v14, v14
	v_fmac_f32_e32 v7, v15, v15
	v_fmac_f32_e32 v6, v16, v16
	v_fmac_f32_e32 v7, v17, v17
	v_fmac_f32_e32 v6, v18, v18
	v_fmac_f32_e32 v7, v19, v19
	v_fmac_f32_e32 v6, v20, v20
	v_fmac_f32_e32 v7, v21, v21
	v_fmac_f32_e32 v6, v22, v22
	v_fmac_f32_e32 v7, v23, v23
	v_fmac_f32_e32 v6, v24, v24
	v_fmac_f32_e32 v7, v25, v25
	v_add_f32_e32 v6, v6, v7
	s_nop 1
	v_add_f32_dpp v8, v6, v6 quad_perm:[1,0,3,2] row_mask:0xf bank_mask:0xf
	s_nop 1
	v_add_f32_dpp v8, v8, v8 quad_perm:[2,3,0,1] row_mask:0xf bank_mask:0xf
	s_nop 1
	v_add_f32_dpp v8, v8, v8 row_half_mirror row_mask:0xf bank_mask:0xf
	s_nop 1
	v_add_f32_dpp v8, v8, v8 row_mirror row_mask:0xf bank_mask:0xf
	s_nop 1
	v_add_f32_dpp v8, v8, v8 row_bcast:15 row_mask:0xa bank_mask:0xf
	s_nop 1
	v_add_f32_dpp v8, v8, v8 row_bcast:31 row_mask:0xc bank_mask:0xf
	s_nop 1
	v_readlane_b32 s84, v8, 63
	s_nop 1
	v_fma_f32 v4, s84, v2, v3
	v_rsq_f32_e32 v4, v4
	s_nop 0
	v_pk_mul_f32 v[34:35], v[10:11], v[4:5] op_sel_hi:[1,0]
	v_pk_mul_f32 v[36:37], v[12:13], v[4:5] op_sel_hi:[1,0]
	v_pk_mul_f32 v[38:39], v[14:15], v[4:5] op_sel_hi:[1,0]
	v_pk_mul_f32 v[40:41], v[16:17], v[4:5] op_sel_hi:[1,0]
	v_pk_mul_f32 v[42:43], v[18:19], v[4:5] op_sel_hi:[1,0]
	v_pk_mul_f32 v[44:45], v[20:21], v[4:5] op_sel_hi:[1,0]
	v_pk_mul_f32 v[46:47], v[22:23], v[4:5] op_sel_hi:[1,0]
	v_pk_mul_f32 v[48:49], v[24:25], v[4:5] op_sel_hi:[1,0]
	v_pk_mul_f32 v[34:35], v[34:35], v[154:155]
	v_pk_mul_f32 v[36:37], v[36:37], v[156:157]
	v_pk_mul_f32 v[38:39], v[38:39], v[158:159]
; __device__ __forceinline__ unsigned cvt_pk_bf16(float lo, float hi) { unsigned r; asm volatile("v_cvt_pk_bf16_f32 %0, %1, %2" : "=v"(r) : "v"(lo), "v"(hi)); return r; }
; __device__ __forceinline__ float bflo(unsigned w) { return __uint_as_float(w << 16); }
; __device__ __forceinline__ float bfhi(unsigned w) { return __uint_as_float(w & 0xffff0000u); }
; template <bool BR, bool WH> ...
;     ...
;         if (BR) {
;             f32x4 m[4]; float s = 0.f;
; #pragma unroll
;             for (int j = 0; j < 4; ++j) { m[j] = (f32x4){bflo(bc[j].x), bfhi(bc[j].x), bflo(bc[j].y), bfhi(bc[j].y)};
;                 s += (m[j][0] * m[j][0] + m[j][1] * m[j][1]) + (m[j][2] * m[j][2] + m[j][3] * m[j][3]); }
;             const float rs = rsqrtf(wave_sum(s, lane) * (1.f / 1024.f) + EPS);
;             float* xo = row < ML ? xout_lat + (size_t)row * 1024 : xout_ctx + (size_t)(row - ML) * 1024;
; #pragma unroll
;             for (int j = 0; j < 4; ++j) { const f32x4 gp = *(const f32x4*)(g_post + 4 * lane + 256 * j), ga = *(const f32x4*)(mod_g + (size_t)mrow * 6144 + gate_off + 4 * lane + 256 * j);
;                 x[j] = x[j] + ga * ((m[j] * rs) * gp); __builtin_nontemporal_store(x[j], (f32x4*)(xo + 4 * lane + 256 * j)); }
;         }
;         if (WH) {
;             float s = 0.f;
; #pragma unroll
;             for (int j = 0; j < 4; ++j) s += (x[j][0] * x[j][0] + x[j][1] * x[j][1]) + (x[j][2] * x[j][2] + x[j][3] * x[j][3]);
;             const float rs = rsqrtf(wave_sum(s, lane) * (1.f / 1024.f) + EPS);
; #pragma unroll
;             for (int j = 0; j < 4; ++j) { const f32x4 gp = *(const f32x4*)(g_pre + 4 * lane + 256 * j), sc = *(const f32x4*)(mod_h + (size_t)mrow * 6144 + sc_off + 4 * lane + 256 * j),
;                     sh = *(const f32x4*)(mod_h + (size_t)mrow * 6144 + sh_off + 4 * lane + 256 * j);
;                 const f32x4 hv = ((x[j] * rs) * gp) * (sc + 1.0f) + sh;
;                 u32x2 w; w.x = cvt_pk_bf16(hv[0], hv[1]); w.y = cvt_pk_bf16(hv[2], hv[3]);
;                 *(u32x2*)(Hout + (size_t)row * 1024 + 4 * lane + 256 * j) = w; }
;         }
	v_pk_mul_f32 v[40:41], v[40:41], v[160:161]
	v_pk_mul_f32 v[42:43], v[42:43], v[162:163]
	v_pk_mul_f32 v[44:45], v[44:45], v[164:165]
	v_pk_mul_f32 v[46:47], v[46:47], v[166:167]
	v_pk_mul_f32 v[48:49], v[48:49], v[168:169]
	v_pk_fma_f32 v[106:107], v[176:177], v[34:35], v[106:107]
	v_pk_fma_f32 v[108:109], v[178:179], v[36:37], v[108:109]
	v_pk_fma_f32 v[110:111], v[180:181], v[38:39], v[110:111]
	v_pk_fma_f32 v[112:113], v[182:183], v[40:41], v[112:113]
	v_pk_fma_f32 v[114:115], v[184:185], v[42:43], v[114:115]
	v_pk_fma_f32 v[116:117], v[186:187], v[44:45], v[116:117]
	v_pk_fma_f32 v[118:119], v[188:189], v[46:47], v[118:119]
	v_pk_fma_f32 v[120:121], v[190:191], v[48:49], v[120:121]
	global_store_dwordx4 v0, v[106:109], s[14:15] offset:0 nt
	global_store_dwordx4 v0, v[110:113], s[14:15] offset:1024 nt
	global_store_dwordx4 v0, v[114:117], s[14:15] offset:2048 nt
	global_store_dwordx4 v0, v[118:121], s[14:15] offset:3072 nt
	s_add_u32 s14, s14, 0x1000
	s_addc_u32 s15, s15, 0
	v_mul_f32_e32 v6, v106, v106
	v_mul_f32_e32 v7, v107, v107
	v_fmac_f32_e32 v6, v108, v108
	v_fmac_f32_e32 v7, v109, v109
	v_fmac_f32_e32 v6, v110, v110
	v_fmac_f32_e32 v7, v111, v111
	v_fmac_f32_e32 v6, v112, v112
	v_fmac_f32_e32 v7, v113, v113
	v_fmac_f32_e32 v6, v114, v114
	v_fmac_f32_e32 v7, v115, v115
	v_fmac_f32_e32 v6, v116, v116
	v_fmac_f32_e32 v7, v117, v117
	v_fmac_f32_e32 v6, v118, v118
	v_fmac_f32_e32 v7, v119, v119
	v_fmac_f32_e32 v6, v120, v120
	v_fmac_f32_e32 v7, v121, v121
	v_add_f32_e32 v6, v6, v7
	s_nop 1
	v_add_f32_dpp v8, v6, v6 quad_perm:[1,0,3,2] row_mask:0xf bank_mask:0xf
	s_nop 1
	v_add_f32_dpp v8, v8, v8 quad_perm:[2,3,0,1] row_mask:0xf bank_mask:0xf
	s_nop 1
	v_add_f32_dpp v8, v8, v8 row_half_mirror row_mask:0xf bank_mask:0xf
	s_nop 1
	v_add_f32_dpp v8, v8, v8 row_mirror row_mask:0xf bank_mask:0xf
	s_nop 1
	v_add_f32_dpp v8, v8, v8 row_bcast:15 row_mask:0xa bank_mask:0xf
	s_nop 1
	v_add_f32_dpp v8, v8, v8 row_bcast:31 row_mask:0xc bank_mask:0xf
	s_nop 1
	v_readlane_b32 s84, v8, 63
	s_nop 1
	v_fma_f32 v4, s84, v2, v3
	v_rsq_f32_e32 v4, v4
	s_nop 0
	v_pk_mul_f32 v[34:35], v[106:107], v[4:5] op_sel_hi:[1,0]
	v_pk_mul_f32 v[36:37], v[108:109], v[4:5] op_sel_hi:[1,0]
	v_pk_mul_f32 v[38:39], v[110:111], v[4:5] op_sel_hi:[1,0]
	v_pk_mul_f32 v[40:41], v[112:113], v[4:5] op_sel_hi:[1,0]
	v_pk_mul_f32 v[42:43], v[114:115], v[4:5] op_sel_hi:[1,0]
	v_pk_mul_f32 v[44:45], v[116:117], v[4:5] op_sel_hi:[1,0]
	v_pk_mul_f32 v[46:47], v[118:119], v[4:5] op_sel_hi:[1,0]
	v_pk_mul_f32 v[48:49], v[120:121], v[4:5] op_sel_hi:[1,0]
	v_pk_mul_f32 v[34:35], v[34:35], v[192:193]
	v_pk_mul_f32 v[36:37], v[36:37], v[194:195]
	v_pk_mul_f32 v[38:39], v[38:39], v[196:197]
	v_pk_mul_f32 v[40:41], v[40:41], v[198:199]
	v_pk_mul_f32 v[42:43], v[42:43], v[200:201]
	v_pk_mul_f32 v[44:45], v[44:45], v[202:203]
	v_pk_mul_f32 v[46:47], v[46:47], v[204:205]
	v_pk_mul_f32 v[48:49], v[48:49], v[206:207]
	v_pk_fma_f32 v[34:35], v[34:35], v[208:209], v[228:229]
	v_pk_fma_f32 v[36:37], v[36:37], v[210:211], v[230:231]
	v_pk_fma_f32 v[38:39], v[38:39], v[212:213], v[232:233]
	v_pk_fma_f32 v[40:41], v[40:41], v[214:215], v[234:235]
	v_pk_fma_f32 v[42:43], v[42:43], v[220:221], v[236:237]
	v_pk_fma_f32 v[44:45], v[44:45], v[222:223], v[238:239]
	v_pk_fma_f32 v[46:47], v[46:47], v[224:225], v[26:27]
	v_pk_fma_f32 v[48:49], v[48:49], v[226:227], v[28:29]
	v_cvt_pk_bf16_f32 v50, v34, v35
	v_cvt_pk_bf16_f32 v51, v36, v37
	v_cvt_pk_bf16_f32 v52, v38, v39
	v_cvt_pk_bf16_f32 v53, v40, v41
	v_cvt_pk_bf16_f32 v54, v42, v43
	v_cvt_pk_bf16_f32 v55, v44, v45
	v_cvt_pk_bf16_f32 v56, v46, v47
	v_cvt_pk_bf16_f32 v57, v48, v49
	global_store_dwordx2 v1, v[50:51], s[16:17] offset:0
	global_store_dwordx2 v1, v[52:53], s[16:17] offset:512
	global_store_dwordx2 v1, v[54:55], s[16:17] offset:1024
	global_store_dwordx2 v1, v[56:57], s[16:17] offset:1536
	s_add_u32 s16, s16, 0x800
	s_addc_u32 s17, s17, 0
	global_load_dwordx4 v[106:109], v0, s[4:5] offset:0 nt
	global_load_dwordx4 v[110:113], v0, s[4:5] offset:1024 nt
	global_load_dwordx4 v[114:117], v0, s[4:5] offset:2048 nt
	global_load_dwordx4 v[118:121], v0, s[4:5] offset:3072 nt
	global_load_dwordx2 v[146:147], v1, s[12:13] offset:0 nt
	global_load_dwordx2 v[148:149], v1, s[12:13] offset:512 nt
	global_load_dwordx2 v[150:151], v1, s[12:13] offset:1024 nt
	global_load_dwordx2 v[152:153], v1, s[12:13] offset:1536 nt
	s_add_u32 s4, s4, 0x1000
	s_addc_u32 s5, s5, 0
	s_add_u32 s12, s12, 0x800
	s_addc_u32 s13, s13, 0
	s_waitcnt vmcnt(48)
; __device__ __forceinline__ unsigned cvt_pk_bf16(float lo, float hi) { unsigned r; asm volatile("v_cvt_pk_bf16_f32 %0, %1, %2" : "=v"(r) : "v"(lo), "v"(hi)); return r; }
; __device__ __forceinline__ float bflo(unsigned w) { return __uint_as_float(w << 16); }
; __device__ __forceinline__ float bfhi(unsigned w) { return __uint_as_float(w & 0xffff0000u); }
; template <bool BR, bool WH> ...
;     ...
;         if (BR) {
;             f32x4 m[4]; float s = 0.f;
; #pragma unroll
;             for (int j = 0; j < 4; ++j) { m[j] = (f32x4){bflo(bc[j].x), bfhi(bc[j].x), bflo(bc[j].y), bfhi(bc[j].y)};
;                 s += (m[j][0] * m[j][0] + m[j][1] * m[j][1]) + (m[j][2] * m[j][2] + m[j][3] * m[j][3]); }
;             const float rs = rsqrtf(wave_sum(s, lane) * (1.f / 1024.f) + EPS);
;             float* xo = row < ML ? xout_lat + (size_t)row * 1024 : xout_ctx + (size_t)(row - ML) * 1024;
; #pragma unroll
;             for (int j = 0; j < 4; ++j) { const f32x4 gp = *(const f32x4*)(g_post + 4 * lane + 256 * j), ga = *(const f32x4*)(mod_g + (size_t)mrow * 6144 + gate_off + 4 * lane + 256 * j);
;                 x[j] = x[j] + ga * ((m[j] * rs) * gp); __builtin_nontemporal_store(x[j], (f32x4*)(xo + 4 * lane + 256 * j)); }
;         }
;         if (WH) {
;             float s = 0.f;
; #pragma unroll
;             for (int j = 0; j < 4; ++j) s += (x[j][0] * x[j][0] + x[j][1] * x[j][1]) + (x[j][2] * x[j][2] + x[j][3] * x[j][3]);
;             const float rs = rsqrtf(wave_sum(s, lane) * (1.f / 1024.f) + EPS);
; #pragma unroll
;             for (int j = 0; j < 4; ++j) { const f32x4 gp = *(const f32x4*)(g_pre + 4 * lane + 256 * j), sc = *(const f32x4*)(mod_h + (size_t)mrow * 6144 + sc_off + 4 * lane + 256 * j),
;                     sh = *(const f32x4*)(mod_h + (size_t)mrow * 6144 + sh_off + 4 * lane + 256 * j);
;                 const f32x4 hv = ((x[j] * rs) * gp) * (sc + 1.0f) + sh;
;                 u32x2 w; w.x = cvt_pk_bf16(hv[0], hv[1]); w.y = cvt_pk_bf16(hv[2], hv[3]);
;                 *(u32x2*)(Hout + (size_t)row * 1024 + 4 * lane + 256 * j) = w; }
;         }
	v_lshlrev_b32_e32 v10, 16, v122
	v_and_b32_e32 v11, 0xffff0000, v122
	v_lshlrev_b32_e32 v12, 16, v123
	v_and_b32_e32 v13, 0xffff0000, v123
	v_lshlrev_b32_e32 v14, 16, v124
	v_and_b32_e32 v15, 0xffff0000, v124
	v_lshlrev_b32_e32 v16, 16, v125
	v_and_b32_e32 v17, 0xffff0000, v125
	v_lshlrev_b32_e32 v18, 16, v126
	v_and_b32_e32 v19, 0xffff0000, v126
	v_lshlrev_b32_e32 v20, 16, v127
	v_and_b32_e32 v21, 0xffff0000, v127
	v_lshlrev_b32_e32 v22, 16, v128
	v_and_b32_e32 v23, 0xffff0000, v128
	v_lshlrev_b32_e32 v24, 16, v129
	v_and_b32_e32 v25, 0xffff0000, v129
	v_mul_f32_e32 v6, v10, v10
	v_mul_f32_e32 v7, v11, v11
	v_fmac_f32_e32 v6, v12, v12
	v_fmac_f32_e32 v7, v13, v13
	v_fmac_f32_e32 v6, v14, v14
	v_fmac_f32_e32 v7, v15, v15
	v_fmac_f32_e32 v6, v16, v16
	v_fmac_f32_e32 v7, v17, v17
	v_fmac_f32_e32 v6, v18, v18
	v_fmac_f32_e32 v7, v19, v19
	v_fmac_f32_e32 v6, v20, v20
	v_fmac_f32_e32 v7, v21, v21
	v_fmac_f32_e32 v6, v22, v22
	v_fmac_f32_e32 v7, v23, v23
	v_fmac_f32_e32 v6, v24, v24
	v_fmac_f32_e32 v7, v25, v25
	v_add_f32_e32 v6, v6, v7
	s_nop 1
	v_add_f32_dpp v8, v6, v6 quad_perm:[1,0,3,2] row_mask:0xf bank_mask:0xf
	s_nop 1
	v_add_f32_dpp v8, v8, v8 quad_perm:[2,3,0,1] row_mask:0xf bank_mask:0xf
	s_nop 1
	v_add_f32_dpp v8, v8, v8 row_half_mirror row_mask:0xf bank_mask:0xf
	s_nop 1
	v_add_f32_dpp v8, v8, v8 row_mirror row_mask:0xf bank_mask:0xf
	s_nop 1
	v_add_f32_dpp v8, v8, v8 row_bcast:15 row_mask:0xa bank_mask:0xf
	s_nop 1
	v_add_f32_dpp v8, v8, v8 row_bcast:31 row_mask:0xc bank_mask:0xf
	s_nop 1
	v_readlane_b32 s84, v8, 63
	s_nop 1
	v_fma_f32 v4, s84, v2, v3
	v_rsq_f32_e32 v4, v4
	s_nop 0
	v_pk_mul_f32 v[34:35], v[10:11], v[4:5] op_sel_hi:[1,0]
	v_pk_mul_f32 v[36:37], v[12:13], v[4:5] op_sel_hi:[1,0]
	v_pk_mul_f32 v[38:39], v[14:15], v[4:5] op_sel_hi:[1,0]
	v_pk_mul_f32 v[40:41], v[16:17], v[4:5] op_sel_hi:[1,0]
	v_pk_mul_f32 v[42:43], v[18:19], v[4:5] op_sel_hi:[1,0]
	v_pk_mul_f32 v[44:45], v[20:21], v[4:5] op_sel_hi:[1,0]
	v_pk_mul_f32 v[46:47], v[22:23], v[4:5] op_sel_hi:[1,0]
	v_pk_mul_f32 v[48:49], v[24:25], v[4:5] op_sel_hi:[1,0]
	v_pk_mul_f32 v[34:35], v[34:35], v[154:155]
	v_pk_mul_f32 v[36:37], v[36:37], v[156:157]
	v_pk_mul_f32 v[38:39], v[38:39], v[158:159]
	v_pk_mul_f32 v[40:41], v[40:41], v[160:161]
	v_pk_mul_f32 v[42:43], v[42:43], v[162:163]
	v_pk_mul_f32 v[44:45], v[44:45], v[164:165]
	v_pk_mul_f32 v[46:47], v[46:47], v[166:167]
	v_pk_mul_f32 v[48:49], v[48:49], v[168:169]
	v_pk_fma_f32 v[58:59], v[176:177], v[34:35], v[58:59]
	v_pk_fma_f32 v[60:61], v[178:179], v[36:37], v[60:61]
	v_pk_fma_f32 v[62:63], v[180:181], v[38:39], v[62:63]
	v_pk_fma_f32 v[64:65], v[182:183], v[40:41], v[64:65]
	v_pk_fma_f32 v[66:67], v[184:185], v[42:43], v[66:67]
	v_pk_fma_f32 v[68:69], v[186:187], v[44:45], v[68:69]
	v_pk_fma_f32 v[70:71], v[188:189], v[46:47], v[70:71]
	v_pk_fma_f32 v[72:73], v[190:191], v[48:49], v[72:73]
	global_store_dwordx4 v0, v[58:61], s[14:15] offset:0 nt
	global_store_dwordx4 v0, v[62:65], s[14:15] offset:1024 nt
	global_store_dwordx4 v0, v[66:69], s[14:15] offset:2048 nt
	global_store_dwordx4 v0, v[70:73], s[14:15] offset:3072 nt
	s_add_u32 s14, s14, 0x1000
	s_addc_u32 s15, s15, 0
	v_mul_f32_e32 v6, v58, v58
	v_mul_f32_e32 v7, v59, v59
	v_fmac_f32_e32 v6, v60, v60
	v_fmac_f32_e32 v7, v61, v61
	v_fmac_f32_e32 v6, v62, v62
	v_fmac_f32_e32 v7, v63, v63
	v_fmac_f32_e32 v6, v64, v64
	v_fmac_f32_e32 v7, v65, v65
	v_fmac_f32_e32 v6, v66, v66
	v_fmac_f32_e32 v7, v67, v67
	v_fmac_f32_e32 v6, v68, v68
	v_fmac_f32_e32 v7, v69, v69
	v_fmac_f32_e32 v6, v70, v70
	v_fmac_f32_e32 v7, v71, v71
	v_fmac_f32_e32 v6, v72, v72
	v_fmac_f32_e32 v7, v73, v73
	v_add_f32_e32 v6, v6, v7
	s_nop 1
	v_add_f32_dpp v8, v6, v6 quad_perm:[1,0,3,2] row_mask:0xf bank_mask:0xf
	s_nop 1
	v_add_f32_dpp v8, v8, v8 quad_perm:[2,3,0,1] row_mask:0xf bank_mask:0xf
	s_nop 1
	v_add_f32_dpp v8, v8, v8 row_half_mirror row_mask:0xf bank_mask:0xf
	s_nop 1
	v_add_f32_dpp v8, v8, v8 row_mirror row_mask:0xf bank_mask:0xf
	s_nop 1
	v_add_f32_dpp v8, v8, v8 row_bcast:15 row_mask:0xa bank_mask:0xf
	s_nop 1
	v_add_f32_dpp v8, v8, v8 row_bcast:31 row_mask:0xc bank_mask:0xf
	s_nop 1
	v_readlane_b32 s84, v8, 63
	s_nop 1
	v_fma_f32 v4, s84, v2, v3
	v_rsq_f32_e32 v4, v4
	s_nop 0
	v_pk_mul_f32 v[34:35], v[58:59], v[4:5] op_sel_hi:[1,0]
	v_pk_mul_f32 v[36:37], v[60:61], v[4:5] op_sel_hi:[1,0]
	v_pk_mul_f32 v[38:39], v[62:63], v[4:5] op_sel_hi:[1,0]
	v_pk_mul_f32 v[40:41], v[64:65], v[4:5] op_sel_hi:[1,0]
	v_pk_mul_f32 v[42:43], v[66:67], v[4:5] op_sel_hi:[1,0]
	v_pk_mul_f32 v[44:45], v[68:69], v[4:5] op_sel_hi:[1,0]
	v_pk_mul_f32 v[46:47], v[70:71], v[4:5] op_sel_hi:[1,0]
	v_pk_mul_f32 v[48:49], v[72:73], v[4:5] op_sel_hi:[1,0]
	v_pk_mul_f32 v[34:35], v[34:35], v[192:193]
	v_pk_mul_f32 v[36:37], v[36:37], v[194:195]
	v_pk_mul_f32 v[38:39], v[38:39], v[196:197]
	v_pk_mul_f32 v[40:41], v[40:41], v[198:199]
	v_pk_mul_f32 v[42:43], v[42:43], v[200:201]
	v_pk_mul_f32 v[44:45], v[44:45], v[202:203]
	v_pk_mul_f32 v[46:47], v[46:47], v[204:205]
	v_pk_mul_f32 v[48:49], v[48:49], v[206:207]
	v_pk_fma_f32 v[34:35], v[34:35], v[208:209], v[228:229]
	v_pk_fma_f32 v[36:37], v[36:37], v[210:211], v[230:231]
	v_pk_fma_f32 v[38:39], v[38:39], v[212:213], v[232:233]
	v_pk_fma_f32 v[40:41], v[40:41], v[214:215], v[234:235]
	v_pk_fma_f32 v[42:43], v[42:43], v[220:221], v[236:237]
	v_pk_fma_f32 v[44:45], v[44:45], v[222:223], v[238:239]
	v_pk_fma_f32 v[46:47], v[46:47], v[224:225], v[26:27]
	v_pk_fma_f32 v[48:49], v[48:49], v[226:227], v[28:29]
	v_cvt_pk_bf16_f32 v50, v34, v35
	v_cvt_pk_bf16_f32 v51, v36, v37
	v_cvt_pk_bf16_f32 v52, v38, v39
	v_cvt_pk_bf16_f32 v53, v40, v41
	v_cvt_pk_bf16_f32 v54, v42, v43
	v_cvt_pk_bf16_f32 v55, v44, v45
	v_cvt_pk_bf16_f32 v56, v46, v47
	v_cvt_pk_bf16_f32 v57, v48, v49
	global_store_dwordx2 v1, v[50:51], s[16:17] offset:0
	global_store_dwordx2 v1, v[52:53], s[16:17] offset:512
	global_store_dwordx2 v1, v[54:55], s[16:17] offset:1024
	global_store_dwordx2 v1, v[56:57], s[16:17] offset:1536
	s_add_u32 s16, s16, 0x800
	s_addc_u32 s17, s17, 0
	s_waitcnt vmcnt(40)
; __device__ __forceinline__ unsigned cvt_pk_bf16(float lo, float hi) { unsigned r; asm volatile("v_cvt_pk_bf16_f32 %0, %1, %2" : "=v"(r) : "v"(lo), "v"(hi)); return r; }
; __device__ __forceinline__ float bflo(unsigned w) { return __uint_as_float(w << 16); }
; __device__ __forceinline__ float bfhi(unsigned w) { return __uint_as_float(w & 0xffff0000u); }
; template <bool BR, bool WH> ...
;     ...
;         if (BR) {
;             f32x4 m[4]; float s = 0.f;
; #pragma unroll
;             for (int j = 0; j < 4; ++j) { m[j] = (f32x4){bflo(bc[j].x), bfhi(bc[j].x), bflo(bc[j].y), bfhi(bc[j].y)};
;                 s += (m[j][0] * m[j][0] + m[j][1] * m[j][1]) + (m[j][2] * m[j][2] + m[j][3] * m[j][3]); }
;             const float rs = rsqrtf(wave_sum(s, lane) * (1.f / 1024.f) + EPS);
;             float* xo = row < ML ? xout_lat + (size_t)row * 1024 : xout_ctx + (size_t)(row - ML) * 1024;
; #pragma unroll
;             for (int j = 0; j < 4; ++j) { const f32x4 gp = *(const f32x4*)(g_post + 4 * lane + 256 * j), ga = *(const f32x4*)(mod_g + (size_t)mrow * 6144 + gate_off + 4 * lane + 256 * j);
;                 x[j] = x[j] + ga * ((m[j] * rs) * gp); __builtin_nontemporal_store(x[j], (f32x4*)(xo + 4 * lane + 256 * j)); }
;         }
;         if (WH) {
;             float s = 0.f;
; #pragma unroll
;             for (int j = 0; j < 4; ++j) s += (x[j][0] * x[j][0] + x[j][1] * x[j][1]) + (x[j][2] * x[j][2] + x[j][3] * x[j][3]);
;             const float rs = rsqrtf(wave_sum(s, lane) * (1.f / 1024.f) + EPS);
; #pragma unroll
;             for (int j = 0; j < 4; ++j) { const f32x4 gp = *(const f32x4*)(g_pre + 4 * lane + 256 * j), sc = *(const f32x4*)(mod_h + (size_t)mrow * 6144 + sc_off + 4 * lane + 256 * j),
;                     sh = *(const f32x4*)(mod_h + (size_t)mrow * 6144 + sh_off + 4 * lane + 256 * j);
;                 const f32x4 hv = ((x[j] * rs) * gp) * (sc + 1.0f) + sh;
;                 u32x2 w; w.x = cvt_pk_bf16(hv[0], hv[1]); w.y = cvt_pk_bf16(hv[2], hv[3]);
;                 *(u32x2*)(Hout + (size_t)row * 1024 + 4 * lane + 256 * j) = w; }
;         }
	v_lshlrev_b32_e32 v10, 16, v130
	v_and_b32_e32 v11, 0xffff0000, v130
	v_lshlrev_b32_e32 v12, 16, v131
	v_and_b32_e32 v13, 0xffff0000, v131
	v_lshlrev_b32_e32 v14, 16, v132
	v_and_b32_e32 v15, 0xffff0000, v132
	v_lshlrev_b32_e32 v16, 16, v133
	v_and_b32_e32 v17, 0xffff0000, v133
	v_lshlrev_b32_e32 v18, 16, v134
	v_and_b32_e32 v19, 0xffff0000, v134
	v_lshlrev_b32_e32 v20, 16, v135
	v_and_b32_e32 v21, 0xffff0000, v135
	v_lshlrev_b32_e32 v22, 16, v136
	v_and_b32_e32 v23, 0xffff0000, v136
	v_lshlrev_b32_e32 v24, 16, v137
	v_and_b32_e32 v25, 0xffff0000, v137
	v_mul_f32_e32 v6, v10, v10
	v_mul_f32_e32 v7, v11, v11
	v_fmac_f32_e32 v6, v12, v12
	v_fmac_f32_e32 v7, v13, v13
	v_fmac_f32_e32 v6, v14, v14
	v_fmac_f32_e32 v7, v15, v15
	v_fmac_f32_e32 v6, v16, v16
	v_fmac_f32_e32 v7, v17, v17
	v_fmac_f32_e32 v6, v18, v18
	v_fmac_f32_e32 v7, v19, v19
	v_fmac_f32_e32 v6, v20, v20
	v_fmac_f32_e32 v7, v21, v21
	v_fmac_f32_e32 v6, v22, v22
	v_fmac_f32_e32 v7, v23, v23
	v_fmac_f32_e32 v6, v24, v24
	v_fmac_f32_e32 v7, v25, v25
	v_add_f32_e32 v6, v6, v7
	s_nop 1
	v_add_f32_dpp v8, v6, v6 quad_perm:[1,0,3,2] row_mask:0xf bank_mask:0xf
	s_nop 1
	v_add_f32_dpp v8, v8, v8 quad_perm:[2,3,0,1] row_mask:0xf bank_mask:0xf
	s_nop 1
	v_add_f32_dpp v8, v8, v8 row_half_mirror row_mask:0xf bank_mask:0xf
	s_nop 1
	v_add_f32_dpp v8, v8, v8 row_mirror row_mask:0xf bank_mask:0xf
	s_nop 1
	v_add_f32_dpp v8, v8, v8 row_bcast:15 row_mask:0xa bank_mask:0xf
	s_nop 1
	v_add_f32_dpp v8, v8, v8 row_bcast:31 row_mask:0xc bank_mask:0xf
	s_nop 1
	v_readlane_b32 s84, v8, 63
	s_nop 1
	v_fma_f32 v4, s84, v2, v3
	v_rsq_f32_e32 v4, v4
	s_nop 0
	v_pk_mul_f32 v[34:35], v[10:11], v[4:5] op_sel_hi:[1,0]
	v_pk_mul_f32 v[36:37], v[12:13], v[4:5] op_sel_hi:[1,0]
	v_pk_mul_f32 v[38:39], v[14:15], v[4:5] op_sel_hi:[1,0]
	v_pk_mul_f32 v[40:41], v[16:17], v[4:5] op_sel_hi:[1,0]
	v_pk_mul_f32 v[42:43], v[18:19], v[4:5] op_sel_hi:[1,0]
	v_pk_mul_f32 v[44:45], v[20:21], v[4:5] op_sel_hi:[1,0]
	v_pk_mul_f32 v[46:47], v[22:23], v[4:5] op_sel_hi:[1,0]
	v_pk_mul_f32 v[48:49], v[24:25], v[4:5] op_sel_hi:[1,0]
	v_pk_mul_f32 v[34:35], v[34:35], v[154:155]
	v_pk_mul_f32 v[36:37], v[36:37], v[156:157]
	v_pk_mul_f32 v[38:39], v[38:39], v[158:159]
	v_pk_mul_f32 v[40:41], v[40:41], v[160:161]
	v_pk_mul_f32 v[42:43], v[42:43], v[162:163]
	v_pk_mul_f32 v[44:45], v[44:45], v[164:165]
	v_pk_mul_f32 v[46:47], v[46:47], v[166:167]
	v_pk_mul_f32 v[48:49], v[48:49], v[168:169]
	v_pk_fma_f32 v[74:75], v[176:177], v[34:35], v[74:75]
	v_pk_fma_f32 v[76:77], v[178:179], v[36:37], v[76:77]
	v_pk_fma_f32 v[78:79], v[180:181], v[38:39], v[78:79]
	v_pk_fma_f32 v[80:81], v[182:183], v[40:41], v[80:81]
	v_pk_fma_f32 v[82:83], v[184:185], v[42:43], v[82:83]
	v_pk_fma_f32 v[84:85], v[186:187], v[44:45], v[84:85]
	v_pk_fma_f32 v[86:87], v[188:189], v[46:47], v[86:87]
	v_pk_fma_f32 v[88:89], v[190:191], v[48:49], v[88:89]
	global_store_dwordx4 v0, v[74:77], s[14:15] offset:0 nt
	global_store_dwordx4 v0, v[78:81], s[14:15] offset:1024 nt
	global_store_dwordx4 v0, v[82:85], s[14:15] offset:2048 nt
	global_store_dwordx4 v0, v[86:89], s[14:15] offset:3072 nt
	s_add_u32 s14, s14, 0x1000
	s_addc_u32 s15, s15, 0
	v_mul_f32_e32 v6, v74, v74
	v_mul_f32_e32 v7, v75, v75
	v_fmac_f32_e32 v6, v76, v76
	v_fmac_f32_e32 v7, v77, v77
	v_fmac_f32_e32 v6, v78, v78
	v_fmac_f32_e32 v7, v79, v79
	v_fmac_f32_e32 v6, v80, v80
	v_fmac_f32_e32 v7, v81, v81
	v_fmac_f32_e32 v6, v82, v82
	v_fmac_f32_e32 v7, v83, v83
	v_fmac_f32_e32 v6, v84, v84
	v_fmac_f32_e32 v7, v85, v85
	v_fmac_f32_e32 v6, v86, v86
	v_fmac_f32_e32 v7, v87, v87
	v_fmac_f32_e32 v6, v88, v88
	v_fmac_f32_e32 v7, v89, v89
	v_add_f32_e32 v6, v6, v7
	s_nop 1
	v_add_f32_dpp v8, v6, v6 quad_perm:[1,0,3,2] row_mask:0xf bank_mask:0xf
	s_nop 1
	v_add_f32_dpp v8, v8, v8 quad_perm:[2,3,0,1] row_mask:0xf bank_mask:0xf
	s_nop 1
	v_add_f32_dpp v8, v8, v8 row_half_mirror row_mask:0xf bank_mask:0xf
	s_nop 1
	v_add_f32_dpp v8, v8, v8 row_mirror row_mask:0xf bank_mask:0xf
	s_nop 1
	v_add_f32_dpp v8, v8, v8 row_bcast:15 row_mask:0xa bank_mask:0xf
	s_nop 1
	v_add_f32_dpp v8, v8, v8 row_bcast:31 row_mask:0xc bank_mask:0xf
	s_nop 1
	v_readlane_b32 s84, v8, 63
	s_nop 1
	v_fma_f32 v4, s84, v2, v3
	v_rsq_f32_e32 v4, v4
	s_nop 0
	v_pk_mul_f32 v[34:35], v[74:75], v[4:5] op_sel_hi:[1,0]
	v_pk_mul_f32 v[36:37], v[76:77], v[4:5] op_sel_hi:[1,0]
	v_pk_mul_f32 v[38:39], v[78:79], v[4:5] op_sel_hi:[1,0]
	v_pk_mul_f32 v[40:41], v[80:81], v[4:5] op_sel_hi:[1,0]
	v_pk_mul_f32 v[42:43], v[82:83], v[4:5] op_sel_hi:[1,0]
	v_pk_mul_f32 v[44:45], v[84:85], v[4:5] op_sel_hi:[1,0]
	v_pk_mul_f32 v[46:47], v[86:87], v[4:5] op_sel_hi:[1,0]
	v_pk_mul_f32 v[48:49], v[88:89], v[4:5] op_sel_hi:[1,0]
	v_pk_mul_f32 v[34:35], v[34:35], v[192:193]
	v_pk_mul_f32 v[36:37], v[36:37], v[194:195]
	v_pk_mul_f32 v[38:39], v[38:39], v[196:197]
	v_pk_mul_f32 v[40:41], v[40:41], v[198:199]
	v_pk_mul_f32 v[42:43], v[42:43], v[200:201]
	v_pk_mul_f32 v[44:45], v[44:45], v[202:203]
	v_pk_mul_f32 v[46:47], v[46:47], v[204:205]
	v_pk_mul_f32 v[48:49], v[48:49], v[206:207]
	v_pk_fma_f32 v[34:35], v[34:35], v[208:209], v[228:229]
	v_pk_fma_f32 v[36:37], v[36:37], v[210:211], v[230:231]
	v_pk_fma_f32 v[38:39], v[38:39], v[212:213], v[232:233]
	v_pk_fma_f32 v[40:41], v[40:41], v[214:215], v[234:235]
	v_pk_fma_f32 v[42:43], v[42:43], v[220:221], v[236:237]
	v_pk_fma_f32 v[44:45], v[44:45], v[222:223], v[238:239]
	v_pk_fma_f32 v[46:47], v[46:47], v[224:225], v[26:27]
	v_pk_fma_f32 v[48:49], v[48:49], v[226:227], v[28:29]
	v_cvt_pk_bf16_f32 v50, v34, v35
	v_cvt_pk_bf16_f32 v51, v36, v37
	v_cvt_pk_bf16_f32 v52, v38, v39
	v_cvt_pk_bf16_f32 v53, v40, v41
	v_cvt_pk_bf16_f32 v54, v42, v43
	v_cvt_pk_bf16_f32 v55, v44, v45
	v_cvt_pk_bf16_f32 v56, v46, v47
	v_cvt_pk_bf16_f32 v57, v48, v49
	global_store_dwordx2 v1, v[50:51], s[16:17] offset:0
	global_store_dwordx2 v1, v[52:53], s[16:17] offset:512
	global_store_dwordx2 v1, v[54:55], s[16:17] offset:1024
	global_store_dwordx2 v1, v[56:57], s[16:17] offset:1536
	s_add_u32 s16, s16, 0x800
	s_addc_u32 s17, s17, 0
	s_waitcnt vmcnt(32)
; __device__ __forceinline__ unsigned cvt_pk_bf16(float lo, float hi) { unsigned r; asm volatile("v_cvt_pk_bf16_f32 %0, %1, %2" : "=v"(r) : "v"(lo), "v"(hi)); return r; }
; __device__ __forceinline__ float bflo(unsigned w) { return __uint_as_float(w << 16); }
; __device__ __forceinline__ float bfhi(unsigned w) { return __uint_as_float(w & 0xffff0000u); }
; template <bool BR, bool WH> ...
;     ...
;         if (BR) {
;             f32x4 m[4]; float s = 0.f;
; #pragma unroll
;             for (int j = 0; j < 4; ++j) { m[j] = (f32x4){bflo(bc[j].x), bfhi(bc[j].x), bflo(bc[j].y), bfhi(bc[j].y)};
;                 s += (m[j][0] * m[j][0] + m[j][1] * m[j][1]) + (m[j][2] * m[j][2] + m[j][3] * m[j][3]); }
;             const float rs = rsqrtf(wave_sum(s, lane) * (1.f / 1024.f) + EPS);
;             float* xo = row < ML ? xout_lat + (size_t)row * 1024 : xout_ctx + (size_t)(row - ML) * 1024;
; #pragma unroll
;             for (int j = 0; j < 4; ++j) { const f32x4 gp = *(const f32x4*)(g_post + 4 * lane + 256 * j), ga = *(const f32x4*)(mod_g + (size_t)mrow * 6144 + gate_off + 4 * lane + 256 * j);
;                 x[j] = x[j] + ga * ((m[j] * rs) * gp); __builtin_nontemporal_store(x[j], (f32x4*)(xo + 4 * lane + 256 * j)); }
;         }
;         if (WH) {
;             float s = 0.f;
; #pragma unroll
;             for (int j = 0; j < 4; ++j) s += (x[j][0] * x[j][0] + x[j][1] * x[j][1]) + (x[j][2] * x[j][2] + x[j][3] * x[j][3]);
;             const float rs = rsqrtf(wave_sum(s, lane) * (1.f / 1024.f) + EPS);
; #pragma unroll
;             for (int j = 0; j < 4; ++j) { const f32x4 gp = *(const f32x4*)(g_pre + 4 * lane + 256 * j), sc = *(const f32x4*)(mod_h + (size_t)mrow * 6144 + sc_off + 4 * lane + 256 * j),
;                     sh = *(const f32x4*)(mod_h + (size_t)mrow * 6144 + sh_off + 4 * lane + 256 * j);
;                 const f32x4 hv = ((x[j] * rs) * gp) * (sc + 1.0f) + sh;
;                 u32x2 w; w.x = cvt_pk_bf16(hv[0], hv[1]); w.y = cvt_pk_bf16(hv[2], hv[3]);
;                 *(u32x2*)(Hout + (size_t)row * 1024 + 4 * lane + 256 * j) = w; }
;         }
	v_lshlrev_b32_e32 v10, 16, v138
	v_and_b32_e32 v11, 0xffff0000, v138
	v_lshlrev_b32_e32 v12, 16, v139
	v_and_b32_e32 v13, 0xffff0000, v139
	v_lshlrev_b32_e32 v14, 16, v140
	v_and_b32_e32 v15, 0xffff0000, v140
	v_lshlrev_b32_e32 v16, 16, v141
	v_and_b32_e32 v17, 0xffff0000, v141
	v_lshlrev_b32_e32 v18, 16, v142
	v_and_b32_e32 v19, 0xffff0000, v142
	v_lshlrev_b32_e32 v20, 16, v143
	v_and_b32_e32 v21, 0xffff0000, v143
	v_lshlrev_b32_e32 v22, 16, v144
	v_and_b32_e32 v23, 0xffff0000, v144
	v_lshlrev_b32_e32 v24, 16, v145
	v_and_b32_e32 v25, 0xffff0000, v145
	v_mul_f32_e32 v6, v10, v10
	v_mul_f32_e32 v7, v11, v11
	v_fmac_f32_e32 v6, v12, v12
	v_fmac_f32_e32 v7, v13, v13
	v_fmac_f32_e32 v6, v14, v14
	v_fmac_f32_e32 v7, v15, v15
	v_fmac_f32_e32 v6, v16, v16
	v_fmac_f32_e32 v7, v17, v17
	v_fmac_f32_e32 v6, v18, v18
	v_fmac_f32_e32 v7, v19, v19
	v_fmac_f32_e32 v6, v20, v20
	v_fmac_f32_e32 v7, v21, v21
	v_fmac_f32_e32 v6, v22, v22
	v_fmac_f32_e32 v7, v23, v23
	v_fmac_f32_e32 v6, v24, v24
	v_fmac_f32_e32 v7, v25, v25
	v_add_f32_e32 v6, v6, v7
	s_nop 1
	v_add_f32_dpp v8, v6, v6 quad_perm:[1,0,3,2] row_mask:0xf bank_mask:0xf
	s_nop 1
	v_add_f32_dpp v8, v8, v8 quad_perm:[2,3,0,1] row_mask:0xf bank_mask:0xf
	s_nop 1
	v_add_f32_dpp v8, v8, v8 row_half_mirror row_mask:0xf bank_mask:0xf
	s_nop 1
	v_add_f32_dpp v8, v8, v8 row_mirror row_mask:0xf bank_mask:0xf
	s_nop 1
	v_add_f32_dpp v8, v8, v8 row_bcast:15 row_mask:0xa bank_mask:0xf
	s_nop 1
	v_add_f32_dpp v8, v8, v8 row_bcast:31 row_mask:0xc bank_mask:0xf
	s_nop 1
	v_readlane_b32 s84, v8, 63
	s_nop 1
	v_fma_f32 v4, s84, v2, v3
	v_rsq_f32_e32 v4, v4
	s_nop 0
	v_pk_mul_f32 v[34:35], v[10:11], v[4:5] op_sel_hi:[1,0]
	v_pk_mul_f32 v[36:37], v[12:13], v[4:5] op_sel_hi:[1,0]
	v_pk_mul_f32 v[38:39], v[14:15], v[4:5] op_sel_hi:[1,0]
	v_pk_mul_f32 v[40:41], v[16:17], v[4:5] op_sel_hi:[1,0]
	v_pk_mul_f32 v[42:43], v[18:19], v[4:5] op_sel_hi:[1,0]
	v_pk_mul_f32 v[44:45], v[20:21], v[4:5] op_sel_hi:[1,0]
	v_pk_mul_f32 v[46:47], v[22:23], v[4:5] op_sel_hi:[1,0]
	v_pk_mul_f32 v[48:49], v[24:25], v[4:5] op_sel_hi:[1,0]
	v_pk_mul_f32 v[34:35], v[34:35], v[154:155]
	v_pk_mul_f32 v[36:37], v[36:37], v[156:157]
	v_pk_mul_f32 v[38:39], v[38:39], v[158:159]
	v_pk_mul_f32 v[40:41], v[40:41], v[160:161]
	v_pk_mul_f32 v[42:43], v[42:43], v[162:163]
	v_pk_mul_f32 v[44:45], v[44:45], v[164:165]
	v_pk_mul_f32 v[46:47], v[46:47], v[166:167]
	v_pk_mul_f32 v[48:49], v[48:49], v[168:169]
	v_pk_fma_f32 v[90:91], v[176:177], v[34:35], v[90:91]
	v_pk_fma_f32 v[92:93], v[178:179], v[36:37], v[92:93]
	v_pk_fma_f32 v[94:95], v[180:181], v[38:39], v[94:95]
	v_pk_fma_f32 v[96:97], v[182:183], v[40:41], v[96:97]
	v_pk_fma_f32 v[98:99], v[184:185], v[42:43], v[98:99]
	v_pk_fma_f32 v[100:101], v[186:187], v[44:45], v[100:101]
	v_pk_fma_f32 v[102:103], v[188:189], v[46:47], v[102:103]
	v_pk_fma_f32 v[104:105], v[190:191], v[48:49], v[104:105]
	global_store_dwordx4 v0, v[90:93], s[14:15] offset:0 nt
	global_store_dwordx4 v0, v[94:97], s[14:15] offset:1024 nt
	global_store_dwordx4 v0, v[98:101], s[14:15] offset:2048 nt
	global_store_dwordx4 v0, v[102:105], s[14:15] offset:3072 nt
	s_add_u32 s14, s14, 0x1000
	s_addc_u32 s15, s15, 0
	v_mul_f32_e32 v6, v90, v90
	v_mul_f32_e32 v7, v91, v91
	v_fmac_f32_e32 v6, v92, v92
	v_fmac_f32_e32 v7, v93, v93
	v_fmac_f32_e32 v6, v94, v94
	v_fmac_f32_e32 v7, v95, v95
	v_fmac_f32_e32 v6, v96, v96
	v_fmac_f32_e32 v7, v97, v97
	v_fmac_f32_e32 v6, v98, v98
	v_fmac_f32_e32 v7, v99, v99
	v_fmac_f32_e32 v6, v100, v100
	v_fmac_f32_e32 v7, v101, v101
	v_fmac_f32_e32 v6, v102, v102
	v_fmac_f32_e32 v7, v103, v103
	v_fmac_f32_e32 v6, v104, v104
	v_fmac_f32_e32 v7, v105, v105
	v_add_f32_e32 v6, v6, v7
	s_nop 1
	v_add_f32_dpp v8, v6, v6 quad_perm:[1,0,3,2] row_mask:0xf bank_mask:0xf
	s_nop 1
	v_add_f32_dpp v8, v8, v8 quad_perm:[2,3,0,1] row_mask:0xf bank_mask:0xf
	s_nop 1
	v_add_f32_dpp v8, v8, v8 row_half_mirror row_mask:0xf bank_mask:0xf
	s_nop 1
	v_add_f32_dpp v8, v8, v8 row_mirror row_mask:0xf bank_mask:0xf
	s_nop 1
	v_add_f32_dpp v8, v8, v8 row_bcast:15 row_mask:0xa bank_mask:0xf
	s_nop 1
	v_add_f32_dpp v8, v8, v8 row_bcast:31 row_mask:0xc bank_mask:0xf
	s_nop 1
	v_readlane_b32 s84, v8, 63
	s_nop 1
	v_fma_f32 v4, s84, v2, v3
	v_rsq_f32_e32 v4, v4
	s_nop 0
	v_pk_mul_f32 v[34:35], v[90:91], v[4:5] op_sel_hi:[1,0]
	v_pk_mul_f32 v[36:37], v[92:93], v[4:5] op_sel_hi:[1,0]
	v_pk_mul_f32 v[38:39], v[94:95], v[4:5] op_sel_hi:[1,0]
	v_pk_mul_f32 v[40:41], v[96:97], v[4:5] op_sel_hi:[1,0]
	v_pk_mul_f32 v[42:43], v[98:99], v[4:5] op_sel_hi:[1,0]
	v_pk_mul_f32 v[44:45], v[100:101], v[4:5] op_sel_hi:[1,0]
	v_pk_mul_f32 v[46:47], v[102:103], v[4:5] op_sel_hi:[1,0]
	v_pk_mul_f32 v[48:49], v[104:105], v[4:5] op_sel_hi:[1,0]
	v_pk_mul_f32 v[34:35], v[34:35], v[192:193]
	v_pk_mul_f32 v[36:37], v[36:37], v[194:195]
	v_pk_mul_f32 v[38:39], v[38:39], v[196:197]
	v_pk_mul_f32 v[40:41], v[40:41], v[198:199]
	v_pk_mul_f32 v[42:43], v[42:43], v[200:201]
	v_pk_mul_f32 v[44:45], v[44:45], v[202:203]
	v_pk_mul_f32 v[46:47], v[46:47], v[204:205]
	v_pk_mul_f32 v[48:49], v[48:49], v[206:207]
	v_pk_fma_f32 v[34:35], v[34:35], v[208:209], v[228:229]
	v_pk_fma_f32 v[36:37], v[36:37], v[210:211], v[230:231]
	v_pk_fma_f32 v[38:39], v[38:39], v[212:213], v[232:233]
	v_pk_fma_f32 v[40:41], v[40:41], v[214:215], v[234:235]
	v_pk_fma_f32 v[42:43], v[42:43], v[220:221], v[236:237]
	v_pk_fma_f32 v[44:45], v[44:45], v[222:223], v[238:239]
	v_pk_fma_f32 v[46:47], v[46:47], v[224:225], v[26:27]
	v_pk_fma_f32 v[48:49], v[48:49], v[226:227], v[28:29]
	v_cvt_pk_bf16_f32 v50, v34, v35
	v_cvt_pk_bf16_f32 v51, v36, v37
	v_cvt_pk_bf16_f32 v52, v38, v39
	v_cvt_pk_bf16_f32 v53, v40, v41
	v_cvt_pk_bf16_f32 v54, v42, v43
	v_cvt_pk_bf16_f32 v55, v44, v45
	v_cvt_pk_bf16_f32 v56, v46, v47
	v_cvt_pk_bf16_f32 v57, v48, v49
	global_store_dwordx2 v1, v[50:51], s[16:17] offset:0
	global_store_dwordx2 v1, v[52:53], s[16:17] offset:512
	global_store_dwordx2 v1, v[54:55], s[16:17] offset:1024
	global_store_dwordx2 v1, v[56:57], s[16:17] offset:1536
	s_add_u32 s16, s16, 0x800
	s_addc_u32 s17, s17, 0
	s_waitcnt vmcnt(24)
; __device__ __forceinline__ unsigned cvt_pk_bf16(float lo, float hi) { unsigned r; asm volatile("v_cvt_pk_bf16_f32 %0, %1, %2" : "=v"(r) : "v"(lo), "v"(hi)); return r; }
; __device__ __forceinline__ float bflo(unsigned w) { return __uint_as_float(w << 16); }
; __device__ __forceinline__ float bfhi(unsigned w) { return __uint_as_float(w & 0xffff0000u); }
; template <bool BR, bool WH> ...
;     ...
;         if (BR) {
;             f32x4 m[4]; float s = 0.f;
; #pragma unroll
;             for (int j = 0; j < 4; ++j) { m[j] = (f32x4){bflo(bc[j].x), bfhi(bc[j].x), bflo(bc[j].y), bfhi(bc[j].y)};
;                 s += (m[j][0] * m[j][0] + m[j][1] * m[j][1]) + (m[j][2] * m[j][2] + m[j][3] * m[j][3]); }
;             const float rs = rsqrtf(wave_sum(s, lane) * (1.f / 1024.f) + EPS);
;             float* xo = row < ML ? xout_lat + (size_t)row * 1024 : xout_ctx + (size_t)(row - ML) * 1024;
; #pragma unroll
;             for (int j = 0; j < 4; ++j) { const f32x4 gp = *(const f32x4*)(g_post + 4 * lane + 256 * j), ga = *(const f32x4*)(mod_g + (size_t)mrow * 6144 + gate_off + 4 * lane + 256 * j);
;                 x[j] = x[j] + ga * ((m[j] * rs) * gp); __builtin_nontemporal_store(x[j], (f32x4*)(xo + 4 * lane + 256 * j)); }
;         }
;         if (WH) {
;             float s = 0.f;
; #pragma unroll
;             for (int j = 0; j < 4; ++j) s += (x[j][0] * x[j][0] + x[j][1] * x[j][1]) + (x[j][2] * x[j][2] + x[j][3] * x[j][3]);
;             const float rs = rsqrtf(wave_sum(s, lane) * (1.f / 1024.f) + EPS);
; #pragma unroll
;             for (int j = 0; j < 4; ++j) { const f32x4 gp = *(const f32x4*)(g_pre + 4 * lane + 256 * j), sc = *(const f32x4*)(mod_h + (size_t)mrow * 6144 + sc_off + 4 * lane + 256 * j),
;                     sh = *(const f32x4*)(mod_h + (size_t)mrow * 6144 + sh_off + 4 * lane + 256 * j);
;                 const f32x4 hv = ((x[j] * rs) * gp) * (sc + 1.0f) + sh;
;                 u32x2 w; w.x = cvt_pk_bf16(hv[0], hv[1]); w.y = cvt_pk_bf16(hv[2], hv[3]);
;                 *(u32x2*)(Hout + (size_t)row * 1024 + 4 * lane + 256 * j) = w; }
;         }
;         if (!hn) break;
; #pragma unroll
;         for (int j = 0; j < 4; ++j) { xc[j] = xn[j]; bc[j] = bn[j]; }
;     }
	v_lshlrev_b32_e32 v10, 16, v146
	v_and_b32_e32 v11, 0xffff0000, v146
	v_lshlrev_b32_e32 v12, 16, v147
	v_and_b32_e32 v13, 0xffff0000, v147
	v_lshlrev_b32_e32 v14, 16, v148
	v_and_b32_e32 v15, 0xffff0000, v148
	v_lshlrev_b32_e32 v16, 16, v149
	v_and_b32_e32 v17, 0xffff0000, v149
	v_lshlrev_b32_e32 v18, 16, v150
	v_and_b32_e32 v19, 0xffff0000, v150
	v_lshlrev_b32_e32 v20, 16, v151
	v_and_b32_e32 v21, 0xffff0000, v151
	v_lshlrev_b32_e32 v22, 16, v152
	v_and_b32_e32 v23, 0xffff0000, v152
	v_lshlrev_b32_e32 v24, 16, v153
	v_and_b32_e32 v25, 0xffff0000, v153
	v_mul_f32_e32 v6, v10, v10
	v_mul_f32_e32 v7, v11, v11
	v_fmac_f32_e32 v6, v12, v12
	v_fmac_f32_e32 v7, v13, v13
	v_fmac_f32_e32 v6, v14, v14
	v_fmac_f32_e32 v7, v15, v15
	v_fmac_f32_e32 v6, v16, v16
	v_fmac_f32_e32 v7, v17, v17
	v_fmac_f32_e32 v6, v18, v18
	v_fmac_f32_e32 v7, v19, v19
	v_fmac_f32_e32 v6, v20, v20
	v_fmac_f32_e32 v7, v21, v21
	v_fmac_f32_e32 v6, v22, v22
	v_fmac_f32_e32 v7, v23, v23
	v_fmac_f32_e32 v6, v24, v24
	v_fmac_f32_e32 v7, v25, v25
	v_add_f32_e32 v6, v6, v7
	s_nop 1
	v_add_f32_dpp v8, v6, v6 quad_perm:[1,0,3,2] row_mask:0xf bank_mask:0xf
	s_nop 1
	v_add_f32_dpp v8, v8, v8 quad_perm:[2,3,0,1] row_mask:0xf bank_mask:0xf
	s_nop 1
	v_add_f32_dpp v8, v8, v8 row_half_mirror row_mask:0xf bank_mask:0xf
	s_nop 1
	v_add_f32_dpp v8, v8, v8 row_mirror row_mask:0xf bank_mask:0xf
	s_nop 1
	v_add_f32_dpp v8, v8, v8 row_bcast:15 row_mask:0xa bank_mask:0xf
	s_nop 1
	v_add_f32_dpp v8, v8, v8 row_bcast:31 row_mask:0xc bank_mask:0xf
	s_nop 1
	v_readlane_b32 s84, v8, 63
	s_nop 1
	v_fma_f32 v4, s84, v2, v3
	v_rsq_f32_e32 v4, v4
	s_nop 0
	v_pk_mul_f32 v[34:35], v[10:11], v[4:5] op_sel_hi:[1,0]
	v_pk_mul_f32 v[36:37], v[12:13], v[4:5] op_sel_hi:[1,0]
	v_pk_mul_f32 v[38:39], v[14:15], v[4:5] op_sel_hi:[1,0]
	v_pk_mul_f32 v[40:41], v[16:17], v[4:5] op_sel_hi:[1,0]
	v_pk_mul_f32 v[42:43], v[18:19], v[4:5] op_sel_hi:[1,0]
	v_pk_mul_f32 v[44:45], v[20:21], v[4:5] op_sel_hi:[1,0]
	v_pk_mul_f32 v[46:47], v[22:23], v[4:5] op_sel_hi:[1,0]
	v_pk_mul_f32 v[48:49], v[24:25], v[4:5] op_sel_hi:[1,0]
	v_pk_mul_f32 v[34:35], v[34:35], v[154:155]
	v_pk_mul_f32 v[36:37], v[36:37], v[156:157]
	v_pk_mul_f32 v[38:39], v[38:39], v[158:159]
	v_pk_mul_f32 v[40:41], v[40:41], v[160:161]
	v_pk_mul_f32 v[42:43], v[42:43], v[162:163]
	v_pk_mul_f32 v[44:45], v[44:45], v[164:165]
	v_pk_mul_f32 v[46:47], v[46:47], v[166:167]
	v_pk_mul_f32 v[48:49], v[48:49], v[168:169]
	v_pk_fma_f32 v[106:107], v[176:177], v[34:35], v[106:107]
	v_pk_fma_f32 v[108:109], v[178:179], v[36:37], v[108:109]
	v_pk_fma_f32 v[110:111], v[180:181], v[38:39], v[110:111]
	v_pk_fma_f32 v[112:113], v[182:183], v[40:41], v[112:113]
	v_pk_fma_f32 v[114:115], v[184:185], v[42:43], v[114:115]
	v_pk_fma_f32 v[116:117], v[186:187], v[44:45], v[116:117]
	v_pk_fma_f32 v[118:119], v[188:189], v[46:47], v[118:119]
	v_pk_fma_f32 v[120:121], v[190:191], v[48:49], v[120:121]
	global_store_dwordx4 v0, v[106:109], s[14:15] offset:0 nt
	global_store_dwordx4 v0, v[110:113], s[14:15] offset:1024 nt
	global_store_dwordx4 v0, v[114:117], s[14:15] offset:2048 nt
	global_store_dwordx4 v0, v[118:121], s[14:15] offset:3072 nt
	s_add_u32 s14, s14, 0x1000
	s_addc_u32 s15, s15, 0
	v_mul_f32_e32 v6, v106, v106
	v_mul_f32_e32 v7, v107, v107
	v_fmac_f32_e32 v6, v108, v108
	v_fmac_f32_e32 v7, v109, v109
	v_fmac_f32_e32 v6, v110, v110
	v_fmac_f32_e32 v7, v111, v111
	v_fmac_f32_e32 v6, v112, v112
	v_fmac_f32_e32 v7, v113, v113
	v_fmac_f32_e32 v6, v114, v114
	v_fmac_f32_e32 v7, v115, v115
	v_fmac_f32_e32 v6, v116, v116
	v_fmac_f32_e32 v7, v117, v117
	v_fmac_f32_e32 v6, v118, v118
	v_fmac_f32_e32 v7, v119, v119
	v_fmac_f32_e32 v6, v120, v120
	v_fmac_f32_e32 v7, v121, v121
	v_add_f32_e32 v6, v6, v7
	s_nop 1
	v_add_f32_dpp v8, v6, v6 quad_perm:[1,0,3,2] row_mask:0xf bank_mask:0xf
	s_nop 1
	v_add_f32_dpp v8, v8, v8 quad_perm:[2,3,0,1] row_mask:0xf bank_mask:0xf
	s_nop 1
	v_add_f32_dpp v8, v8, v8 row_half_mirror row_mask:0xf bank_mask:0xf
	s_nop 1
	v_add_f32_dpp v8, v8, v8 row_mirror row_mask:0xf bank_mask:0xf
	s_nop 1
	v_add_f32_dpp v8, v8, v8 row_bcast:15 row_mask:0xa bank_mask:0xf
	s_nop 1
	v_add_f32_dpp v8, v8, v8 row_bcast:31 row_mask:0xc bank_mask:0xf
	s_nop 1
	v_readlane_b32 s84, v8, 63
	s_nop 1
	v_fma_f32 v4, s84, v2, v3
	v_rsq_f32_e32 v4, v4
	s_nop 0
	v_pk_mul_f32 v[34:35], v[106:107], v[4:5] op_sel_hi:[1,0]
	v_pk_mul_f32 v[36:37], v[108:109], v[4:5] op_sel_hi:[1,0]
	v_pk_mul_f32 v[38:39], v[110:111], v[4:5] op_sel_hi:[1,0]
	v_pk_mul_f32 v[40:41], v[112:113], v[4:5] op_sel_hi:[1,0]
	v_pk_mul_f32 v[42:43], v[114:115], v[4:5] op_sel_hi:[1,0]
	v_pk_mul_f32 v[44:45], v[116:117], v[4:5] op_sel_hi:[1,0]
	v_pk_mul_f32 v[46:47], v[118:119], v[4:5] op_sel_hi:[1,0]
	v_pk_mul_f32 v[48:49], v[120:121], v[4:5] op_sel_hi:[1,0]
	v_pk_mul_f32 v[34:35], v[34:35], v[192:193]
	v_pk_mul_f32 v[36:37], v[36:37], v[194:195]
	v_pk_mul_f32 v[38:39], v[38:39], v[196:197]
	v_pk_mul_f32 v[40:41], v[40:41], v[198:199]
	v_pk_mul_f32 v[42:43], v[42:43], v[200:201]
	v_pk_mul_f32 v[44:45], v[44:45], v[202:203]
	v_pk_mul_f32 v[46:47], v[46:47], v[204:205]
	v_pk_mul_f32 v[48:49], v[48:49], v[206:207]
	v_pk_fma_f32 v[34:35], v[34:35], v[208:209], v[228:229]
	v_pk_fma_f32 v[36:37], v[36:37], v[210:211], v[230:231]
	v_pk_fma_f32 v[38:39], v[38:39], v[212:213], v[232:233]
	v_pk_fma_f32 v[40:41], v[40:41], v[214:215], v[234:235]
	v_pk_fma_f32 v[42:43], v[42:43], v[220:221], v[236:237]
	v_pk_fma_f32 v[44:45], v[44:45], v[222:223], v[238:239]
	v_pk_fma_f32 v[46:47], v[46:47], v[224:225], v[26:27]
	v_pk_fma_f32 v[48:49], v[48:49], v[226:227], v[28:29]
	v_cvt_pk_bf16_f32 v50, v34, v35
	v_cvt_pk_bf16_f32 v51, v36, v37
	v_cvt_pk_bf16_f32 v52, v38, v39
	v_cvt_pk_bf16_f32 v53, v40, v41
	v_cvt_pk_bf16_f32 v54, v42, v43
	v_cvt_pk_bf16_f32 v55, v44, v45
	v_cvt_pk_bf16_f32 v56, v46, v47
	v_cvt_pk_bf16_f32 v57, v48, v49
	global_store_dwordx2 v1, v[50:51], s[16:17] offset:0
	global_store_dwordx2 v1, v[52:53], s[16:17] offset:512
	global_store_dwordx2 v1, v[54:55], s[16:17] offset:1024
	global_store_dwordx2 v1, v[56:57], s[16:17] offset:1536
	s_add_u32 s16, s16, 0x800
	s_addc_u32 s17, s17, 0
	s_add_u32 s32, s32, s27
	s_branch .Lnrm_B_lat_loop

; __device__ __forceinline__ float bflo(unsigned w) { return __uint_as_float(w << 16); }
; __device__ __forceinline__ float bfhi(unsigned w) { return __uint_as_float(w & 0xffff0000u); }
; template <bool BR, bool WH> ...
;     ...
;     if (gw >= nrows) return;
;     NORM_LOAD(gw, xc, bc);
;     for (int row = gw; row < nrows; row += NGW) {
;         const bool hn = row + NGW < nrows;
;         if (hn) NORM_LOAD(row + NGW, xn, bn);
;         const int mrow = row < ML ? (row >> 12) : 4;
;         f32x4 x[4];
; #pragma unroll
;         for (int j = 0; j < 4; ++j) x[j] = xc[j];
;         if (BR) {
;             f32x4 m[4]; float s = 0.f;
; #pragma unroll
;             for (int j = 0; j < 4; ++j) { m[j] = (f32x4){bflo(bc[j].x), bfhi(bc[j].x), bflo(bc[j].y), bfhi(bc[j].y)};
;                 s += (m[j][0] * m[j][0] + m[j][1] * m[j][1]) + (m[j][2] * m[j][2] + m[j][3] * m[j][3]); }
;             const float rs = rsqrtf(wave_sum(s, lane) * (1.f / 1024.f) + EPS);
;             float* xo = row < ML ? xout_lat + (size_t)row * 1024 : xout_ctx + (size_t)(row - ML) * 1024;
; #pragma unroll
;             for (int j = 0; j < 4; ++j) { const f32x4 gp = *(const f32x4*)(g_post + 4 * lane + 256 * j), ga = *(const f32x4*)(mod_g + (size_t)mrow * 6144 + gate_off + 4 * lane + 256 * j);
;                 x[j] = x[j] + ga * ((m[j] * rs) * gp); __builtin_nontemporal_store(x[j], (f32x4*)(xo + 4 * lane + 256 * j)); }
;         }
.Lnrm_C_lat_loop:
	s_cmpk_lt_u32 s32, 0x800
	s_cbranch_scc0 .Lnrm_ret
	s_lshl_b32 s97, s32, 15
	s_add_u32 s4, s44, s97
	s_addc_u32 s5, s45, 0
	s_lshl_b32 s97, s32, 14
	s_add_u32 s12, s54, s97
	s_addc_u32 s13, s55, 0
	s_lshl_b32 s97, s32, 15
	s_add_u32 s14, s42, s97
	s_addc_u32 s15, s43, 0
	s_lshr_b32 s88, s32, 9
	s_mul_i32 s88, s88, 0x6000
	global_load_dwordx4 v[58:61], v0, s[4:5] offset:0 nt
	global_load_dwordx4 v[62:65], v0, s[4:5] offset:1024 nt
	global_load_dwordx4 v[66:69], v0, s[4:5] offset:2048 nt
	global_load_dwordx4 v[70:73], v0, s[4:5] offset:3072 nt
	global_load_dwordx2 v[122:123], v1, s[12:13] offset:0 nt
	global_load_dwordx2 v[124:125], v1, s[12:13] offset:512 nt
	global_load_dwordx2 v[126:127], v1, s[12:13] offset:1024 nt
	global_load_dwordx2 v[128:129], v1, s[12:13] offset:1536 nt
	s_add_u32 s4, s4, 0x1000
	s_addc_u32 s5, s5, 0
	s_add_u32 s12, s12, 0x800
	s_addc_u32 s13, s13, 0
	global_load_dwordx4 v[154:157], v0, s[90:91] offset:0
	global_load_dwordx4 v[158:161], v0, s[90:91] offset:1024
	global_load_dwordx4 v[162:165], v0, s[90:91] offset:2048
	global_load_dwordx4 v[166:169], v0, s[90:91] offset:3072
	s_add_u32 s98, s88, s8
	s_add_u32 s98, s98, s40
	s_addc_u32 s99, s41, 0
	s_add_u32 s98, s98, 0x1600000
	s_addc_u32 s99, s99, 0
	global_load_dwordx4 v[176:179], v0, s[98:99] offset:0
	global_load_dwordx4 v[180:183], v0, s[98:99] offset:1024
	global_load_dwordx4 v[184:187], v0, s[98:99] offset:2048
	global_load_dwordx4 v[188:191], v0, s[98:99] offset:3072
	global_load_dwordx4 v[74:77], v0, s[4:5] offset:0 nt
	global_load_dwordx4 v[78:81], v0, s[4:5] offset:1024 nt
	global_load_dwordx4 v[82:85], v0, s[4:5] offset:2048 nt
	global_load_dwordx4 v[86:89], v0, s[4:5] offset:3072 nt
	global_load_dwordx2 v[130:131], v1, s[12:13] offset:0 nt
	global_load_dwordx2 v[132:133], v1, s[12:13] offset:512 nt
	global_load_dwordx2 v[134:135], v1, s[12:13] offset:1024 nt
	global_load_dwordx2 v[136:137], v1, s[12:13] offset:1536 nt
	s_add_u32 s4, s4, 0x1000
	s_addc_u32 s5, s5, 0
	s_add_u32 s12, s12, 0x800
	s_addc_u32 s13, s13, 0
	global_load_dwordx4 v[90:93], v0, s[4:5] offset:0 nt
	global_load_dwordx4 v[94:97], v0, s[4:5] offset:1024 nt
	global_load_dwordx4 v[98:101], v0, s[4:5] offset:2048 nt
	global_load_dwordx4 v[102:105], v0, s[4:5] offset:3072 nt
	global_load_dwordx2 v[138:139], v1, s[12:13] offset:0 nt
	global_load_dwordx2 v[140:141], v1, s[12:13] offset:512 nt
	global_load_dwordx2 v[142:143], v1, s[12:13] offset:1024 nt
	global_load_dwordx2 v[144:145], v1, s[12:13] offset:1536 nt
	s_add_u32 s4, s4, 0x1000
	s_addc_u32 s5, s5, 0
	s_add_u32 s12, s12, 0x800
	s_addc_u32 s13, s13, 0
	global_load_dwordx4 v[106:109], v0, s[4:5] offset:0 nt
	global_load_dwordx4 v[110:113], v0, s[4:5] offset:1024 nt
	global_load_dwordx4 v[114:117], v0, s[4:5] offset:2048 nt
	global_load_dwordx4 v[118:121], v0, s[4:5] offset:3072 nt
	global_load_dwordx2 v[146:147], v1, s[12:13] offset:0 nt
	global_load_dwordx2 v[148:149], v1, s[12:13] offset:512 nt
	global_load_dwordx2 v[150:151], v1, s[12:13] offset:1024 nt
	global_load_dwordx2 v[152:153], v1, s[12:13] offset:1536 nt
	s_add_u32 s4, s4, 0x1000
	s_addc_u32 s5, s5, 0
	s_add_u32 s12, s12, 0x800
	s_addc_u32 s13, s13, 0
	s_waitcnt vmcnt(24)
	v_lshlrev_b32_e32 v10, 16, v122
	v_and_b32_e32 v11, 0xffff0000, v122
	v_lshlrev_b32_e32 v12, 16, v123
	v_and_b32_e32 v13, 0xffff0000, v123
	v_lshlrev_b32_e32 v14, 16, v124
	v_and_b32_e32 v15, 0xffff0000, v124
	v_lshlrev_b32_e32 v16, 16, v125
	v_and_b32_e32 v17, 0xffff0000, v125
	v_lshlrev_b32_e32 v18, 16, v126
	v_and_b32_e32 v19, 0xffff0000, v126
	v_lshlrev_b32_e32 v20, 16, v127
	v_and_b32_e32 v21, 0xffff0000, v127
	v_lshlrev_b32_e32 v22, 16, v128
	v_and_b32_e32 v23, 0xffff0000, v128
	v_lshlrev_b32_e32 v24, 16, v129
	v_and_b32_e32 v25, 0xffff0000, v129
	v_mul_f32_e32 v6, v10, v10
	v_mul_f32_e32 v7, v11, v11
	v_fmac_f32_e32 v6, v12, v12
	v_fmac_f32_e32 v7, v13, v13
	v_fmac_f32_e32 v6, v14, v14
	v_fmac_f32_e32 v7, v15, v15
	v_fmac_f32_e32 v6, v16, v16
	v_fmac_f32_e32 v7, v17, v17
	v_fmac_f32_e32 v6, v18, v18
	v_fmac_f32_e32 v7, v19, v19
	v_fmac_f32_e32 v6, v20, v20
	v_fmac_f32_e32 v7, v21, v21
	v_fmac_f32_e32 v6, v22, v22
	v_fmac_f32_e32 v7, v23, v23
	v_fmac_f32_e32 v6, v24, v24
	v_fmac_f32_e32 v7, v25, v25
	v_add_f32_e32 v6, v6, v7
	s_nop 1
	v_add_f32_dpp v8, v6, v6 quad_perm:[1,0,3,2] row_mask:0xf bank_mask:0xf
	s_nop 1
	v_add_f32_dpp v8, v8, v8 quad_perm:[2,3,0,1] row_mask:0xf bank_mask:0xf
	s_nop 1
	v_add_f32_dpp v8, v8, v8 row_half_mirror row_mask:0xf bank_mask:0xf
	s_nop 1
	v_add_f32_dpp v8, v8, v8 row_mirror row_mask:0xf bank_mask:0xf
	s_nop 1
	v_add_f32_dpp v8, v8, v8 row_bcast:15 row_mask:0xa bank_mask:0xf
	s_nop 1
	v_add_f32_dpp v8, v8, v8 row_bcast:31 row_mask:0xc bank_mask:0xf
	s_nop 1
	v_readlane_b32 s84, v8, 63
	s_nop 1
	v_fma_f32 v4, s84, v2, v3
	v_rsq_f32_e32 v4, v4
	s_nop 0
	v_pk_mul_f32 v[34:35], v[10:11], v[4:5] op_sel_hi:[1,0]
	v_pk_mul_f32 v[36:37], v[12:13], v[4:5] op_sel_hi:[1,0]
	v_pk_mul_f32 v[38:39], v[14:15], v[4:5] op_sel_hi:[1,0]
	v_pk_mul_f32 v[40:41], v[16:17], v[4:5] op_sel_hi:[1,0]
	v_pk_mul_f32 v[42:43], v[18:19], v[4:5] op_sel_hi:[1,0]
	v_pk_mul_f32 v[44:45], v[20:21], v[4:5] op_sel_hi:[1,0]
	v_pk_mul_f32 v[46:47], v[22:23], v[4:5] op_sel_hi:[1,0]
	v_pk_mul_f32 v[48:49], v[24:25], v[4:5] op_sel_hi:[1,0]
	v_pk_mul_f32 v[34:35], v[34:35], v[154:155]
	v_pk_mul_f32 v[36:37], v[36:37], v[156:157]
	v_pk_mul_f32 v[38:39], v[38:39], v[158:159]
	v_pk_mul_f32 v[40:41], v[40:41], v[160:161]
	v_pk_mul_f32 v[42:43], v[42:43], v[162:163]
	v_pk_mul_f32 v[44:45], v[44:45], v[164:165]
	v_pk_mul_f32 v[46:47], v[46:47], v[166:167]
	v_pk_mul_f32 v[48:49], v[48:49], v[168:169]
	v_pk_fma_f32 v[58:59], v[176:177], v[34:35], v[58:59]
	v_pk_fma_f32 v[60:61], v[178:179], v[36:37], v[60:61]
	v_pk_fma_f32 v[62:63], v[180:181], v[38:39], v[62:63]
	v_pk_fma_f32 v[64:65], v[182:183], v[40:41], v[64:65]
	v_pk_fma_f32 v[66:67], v[184:185], v[42:43], v[66:67]
	v_pk_fma_f32 v[68:69], v[186:187], v[44:45], v[68:69]
	v_pk_fma_f32 v[70:71], v[188:189], v[46:47], v[70:71]
	v_pk_fma_f32 v[72:73], v[190:191], v[48:49], v[72:73]
	global_store_dwordx4 v0, v[58:61], s[14:15] offset:0 nt
	global_store_dwordx4 v0, v[62:65], s[14:15] offset:1024 nt
	global_store_dwordx4 v0, v[66:69], s[14:15] offset:2048 nt
	global_store_dwordx4 v0, v[70:73], s[14:15] offset:3072 nt
	s_add_u32 s14, s14, 0x1000
	s_addc_u32 s15, s15, 0
	global_load_dwordx4 v[58:61], v0, s[4:5] offset:0 nt
	global_load_dwordx4 v[62:65], v0, s[4:5] offset:1024 nt
	global_load_dwordx4 v[66:69], v0, s[4:5] offset:2048 nt
	global_load_dwordx4 v[70:73], v0, s[4:5] offset:3072 nt
	global_load_dwordx2 v[122:123], v1, s[12:13] offset:0 nt
	global_load_dwordx2 v[124:125], v1, s[12:13] offset:512 nt
	global_load_dwordx2 v[126:127], v1, s[12:13] offset:1024 nt
	global_load_dwordx2 v[128:129], v1, s[12:13] offset:1536 nt
	s_add_u32 s4, s4, 0x1000
	s_addc_u32 s5, s5, 0
	s_add_u32 s12, s12, 0x800
	s_addc_u32 s13, s13, 0
	s_waitcnt vmcnt(28)
; __device__ __forceinline__ float bflo(unsigned w) { return __uint_as_float(w << 16); }
; __device__ __forceinline__ float bfhi(unsigned w) { return __uint_as_float(w & 0xffff0000u); }
; template <bool BR, bool WH> ...
;     ...
;         if (BR) {
;             f32x4 m[4]; float s = 0.f;
; #pragma unroll
;             for (int j = 0; j < 4; ++j) { m[j] = (f32x4){bflo(bc[j].x), bfhi(bc[j].x), bflo(bc[j].y), bfhi(bc[j].y)};
;                 s += (m[j][0] * m[j][0] + m[j][1] * m[j][1]) + (m[j][2] * m[j][2] + m[j][3] * m[j][3]); }
;             const float rs = rsqrtf(wave_sum(s, lane) * (1.f / 1024.f) + EPS);
;             float* xo = row < ML ? xout_lat + (size_t)row * 1024 : xout_ctx + (size_t)(row - ML) * 1024;
; #pragma unroll
;             for (int j = 0; j < 4; ++j) { const f32x4 gp = *(const f32x4*)(g_post + 4 * lane + 256 * j), ga = *(const f32x4*)(mod_g + (size_t)mrow * 6144 + gate_off + 4 * lane + 256 * j);
;                 x[j] = x[j] + ga * ((m[j] * rs) * gp); __builtin_nontemporal_store(x[j], (f32x4*)(xo + 4 * lane + 256 * j)); }
;         }
	v_lshlrev_b32_e32 v10, 16, v130
	v_and_b32_e32 v11, 0xffff0000, v130
	v_lshlrev_b32_e32 v12, 16, v131
	v_and_b32_e32 v13, 0xffff0000, v131
	v_lshlrev_b32_e32 v14, 16, v132
	v_and_b32_e32 v15, 0xffff0000, v132
	v_lshlrev_b32_e32 v16, 16, v133
	v_and_b32_e32 v17, 0xffff0000, v133
	v_lshlrev_b32_e32 v18, 16, v134
	v_and_b32_e32 v19, 0xffff0000, v134
	v_lshlrev_b32_e32 v20, 16, v135
	v_and_b32_e32 v21, 0xffff0000, v135
	v_lshlrev_b32_e32 v22, 16, v136
	v_and_b32_e32 v23, 0xffff0000, v136
	v_lshlrev_b32_e32 v24, 16, v137
	v_and_b32_e32 v25, 0xffff0000, v137
	v_mul_f32_e32 v6, v10, v10
	v_mul_f32_e32 v7, v11, v11
	v_fmac_f32_e32 v6, v12, v12
	v_fmac_f32_e32 v7, v13, v13
	v_fmac_f32_e32 v6, v14, v14
	v_fmac_f32_e32 v7, v15, v15
	v_fmac_f32_e32 v6, v16, v16
	v_fmac_f32_e32 v7, v17, v17
	v_fmac_f32_e32 v6, v18, v18
	v_fmac_f32_e32 v7, v19, v19
	v_fmac_f32_e32 v6, v20, v20
	v_fmac_f32_e32 v7, v21, v21
	v_fmac_f32_e32 v6, v22, v22
	v_fmac_f32_e32 v7, v23, v23
	v_fmac_f32_e32 v6, v24, v24
	v_fmac_f32_e32 v7, v25, v25
	v_add_f32_e32 v6, v6, v7
	s_nop 1
	v_add_f32_dpp v8, v6, v6 quad_perm:[1,0,3,2] row_mask:0xf bank_mask:0xf
	s_nop 1
	v_add_f32_dpp v8, v8, v8 quad_perm:[2,3,0,1] row_mask:0xf bank_mask:0xf
	s_nop 1
	v_add_f32_dpp v8, v8, v8 row_half_mirror row_mask:0xf bank_mask:0xf
	s_nop 1
	v_add_f32_dpp v8, v8, v8 row_mirror row_mask:0xf bank_mask:0xf
	s_nop 1
	v_add_f32_dpp v8, v8, v8 row_bcast:15 row_mask:0xa bank_mask:0xf
	s_nop 1
	v_add_f32_dpp v8, v8, v8 row_bcast:31 row_mask:0xc bank_mask:0xf
	s_nop 1
	v_readlane_b32 s84, v8, 63
	s_nop 1
	v_fma_f32 v4, s84, v2, v3
	v_rsq_f32_e32 v4, v4
	s_nop 0
	v_pk_mul_f32 v[34:35], v[10:11], v[4:5] op_sel_hi:[1,0]
	v_pk_mul_f32 v[36:37], v[12:13], v[4:5] op_sel_hi:[1,0]
	v_pk_mul_f32 v[38:39], v[14:15], v[4:5] op_sel_hi:[1,0]
	v_pk_mul_f32 v[40:41], v[16:17], v[4:5] op_sel_hi:[1,0]
	v_pk_mul_f32 v[42:43], v[18:19], v[4:5] op_sel_hi:[1,0]
	v_pk_mul_f32 v[44:45], v[20:21], v[4:5] op_sel_hi:[1,0]
	v_pk_mul_f32 v[46:47], v[22:23], v[4:5] op_sel_hi:[1,0]
	v_pk_mul_f32 v[48:49], v[24:25], v[4:5] op_sel_hi:[1,0]
	v_pk_mul_f32 v[34:35], v[34:35], v[154:155]
	v_pk_mul_f32 v[36:37], v[36:37], v[156:157]
	v_pk_mul_f32 v[38:39], v[38:39], v[158:159]
	v_pk_mul_f32 v[40:41], v[40:41], v[160:161]
	v_pk_mul_f32 v[42:43], v[42:43], v[162:163]
	v_pk_mul_f32 v[44:45], v[44:45], v[164:165]
	v_pk_mul_f32 v[46:47], v[46:47], v[166:167]
	v_pk_mul_f32 v[48:49], v[48:49], v[168:169]
	v_pk_fma_f32 v[74:75], v[176:177], v[34:35], v[74:75]
	v_pk_fma_f32 v[76:77], v[178:179], v[36:37], v[76:77]
	v_pk_fma_f32 v[78:79], v[180:181], v[38:39], v[78:79]
	v_pk_fma_f32 v[80:81], v[182:183], v[40:41], v[80:81]
	v_pk_fma_f32 v[82:83], v[184:185], v[42:43], v[82:83]
	v_pk_fma_f32 v[84:85], v[186:187], v[44:45], v[84:85]
	v_pk_fma_f32 v[86:87], v[188:189], v[46:47], v[86:87]
	v_pk_fma_f32 v[88:89], v[190:191], v[48:49], v[88:89]
	global_store_dwordx4 v0, v[74:77], s[14:15] offset:0 nt
	global_store_dwordx4 v0, v[78:81], s[14:15] offset:1024 nt
	global_store_dwordx4 v0, v[82:85], s[14:15] offset:2048 nt
	global_store_dwordx4 v0, v[86:89], s[14:15] offset:3072 nt
	s_add_u32 s14, s14, 0x1000
	s_addc_u32 s15, s15, 0
	global_load_dwordx4 v[74:77], v0, s[4:5] offset:0 nt
	global_load_dwordx4 v[78:81], v0, s[4:5] offset:1024 nt
	global_load_dwordx4 v[82:85], v0, s[4:5] offset:2048 nt
	global_load_dwordx4 v[86:89], v0, s[4:5] offset:3072 nt
	global_load_dwordx2 v[130:131], v1, s[12:13] offset:0 nt
	global_load_dwordx2 v[132:133], v1, s[12:13] offset:512 nt
	global_load_dwordx2 v[134:135], v1, s[12:13] offset:1024 nt
	global_load_dwordx2 v[136:137], v1, s[12:13] offset:1536 nt
	s_add_u32 s4, s4, 0x1000
	s_addc_u32 s5, s5, 0
	s_add_u32 s12, s12, 0x800
	s_addc_u32 s13, s13, 0
	s_waitcnt vmcnt(32)
	v_lshlrev_b32_e32 v10, 16, v138
	v_and_b32_e32 v11, 0xffff0000, v138
	v_lshlrev_b32_e32 v12, 16, v139
	v_and_b32_e32 v13, 0xffff0000, v139
	v_lshlrev_b32_e32 v14, 16, v140
	v_and_b32_e32 v15, 0xffff0000, v140
	v_lshlrev_b32_e32 v16, 16, v141
	v_and_b32_e32 v17, 0xffff0000, v141
	v_lshlrev_b32_e32 v18, 16, v142
	v_and_b32_e32 v19, 0xffff0000, v142
	v_lshlrev_b32_e32 v20, 16, v143
	v_and_b32_e32 v21, 0xffff0000, v143
	v_lshlrev_b32_e32 v22, 16, v144
	v_and_b32_e32 v23, 0xffff0000, v144
	v_lshlrev_b32_e32 v24, 16, v145
	v_and_b32_e32 v25, 0xffff0000, v145
	v_mul_f32_e32 v6, v10, v10
	v_mul_f32_e32 v7, v11, v11
	v_fmac_f32_e32 v6, v12, v12
	v_fmac_f32_e32 v7, v13, v13
	v_fmac_f32_e32 v6, v14, v14
	v_fmac_f32_e32 v7, v15, v15
	v_fmac_f32_e32 v6, v16, v16
	v_fmac_f32_e32 v7, v17, v17
	v_fmac_f32_e32 v6, v18, v18
	v_fmac_f32_e32 v7, v19, v19
	v_fmac_f32_e32 v6, v20, v20
	v_fmac_f32_e32 v7, v21, v21
	v_fmac_f32_e32 v6, v22, v22
	v_fmac_f32_e32 v7, v23, v23
	v_fmac_f32_e32 v6, v24, v24
	v_fmac_f32_e32 v7, v25, v25
	v_add_f32_e32 v6, v6, v7
	s_nop 1
	v_add_f32_dpp v8, v6, v6 quad_perm:[1,0,3,2] row_mask:0xf bank_mask:0xf
	s_nop 1
	v_add_f32_dpp v8, v8, v8 quad_perm:[2,3,0,1] row_mask:0xf bank_mask:0xf
	s_nop 1
	v_add_f32_dpp v8, v8, v8 row_half_mirror row_mask:0xf bank_mask:0xf
	s_nop 1
	v_add_f32_dpp v8, v8, v8 row_mirror row_mask:0xf bank_mask:0xf
	s_nop 1
	v_add_f32_dpp v8, v8, v8 row_bcast:15 row_mask:0xa bank_mask:0xf
	s_nop 1
	v_add_f32_dpp v8, v8, v8 row_bcast:31 row_mask:0xc bank_mask:0xf
	s_nop 1
	v_readlane_b32 s84, v8, 63
	s_nop 1
	v_fma_f32 v4, s84, v2, v3
	v_rsq_f32_e32 v4, v4
	s_nop 0
	v_pk_mul_f32 v[34:35], v[10:11], v[4:5] op_sel_hi:[1,0]
	v_pk_mul_f32 v[36:37], v[12:13], v[4:5] op_sel_hi:[1,0]
	v_pk_mul_f32 v[38:39], v[14:15], v[4:5] op_sel_hi:[1,0]
	v_pk_mul_f32 v[40:41], v[16:17], v[4:5] op_sel_hi:[1,0]
	v_pk_mul_f32 v[42:43], v[18:19], v[4:5] op_sel_hi:[1,0]
; __device__ __forceinline__ float bflo(unsigned w) { return __uint_as_float(w << 16); }
; __device__ __forceinline__ float bfhi(unsigned w) { return __uint_as_float(w & 0xffff0000u); }
; template <bool BR, bool WH> ...
;     ...
;         if (BR) {
;             f32x4 m[4]; float s = 0.f;
; #pragma unroll
;             for (int j = 0; j < 4; ++j) { m[j] = (f32x4){bflo(bc[j].x), bfhi(bc[j].x), bflo(bc[j].y), bfhi(bc[j].y)};
;                 s += (m[j][0] * m[j][0] + m[j][1] * m[j][1]) + (m[j][2] * m[j][2] + m[j][3] * m[j][3]); }
;             const float rs = rsqrtf(wave_sum(s, lane) * (1.f / 1024.f) + EPS);
;             float* xo = row < ML ? xout_lat + (size_t)row * 1024 : xout_ctx + (size_t)(row - ML) * 1024;
; #pragma unroll
;             for (int j = 0; j < 4; ++j) { const f32x4 gp = *(const f32x4*)(g_post + 4 * lane + 256 * j), ga = *(const f32x4*)(mod_g + (size_t)mrow * 6144 + gate_off + 4 * lane + 256 * j);
;                 x[j] = x[j] + ga * ((m[j] * rs) * gp); __builtin_nontemporal_store(x[j], (f32x4*)(xo + 4 * lane + 256 * j)); }
;         }
	v_pk_mul_f32 v[44:45], v[20:21], v[4:5] op_sel_hi:[1,0]
	v_pk_mul_f32 v[46:47], v[22:23], v[4:5] op_sel_hi:[1,0]
	v_pk_mul_f32 v[48:49], v[24:25], v[4:5] op_sel_hi:[1,0]
	v_pk_mul_f32 v[34:35], v[34:35], v[154:155]
	v_pk_mul_f32 v[36:37], v[36:37], v[156:157]
	v_pk_mul_f32 v[38:39], v[38:39], v[158:159]
	v_pk_mul_f32 v[40:41], v[40:41], v[160:161]
	v_pk_mul_f32 v[42:43], v[42:43], v[162:163]
	v_pk_mul_f32 v[44:45], v[44:45], v[164:165]
	v_pk_mul_f32 v[46:47], v[46:47], v[166:167]
	v_pk_mul_f32 v[48:49], v[48:49], v[168:169]
	v_pk_fma_f32 v[90:91], v[176:177], v[34:35], v[90:91]
	v_pk_fma_f32 v[92:93], v[178:179], v[36:37], v[92:93]
	v_pk_fma_f32 v[94:95], v[180:181], v[38:39], v[94:95]
	v_pk_fma_f32 v[96:97], v[182:183], v[40:41], v[96:97]
	v_pk_fma_f32 v[98:99], v[184:185], v[42:43], v[98:99]
	v_pk_fma_f32 v[100:101], v[186:187], v[44:45], v[100:101]
	v_pk_fma_f32 v[102:103], v[188:189], v[46:47], v[102:103]
	v_pk_fma_f32 v[104:105], v[190:191], v[48:49], v[104:105]
	global_store_dwordx4 v0, v[90:93], s[14:15] offset:0 nt
	global_store_dwordx4 v0, v[94:97], s[14:15] offset:1024 nt
	global_store_dwordx4 v0, v[98:101], s[14:15] offset:2048 nt
	global_store_dwordx4 v0, v[102:105], s[14:15] offset:3072 nt
	s_add_u32 s14, s14, 0x1000
	s_addc_u32 s15, s15, 0
	global_load_dwordx4 v[90:93], v0, s[4:5] offset:0 nt
	global_load_dwordx4 v[94:97], v0, s[4:5] offset:1024 nt
	global_load_dwordx4 v[98:101], v0, s[4:5] offset:2048 nt
	global_load_dwordx4 v[102:105], v0, s[4:5] offset:3072 nt
	global_load_dwordx2 v[138:139], v1, s[12:13] offset:0 nt
	global_load_dwordx2 v[140:141], v1, s[12:13] offset:512 nt
	global_load_dwordx2 v[142:143], v1, s[12:13] offset:1024 nt
	global_load_dwordx2 v[144:145], v1, s[12:13] offset:1536 nt
	s_add_u32 s4, s4, 0x1000
	s_addc_u32 s5, s5, 0
	s_add_u32 s12, s12, 0x800
	s_addc_u32 s13, s13, 0
	s_waitcnt vmcnt(36)
	v_lshlrev_b32_e32 v10, 16, v146
	v_and_b32_e32 v11, 0xffff0000, v146
	v_lshlrev_b32_e32 v12, 16, v147
	v_and_b32_e32 v13, 0xffff0000, v147
	v_lshlrev_b32_e32 v14, 16, v148
	v_and_b32_e32 v15, 0xffff0000, v148
	v_lshlrev_b32_e32 v16, 16, v149
	v_and_b32_e32 v17, 0xffff0000, v149
	v_lshlrev_b32_e32 v18, 16, v150
	v_and_b32_e32 v19, 0xffff0000, v150
	v_lshlrev_b32_e32 v20, 16, v151
	v_and_b32_e32 v21, 0xffff0000, v151
	v_lshlrev_b32_e32 v22, 16, v152
	v_and_b32_e32 v23, 0xffff0000, v152
	v_lshlrev_b32_e32 v24, 16, v153
	v_and_b32_e32 v25, 0xffff0000, v153
	v_mul_f32_e32 v6, v10, v10
	v_mul_f32_e32 v7, v11, v11
	v_fmac_f32_e32 v6, v12, v12
	v_fmac_f32_e32 v7, v13, v13
	v_fmac_f32_e32 v6, v14, v14
	v_fmac_f32_e32 v7, v15, v15
	v_fmac_f32_e32 v6, v16, v16
	v_fmac_f32_e32 v7, v17, v17
	v_fmac_f32_e32 v6, v18, v18
	v_fmac_f32_e32 v7, v19, v19
	v_fmac_f32_e32 v6, v20, v20
	v_fmac_f32_e32 v7, v21, v21
	v_fmac_f32_e32 v6, v22, v22
	v_fmac_f32_e32 v7, v23, v23
	v_fmac_f32_e32 v6, v24, v24
	v_fmac_f32_e32 v7, v25, v25
	v_add_f32_e32 v6, v6, v7
	s_nop 1
	v_add_f32_dpp v8, v6, v6 quad_perm:[1,0,3,2] row_mask:0xf bank_mask:0xf
	s_nop 1
	v_add_f32_dpp v8, v8, v8 quad_perm:[2,3,0,1] row_mask:0xf bank_mask:0xf
	s_nop 1
	v_add_f32_dpp v8, v8, v8 row_half_mirror row_mask:0xf bank_mask:0xf
	s_nop 1
	v_add_f32_dpp v8, v8, v8 row_mirror row_mask:0xf bank_mask:0xf
	s_nop 1
	v_add_f32_dpp v8, v8, v8 row_bcast:15 row_mask:0xa bank_mask:0xf
	s_nop 1
	v_add_f32_dpp v8, v8, v8 row_bcast:31 row_mask:0xc bank_mask:0xf
	s_nop 1
	v_readlane_b32 s84, v8, 63
	s_nop 1
	v_fma_f32 v4, s84, v2, v3
	v_rsq_f32_e32 v4, v4
	s_nop 0
	v_pk_mul_f32 v[34:35], v[10:11], v[4:5] op_sel_hi:[1,0]
	v_pk_mul_f32 v[36:37], v[12:13], v[4:5] op_sel_hi:[1,0]
	v_pk_mul_f32 v[38:39], v[14:15], v[4:5] op_sel_hi:[1,0]
	v_pk_mul_f32 v[40:41], v[16:17], v[4:5] op_sel_hi:[1,0]
	v_pk_mul_f32 v[42:43], v[18:19], v[4:5] op_sel_hi:[1,0]
	v_pk_mul_f32 v[44:45], v[20:21], v[4:5] op_sel_hi:[1,0]
	v_pk_mul_f32 v[46:47], v[22:23], v[4:5] op_sel_hi:[1,0]
	v_pk_mul_f32 v[48:49], v[24:25], v[4:5] op_sel_hi:[1,0]
	v_pk_mul_f32 v[34:35], v[34:35], v[154:155]
	v_pk_mul_f32 v[36:37], v[36:37], v[156:157]
	v_pk_mul_f32 v[38:39], v[38:39], v[158:159]
	v_pk_mul_f32 v[40:41], v[40:41], v[160:161]
	v_pk_mul_f32 v[42:43], v[42:43], v[162:163]
	v_pk_mul_f32 v[44:45], v[44:45], v[164:165]
	v_pk_mul_f32 v[46:47], v[46:47], v[166:167]
	v_pk_mul_f32 v[48:49], v[48:49], v[168:169]
	v_pk_fma_f32 v[106:107], v[176:177], v[34:35], v[106:107]
	v_pk_fma_f32 v[108:109], v[178:179], v[36:37], v[108:109]
	v_pk_fma_f32 v[110:111], v[180:181], v[38:39], v[110:111]
	v_pk_fma_f32 v[112:113], v[182:183], v[40:41], v[112:113]
	v_pk_fma_f32 v[114:115], v[184:185], v[42:43], v[114:115]
	v_pk_fma_f32 v[116:117], v[186:187], v[44:45], v[116:117]
	v_pk_fma_f32 v[118:119], v[188:189], v[46:47], v[118:119]
	v_pk_fma_f32 v[120:121], v[190:191], v[48:49], v[120:121]
	global_store_dwordx4 v0, v[106:109], s[14:15] offset:0 nt
	global_store_dwordx4 v0, v[110:113], s[14:15] offset:1024 nt
	global_store_dwordx4 v0, v[114:117], s[14:15] offset:2048 nt
	global_store_dwordx4 v0, v[118:121], s[14:15] offset:3072 nt
	s_add_u32 s14, s14, 0x1000
	s_addc_u32 s15, s15, 0
	global_load_dwordx4 v[106:109], v0, s[4:5] offset:0 nt
	global_load_dwordx4 v[110:113], v0, s[4:5] offset:1024 nt
	global_load_dwordx4 v[114:117], v0, s[4:5] offset:2048 nt
	global_load_dwordx4 v[118:121], v0, s[4:5] offset:3072 nt
	global_load_dwordx2 v[146:147], v1, s[12:13] offset:0 nt
	global_load_dwordx2 v[148:149], v1, s[12:13] offset:512 nt
	global_load_dwordx2 v[150:151], v1, s[12:13] offset:1024 nt
	global_load_dwordx2 v[152:153], v1, s[12:13] offset:1536 nt
	s_add_u32 s4, s4, 0x1000
	s_addc_u32 s5, s5, 0
	s_add_u32 s12, s12, 0x800
	s_addc_u32 s13, s13, 0
	s_waitcnt vmcnt(36)
; __device__ __forceinline__ float bflo(unsigned w) { return __uint_as_float(w << 16); }
; __device__ __forceinline__ float bfhi(unsigned w) { return __uint_as_float(w & 0xffff0000u); }
; template <bool BR, bool WH> ...
;     ...
;         if (BR) {
;             f32x4 m[4]; float s = 0.f;
; #pragma unroll
;             for (int j = 0; j < 4; ++j) { m[j] = (f32x4){bflo(bc[j].x), bfhi(bc[j].x), bflo(bc[j].y), bfhi(bc[j].y)};
;                 s += (m[j][0] * m[j][0] + m[j][1] * m[j][1]) + (m[j][2] * m[j][2] + m[j][3] * m[j][3]); }
;             const float rs = rsqrtf(wave_sum(s, lane) * (1.f / 1024.f) + EPS);
;             float* xo = row < ML ? xout_lat + (size_t)row * 1024 : xout_ctx + (size_t)(row - ML) * 1024;
; #pragma unroll
;             for (int j = 0; j < 4; ++j) { const f32x4 gp = *(const f32x4*)(g_post + 4 * lane + 256 * j), ga = *(const f32x4*)(mod_g + (size_t)mrow * 6144 + gate_off + 4 * lane + 256 * j);
;                 x[j] = x[j] + ga * ((m[j] * rs) * gp); __builtin_nontemporal_store(x[j], (f32x4*)(xo + 4 * lane + 256 * j)); }
;         }
	v_lshlrev_b32_e32 v10, 16, v122
	v_and_b32_e32 v11, 0xffff0000, v122
	v_lshlrev_b32_e32 v12, 16, v123
	v_and_b32_e32 v13, 0xffff0000, v123
	v_lshlrev_b32_e32 v14, 16, v124
	v_and_b32_e32 v15, 0xffff0000, v124
	v_lshlrev_b32_e32 v16, 16, v125
	v_and_b32_e32 v17, 0xffff0000, v125
	v_lshlrev_b32_e32 v18, 16, v126
	v_and_b32_e32 v19, 0xffff0000, v126
	v_lshlrev_b32_e32 v20, 16, v127
	v_and_b32_e32 v21, 0xffff0000, v127
	v_lshlrev_b32_e32 v22, 16, v128
	v_and_b32_e32 v23, 0xffff0000, v128
	v_lshlrev_b32_e32 v24, 16, v129
	v_and_b32_e32 v25, 0xffff0000, v129
	v_mul_f32_e32 v6, v10, v10
	v_mul_f32_e32 v7, v11, v11
	v_fmac_f32_e32 v6, v12, v12
	v_fmac_f32_e32 v7, v13, v13
	v_fmac_f32_e32 v6, v14, v14
	v_fmac_f32_e32 v7, v15, v15
	v_fmac_f32_e32 v6, v16, v16
	v_fmac_f32_e32 v7, v17, v17
	v_fmac_f32_e32 v6, v18, v18
	v_fmac_f32_e32 v7, v19, v19
	v_fmac_f32_e32 v6, v20, v20
	v_fmac_f32_e32 v7, v21, v21
	v_fmac_f32_e32 v6, v22, v22
	v_fmac_f32_e32 v7, v23, v23
	v_fmac_f32_e32 v6, v24, v24
	v_fmac_f32_e32 v7, v25, v25
	v_add_f32_e32 v6, v6, v7
	s_nop 1
	v_add_f32_dpp v8, v6, v6 quad_perm:[1,0,3,2] row_mask:0xf bank_mask:0xf
	s_nop 1
	v_add_f32_dpp v8, v8, v8 quad_perm:[2,3,0,1] row_mask:0xf bank_mask:0xf
	s_nop 1
	v_add_f32_dpp v8, v8, v8 row_half_mirror row_mask:0xf bank_mask:0xf
	s_nop 1
	v_add_f32_dpp v8, v8, v8 row_mirror row_mask:0xf bank_mask:0xf
	s_nop 1
	v_add_f32_dpp v8, v8, v8 row_bcast:15 row_mask:0xa bank_mask:0xf
	s_nop 1
	v_add_f32_dpp v8, v8, v8 row_bcast:31 row_mask:0xc bank_mask:0xf
	s_nop 1
	v_readlane_b32 s84, v8, 63
	s_nop 1
	v_fma_f32 v4, s84, v2, v3
	v_rsq_f32_e32 v4, v4
	s_nop 0
	v_pk_mul_f32 v[34:35], v[10:11], v[4:5] op_sel_hi:[1,0]
	v_pk_mul_f32 v[36:37], v[12:13], v[4:5] op_sel_hi:[1,0]
	v_pk_mul_f32 v[38:39], v[14:15], v[4:5] op_sel_hi:[1,0]
	v_pk_mul_f32 v[40:41], v[16:17], v[4:5] op_sel_hi:[1,0]
	v_pk_mul_f32 v[42:43], v[18:19], v[4:5] op_sel_hi:[1,0]
	v_pk_mul_f32 v[44:45], v[20:21], v[4:5] op_sel_hi:[1,0]
	v_pk_mul_f32 v[46:47], v[22:23], v[4:5] op_sel_hi:[1,0]
	v_pk_mul_f32 v[48:49], v[24:25], v[4:5] op_sel_hi:[1,0]
	v_pk_mul_f32 v[34:35], v[34:35], v[154:155]
	v_pk_mul_f32 v[36:37], v[36:37], v[156:157]
	v_pk_mul_f32 v[38:39], v[38:39], v[158:159]
	v_pk_mul_f32 v[40:41], v[40:41], v[160:161]
	v_pk_mul_f32 v[42:43], v[42:43], v[162:163]
	v_pk_mul_f32 v[44:45], v[44:45], v[164:165]
	v_pk_mul_f32 v[46:47], v[46:47], v[166:167]
	v_pk_mul_f32 v[48:49], v[48:49], v[168:169]
	v_pk_fma_f32 v[58:59], v[176:177], v[34:35], v[58:59]
	v_pk_fma_f32 v[60:61], v[178:179], v[36:37], v[60:61]
	v_pk_fma_f32 v[62:63], v[180:181], v[38:39], v[62:63]
	v_pk_fma_f32 v[64:65], v[182:183], v[40:41], v[64:65]
	v_pk_fma_f32 v[66:67], v[184:185], v[42:43], v[66:67]
	v_pk_fma_f32 v[68:69], v[186:187], v[44:45], v[68:69]
	v_pk_fma_f32 v[70:71], v[188:189], v[46:47], v[70:71]
	v_pk_fma_f32 v[72:73], v[190:191], v[48:49], v[72:73]
	global_store_dwordx4 v0, v[58:61], s[14:15] offset:0 nt
	global_store_dwordx4 v0, v[62:65], s[14:15] offset:1024 nt
	global_store_dwordx4 v0, v[66:69], s[14:15] offset:2048 nt
	global_store_dwordx4 v0, v[70:73], s[14:15] offset:3072 nt
	s_add_u32 s14, s14, 0x1000
	s_addc_u32 s15, s15, 0
	s_waitcnt vmcnt(28)
	v_lshlrev_b32_e32 v10, 16, v130
	v_and_b32_e32 v11, 0xffff0000, v130
	v_lshlrev_b32_e32 v12, 16, v131
	v_and_b32_e32 v13, 0xffff0000, v131
	v_lshlrev_b32_e32 v14, 16, v132
	v_and_b32_e32 v15, 0xffff0000, v132
	v_lshlrev_b32_e32 v16, 16, v133
	v_and_b32_e32 v17, 0xffff0000, v133
	v_lshlrev_b32_e32 v18, 16, v134
	v_and_b32_e32 v19, 0xffff0000, v134
	v_lshlrev_b32_e32 v20, 16, v135
	v_and_b32_e32 v21, 0xffff0000, v135
	v_lshlrev_b32_e32 v22, 16, v136
	v_and_b32_e32 v23, 0xffff0000, v136
	v_lshlrev_b32_e32 v24, 16, v137
	v_and_b32_e32 v25, 0xffff0000, v137
	v_mul_f32_e32 v6, v10, v10
	v_mul_f32_e32 v7, v11, v11
	v_fmac_f32_e32 v6, v12, v12
	v_fmac_f32_e32 v7, v13, v13
	v_fmac_f32_e32 v6, v14, v14
	v_fmac_f32_e32 v7, v15, v15
	v_fmac_f32_e32 v6, v16, v16
	v_fmac_f32_e32 v7, v17, v17
	v_fmac_f32_e32 v6, v18, v18
	v_fmac_f32_e32 v7, v19, v19
	v_fmac_f32_e32 v6, v20, v20
	v_fmac_f32_e32 v7, v21, v21
	v_fmac_f32_e32 v6, v22, v22
	v_fmac_f32_e32 v7, v23, v23
	v_fmac_f32_e32 v6, v24, v24
	v_fmac_f32_e32 v7, v25, v25
	v_add_f32_e32 v6, v6, v7
	s_nop 1
	v_add_f32_dpp v8, v6, v6 quad_perm:[1,0,3,2] row_mask:0xf bank_mask:0xf
	s_nop 1
	v_add_f32_dpp v8, v8, v8 quad_perm:[2,3,0,1] row_mask:0xf bank_mask:0xf
	s_nop 1
	v_add_f32_dpp v8, v8, v8 row_half_mirror row_mask:0xf bank_mask:0xf
	s_nop 1
	v_add_f32_dpp v8, v8, v8 row_mirror row_mask:0xf bank_mask:0xf
	s_nop 1
	v_add_f32_dpp v8, v8, v8 row_bcast:15 row_mask:0xa bank_mask:0xf
	s_nop 1
	v_add_f32_dpp v8, v8, v8 row_bcast:31 row_mask:0xc bank_mask:0xf
	s_nop 1
	v_readlane_b32 s84, v8, 63
	s_nop 1
	v_fma_f32 v4, s84, v2, v3
	v_rsq_f32_e32 v4, v4
	s_nop 0
	v_pk_mul_f32 v[34:35], v[10:11], v[4:5] op_sel_hi:[1,0]
	v_pk_mul_f32 v[36:37], v[12:13], v[4:5] op_sel_hi:[1,0]
	v_pk_mul_f32 v[38:39], v[14:15], v[4:5] op_sel_hi:[1,0]
	v_pk_mul_f32 v[40:41], v[16:17], v[4:5] op_sel_hi:[1,0]
	v_pk_mul_f32 v[42:43], v[18:19], v[4:5] op_sel_hi:[1,0]
	v_pk_mul_f32 v[44:45], v[20:21], v[4:5] op_sel_hi:[1,0]
	v_pk_mul_f32 v[46:47], v[22:23], v[4:5] op_sel_hi:[1,0]
	v_pk_mul_f32 v[48:49], v[24:25], v[4:5] op_sel_hi:[1,0]
	v_pk_mul_f32 v[34:35], v[34:35], v[154:155]
	v_pk_mul_f32 v[36:37], v[36:37], v[156:157]
	v_pk_mul_f32 v[38:39], v[38:39], v[158:159]
	v_pk_mul_f32 v[40:41], v[40:41], v[160:161]
	v_pk_mul_f32 v[42:43], v[42:43], v[162:163]
	v_pk_mul_f32 v[44:45], v[44:45], v[164:165]
	v_pk_mul_f32 v[46:47], v[46:47], v[166:167]
	v_pk_mul_f32 v[48:49], v[48:49], v[168:169]
	v_pk_fma_f32 v[74:75], v[176:177], v[34:35], v[74:75]
	v_pk_fma_f32 v[76:77], v[178:179], v[36:37], v[76:77]
	v_pk_fma_f32 v[78:79], v[180:181], v[38:39], v[78:79]
	v_pk_fma_f32 v[80:81], v[182:183], v[40:41], v[80:81]
	v_pk_fma_f32 v[82:83], v[184:185], v[42:43], v[82:83]
	v_pk_fma_f32 v[84:85], v[186:187], v[44:45], v[84:85]
	v_pk_fma_f32 v[86:87], v[188:189], v[46:47], v[86:87]
	v_pk_fma_f32 v[88:89], v[190:191], v[48:49], v[88:89]
	global_store_dwordx4 v0, v[74:77], s[14:15] offset:0 nt
	global_store_dwordx4 v0, v[78:81], s[14:15] offset:1024 nt
	global_store_dwordx4 v0, v[82:85], s[14:15] offset:2048 nt
	global_store_dwordx4 v0, v[86:89], s[14:15] offset:3072 nt
	s_add_u32 s14, s14, 0x1000
	s_addc_u32 s15, s15, 0
	s_waitcnt vmcnt(20)
; __device__ __forceinline__ float bflo(unsigned w) { return __uint_as_float(w << 16); }
; __device__ __forceinline__ float bfhi(unsigned w) { return __uint_as_float(w & 0xffff0000u); }
; template <bool BR, bool WH> ...
;     ...
;     for (int row = gw; row < nrows; row += NGW) {
;         const bool hn = row + NGW < nrows;
;         if (hn) NORM_LOAD(row + NGW, xn, bn);
;         const int mrow = row < ML ? (row >> 12) : 4;
;         f32x4 x[4];
; #pragma unroll
;         for (int j = 0; j < 4; ++j) x[j] = xc[j];
;         if (BR) {
;             f32x4 m[4]; float s = 0.f;
; #pragma unroll
;             for (int j = 0; j < 4; ++j) { m[j] = (f32x4){bflo(bc[j].x), bfhi(bc[j].x), bflo(bc[j].y), bfhi(bc[j].y)};
;                 s += (m[j][0] * m[j][0] + m[j][1] * m[j][1]) + (m[j][2] * m[j][2] + m[j][3] * m[j][3]); }
;             const float rs = rsqrtf(wave_sum(s, lane) * (1.f / 1024.f) + EPS);
;             float* xo = row < ML ? xout_lat + (size_t)row * 1024 : xout_ctx + (size_t)(row - ML) * 1024;
; #pragma unroll
;             for (int j = 0; j < 4; ++j) { const f32x4 gp = *(const f32x4*)(g_post + 4 * lane + 256 * j), ga = *(const f32x4*)(mod_g + (size_t)mrow * 6144 + gate_off + 4 * lane + 256 * j);
;                 x[j] = x[j] + ga * ((m[j] * rs) * gp); __builtin_nontemporal_store(x[j], (f32x4*)(xo + 4 * lane + 256 * j)); }
;         }
	v_lshlrev_b32_e32 v10, 16, v138
	v_and_b32_e32 v11, 0xffff0000, v138
	v_lshlrev_b32_e32 v12, 16, v139
	v_and_b32_e32 v13, 0xffff0000, v139
	v_lshlrev_b32_e32 v14, 16, v140
	v_and_b32_e32 v15, 0xffff0000, v140
	v_lshlrev_b32_e32 v16, 16, v141
	v_and_b32_e32 v17, 0xffff0000, v141
	v_lshlrev_b32_e32 v18, 16, v142
	v_and_b32_e32 v19, 0xffff0000, v142
	v_lshlrev_b32_e32 v20, 16, v143
	v_and_b32_e32 v21, 0xffff0000, v143
	v_lshlrev_b32_e32 v22, 16, v144
	v_and_b32_e32 v23, 0xffff0000, v144
	v_lshlrev_b32_e32 v24, 16, v145
	v_and_b32_e32 v25, 0xffff0000, v145
	v_mul_f32_e32 v6, v10, v10
	v_mul_f32_e32 v7, v11, v11
	v_fmac_f32_e32 v6, v12, v12
	v_fmac_f32_e32 v7, v13, v13
	v_fmac_f32_e32 v6, v14, v14
	v_fmac_f32_e32 v7, v15, v15
	v_fmac_f32_e32 v6, v16, v16
	v_fmac_f32_e32 v7, v17, v17
	v_fmac_f32_e32 v6, v18, v18
	v_fmac_f32_e32 v7, v19, v19
	v_fmac_f32_e32 v6, v20, v20
	v_fmac_f32_e32 v7, v21, v21
	v_fmac_f32_e32 v6, v22, v22
	v_fmac_f32_e32 v7, v23, v23
	v_fmac_f32_e32 v6, v24, v24
	v_fmac_f32_e32 v7, v25, v25
	v_add_f32_e32 v6, v6, v7
	s_nop 1
	v_add_f32_dpp v8, v6, v6 quad_perm:[1,0,3,2] row_mask:0xf bank_mask:0xf
	s_nop 1
	v_add_f32_dpp v8, v8, v8 quad_perm:[2,3,0,1] row_mask:0xf bank_mask:0xf
	s_nop 1
	v_add_f32_dpp v8, v8, v8 row_half_mirror row_mask:0xf bank_mask:0xf
	s_nop 1
	v_add_f32_dpp v8, v8, v8 row_mirror row_mask:0xf bank_mask:0xf
	s_nop 1
	v_add_f32_dpp v8, v8, v8 row_bcast:15 row_mask:0xa bank_mask:0xf
	s_nop 1
	v_add_f32_dpp v8, v8, v8 row_bcast:31 row_mask:0xc bank_mask:0xf
	s_nop 1
	v_readlane_b32 s84, v8, 63
	s_nop 1
	v_fma_f32 v4, s84, v2, v3
	v_rsq_f32_e32 v4, v4
	s_nop 0
	v_pk_mul_f32 v[34:35], v[10:11], v[4:5] op_sel_hi:[1,0]
	v_pk_mul_f32 v[36:37], v[12:13], v[4:5] op_sel_hi:[1,0]
	v_pk_mul_f32 v[38:39], v[14:15], v[4:5] op_sel_hi:[1,0]
	v_pk_mul_f32 v[40:41], v[16:17], v[4:5] op_sel_hi:[1,0]
	v_pk_mul_f32 v[42:43], v[18:19], v[4:5] op_sel_hi:[1,0]
	v_pk_mul_f32 v[44:45], v[20:21], v[4:5] op_sel_hi:[1,0]
	v_pk_mul_f32 v[46:47], v[22:23], v[4:5] op_sel_hi:[1,0]
	v_pk_mul_f32 v[48:49], v[24:25], v[4:5] op_sel_hi:[1,0]
	v_pk_mul_f32 v[34:35], v[34:35], v[154:155]
	v_pk_mul_f32 v[36:37], v[36:37], v[156:157]
	v_pk_mul_f32 v[38:39], v[38:39], v[158:159]
	v_pk_mul_f32 v[40:41], v[40:41], v[160:161]
	v_pk_mul_f32 v[42:43], v[42:43], v[162:163]
	v_pk_mul_f32 v[44:45], v[44:45], v[164:165]
	v_pk_mul_f32 v[46:47], v[46:47], v[166:167]
	v_pk_mul_f32 v[48:49], v[48:49], v[168:169]
	v_pk_fma_f32 v[90:91], v[176:177], v[34:35], v[90:91]
	v_pk_fma_f32 v[92:93], v[178:179], v[36:37], v[92:93]
	v_pk_fma_f32 v[94:95], v[180:181], v[38:39], v[94:95]
	v_pk_fma_f32 v[96:97], v[182:183], v[40:41], v[96:97]
	v_pk_fma_f32 v[98:99], v[184:185], v[42:43], v[98:99]
	v_pk_fma_f32 v[100:101], v[186:187], v[44:45], v[100:101]
	v_pk_fma_f32 v[102:103], v[188:189], v[46:47], v[102:103]
	v_pk_fma_f32 v[104:105], v[190:191], v[48:49], v[104:105]
	global_store_dwordx4 v0, v[90:93], s[14:15] offset:0 nt
	global_store_dwordx4 v0, v[94:97], s[14:15] offset:1024 nt
	global_store_dwordx4 v0, v[98:101], s[14:15] offset:2048 nt
	global_store_dwordx4 v0, v[102:105], s[14:15] offset:3072 nt
	s_add_u32 s14, s14, 0x1000
	s_addc_u32 s15, s15, 0
	s_waitcnt vmcnt(12)
	v_lshlrev_b32_e32 v10, 16, v146
	v_and_b32_e32 v11, 0xffff0000, v146
	v_lshlrev_b32_e32 v12, 16, v147
	v_and_b32_e32 v13, 0xffff0000, v147
	v_lshlrev_b32_e32 v14, 16, v148
	v_and_b32_e32 v15, 0xffff0000, v148
	v_lshlrev_b32_e32 v16, 16, v149
	v_and_b32_e32 v17, 0xffff0000, v149
	v_lshlrev_b32_e32 v18, 16, v150
	v_and_b32_e32 v19, 0xffff0000, v150
	v_lshlrev_b32_e32 v20, 16, v151
	v_and_b32_e32 v21, 0xffff0000, v151
	v_lshlrev_b32_e32 v22, 16, v152
	v_and_b32_e32 v23, 0xffff0000, v152
	v_lshlrev_b32_e32 v24, 16, v153
	v_and_b32_e32 v25, 0xffff0000, v153
	v_mul_f32_e32 v6, v10, v10
	v_mul_f32_e32 v7, v11, v11
	v_fmac_f32_e32 v6, v12, v12
	v_fmac_f32_e32 v7, v13, v13
	v_fmac_f32_e32 v6, v14, v14
	v_fmac_f32_e32 v7, v15, v15
	v_fmac_f32_e32 v6, v16, v16
	v_fmac_f32_e32 v7, v17, v17
	v_fmac_f32_e32 v6, v18, v18
	v_fmac_f32_e32 v7, v19, v19
	v_fmac_f32_e32 v6, v20, v20
	v_fmac_f32_e32 v7, v21, v21
	v_fmac_f32_e32 v6, v22, v22
	v_fmac_f32_e32 v7, v23, v23
	v_fmac_f32_e32 v6, v24, v24
	v_fmac_f32_e32 v7, v25, v25
	v_add_f32_e32 v6, v6, v7
	s_nop 1
	v_add_f32_dpp v8, v6, v6 quad_perm:[1,0,3,2] row_mask:0xf bank_mask:0xf
	s_nop 1
	v_add_f32_dpp v8, v8, v8 quad_perm:[2,3,0,1] row_mask:0xf bank_mask:0xf
	s_nop 1
	v_add_f32_dpp v8, v8, v8 row_half_mirror row_mask:0xf bank_mask:0xf
	s_nop 1
	v_add_f32_dpp v8, v8, v8 row_mirror row_mask:0xf bank_mask:0xf
	s_nop 1
	v_add_f32_dpp v8, v8, v8 row_bcast:15 row_mask:0xa bank_mask:0xf
	s_nop 1
	v_add_f32_dpp v8, v8, v8 row_bcast:31 row_mask:0xc bank_mask:0xf
	s_nop 1
	v_readlane_b32 s84, v8, 63
	s_nop 1
	v_fma_f32 v4, s84, v2, v3
	v_rsq_f32_e32 v4, v4
	s_nop 0
	v_pk_mul_f32 v[34:35], v[10:11], v[4:5] op_sel_hi:[1,0]
	v_pk_mul_f32 v[36:37], v[12:13], v[4:5] op_sel_hi:[1,0]
	v_pk_mul_f32 v[38:39], v[14:15], v[4:5] op_sel_hi:[1,0]
	v_pk_mul_f32 v[40:41], v[16:17], v[4:5] op_sel_hi:[1,0]
	v_pk_mul_f32 v[42:43], v[18:19], v[4:5] op_sel_hi:[1,0]
	v_pk_mul_f32 v[44:45], v[20:21], v[4:5] op_sel_hi:[1,0]
	v_pk_mul_f32 v[46:47], v[22:23], v[4:5] op_sel_hi:[1,0]
	v_pk_mul_f32 v[48:49], v[24:25], v[4:5] op_sel_hi:[1,0]
	v_pk_mul_f32 v[34:35], v[34:35], v[154:155]
	v_pk_mul_f32 v[36:37], v[36:37], v[156:157]
	v_pk_mul_f32 v[38:39], v[38:39], v[158:159]
	v_pk_mul_f32 v[40:41], v[40:41], v[160:161]
	v_pk_mul_f32 v[42:43], v[42:43], v[162:163]
	v_pk_mul_f32 v[44:45], v[44:45], v[164:165]
	v_pk_mul_f32 v[46:47], v[46:47], v[166:167]
	v_pk_mul_f32 v[48:49], v[48:49], v[168:169]
	v_pk_fma_f32 v[106:107], v[176:177], v[34:35], v[106:107]
	v_pk_fma_f32 v[108:109], v[178:179], v[36:37], v[108:109]
	v_pk_fma_f32 v[110:111], v[180:181], v[38:39], v[110:111]
	v_pk_fma_f32 v[112:113], v[182:183], v[40:41], v[112:113]
	v_pk_fma_f32 v[114:115], v[184:185], v[42:43], v[114:115]
	v_pk_fma_f32 v[116:117], v[186:187], v[44:45], v[116:117]
	v_pk_fma_f32 v[118:119], v[188:189], v[46:47], v[118:119]
	v_pk_fma_f32 v[120:121], v[190:191], v[48:49], v[120:121]
	global_store_dwordx4 v0, v[106:109], s[14:15] offset:0 nt
	global_store_dwordx4 v0, v[110:113], s[14:15] offset:1024 nt
	global_store_dwordx4 v0, v[114:117], s[14:15] offset:2048 nt
	global_store_dwordx4 v0, v[118:121], s[14:15] offset:3072 nt
	s_add_u32 s14, s14, 0x1000
	s_addc_u32 s15, s15, 0
	s_add_u32 s32, s32, s27
	s_branch .Lnrm_C_lat_loop

; __device__ __forceinline__ void convert_WA(const Ctx& F, int l) { convert_weights<false>(F, l); }
; __global__ void __launch_bounds__(512, 2) fwd_kernel(Params prm) {
;     ...
;         if (ph == 0) {
;             if (F.bid == F.G - 1) { float* TAB = (float*)(ws + OFF_TAB);
;                 for (int i = F.tid; i < 64 * 32; i += 512) { const int pos = i >> 5, f = i & 31; float sn, cs; sincosf((float)pos * exp2f(-(float)f * (13.287712379549449f / 32.0f)), &sn, &cs); TAB[2 * i] = cs; TAB[2 * i + 1] = sn; } }
;             mod_phase(F); __syncthreads(); convert_WA(F, 0); continue; }
;         if (ph == 1) { norm_phase<false, true>(F, MT, prm.in[0], prm.in[2], nullptr, nullptr, nullptr, nullptr, 0, nullptr, nullptr, prm.in[6], MOD, 1024, 0, RY); continue; }
.LBB0_76:
.LBB0_77:
	s_cmp_eq_u32 s72, 1
	s_cbranch_scc1 .Lnrm_ph1
	s_cmp_eq_u32 s72, 7
	s_cbranch_scc1 .Lnrm_sp5a
	s_cmp_eq_u32 s72, 16
	s_cbranch_scc1 .Lnrm_sp5b
	s_cmp_eq_u32 s72, 10
	s_cbranch_scc1 .Lnrm_sp8a
	s_cmp_eq_u32 s72, 19
	s_cbranch_scc1 .Lnrm_sp8b
.Lnrm_ret:
	v_readlane_b32 s73, v252, 7
	s_mov_b64 s[40:41], 0
	v_mbcnt_lo_u32_b32 v166, -1, 0
	v_mbcnt_hi_u32_b32 v166, -1, v166
	s_add_u32 s2, s66, s40
	s_addc_u32 s97, s67, s41
	s_add_u32 s0, s2, 0x1600000
	s_addc_u32 s1, s97, 0
	s_mov_b64 s[14:15], -1
	s_mov_b64 s[4:5], 0
	s_cmp_lt_i32 s72, 1
	s_mov_b64 s[12:13], 0
	s_cbranch_scc1 .LBB0_86
	s_cmp_eq_u32 s72, 1
	s_mov_b64 s[12:13], -1
	s_cbranch_scc0 .LBB0_90
	s_branch .LBB0_89

; __device__ __forceinline__ void convert_WA(const Ctx& F, int l) { convert_weights<false>(F, l); }
; __global__ void __launch_bounds__(512, 2) fwd_kernel(Params prm) {
;     ...
;         const int l = (ph - 2) / 9, sp = (ph - 2) % 9;
;         const bool lastl = (l == 1);
;         bf16_t* Hl = l == 0 ? RY : RX; bf16_t* XRb = l == 0 ? RX : RY;
;         bf16_t* HF = Hl; bf16_t* Gb = XRb; bf16_t* H2 = RX;
;         const int Mg = lastl ? ML : MT;
;         const float* xres_lat = l == 0 ? prm.in[0] : prm.out; const float* xres_ctx = l == 0 ? prm.in[2] : ctxres;
;         const float* modl = MOD + (size_t)l * 5 * 6144;
;         switch (sp) {
;     ...
;         case 8: { if (!lastl) { convert_WA(F, l + 1);
;                       norm_phase<true, true>(F, MT, prm.out, ctxres, Fb, Fb + (size_t)MT * 1024, prm.in[9] + l * 1024, modl, 5120, prm.out, ctxres, prm.in[6] + (l + 1) * 1024, MOD + (size_t)(l + 1) * 5 * 6144, 1024, 0, RX); }
;                   else norm_phase<true, false>(F, ML, prm.out, ctxres, Fb, nullptr, prm.in[9] + l * 1024, modl, 5120, prm.out, ctxres, nullptr, nullptr, 0, 0, nullptr); } break;
.LBB0_92:
	s_add_u32 s44, s2, 0x1a7c000
	s_addc_u32 s45, s97, 0
	s_add_u32 s24, s2, 0xd57c000
	s_addc_u32 s25, s97, 0
	s_add_i32 s4, s72, -2
	s_mul_hi_i32 s5, s4, 0x38e38e39
	s_lshr_b32 s8, s5, 31
	s_ashr_i32 s5, s5, 1
	s_add_i32 s88, s5, s8
	s_mul_i32 s5, s88, 9
	s_sub_i32 s76, s4, s5
	s_sub_i32 s4, s72, 20
	s_cmp_lt_u32 s4, -9
	s_cselect_b64 s[56:57], -1, 0
	s_cmp_gt_u32 s4, -10
	s_cselect_b64 s[42:43], -1, 0
	s_add_i32 s4, s72, 6
	s_cmp_lt_u32 s4, 17
	s_cselect_b64 s[48:49], -1, 0
	s_and_b64 s[4:5], s[48:49], exec
	s_cselect_b32 s5, s45, s25
	s_cselect_b32 s4, s44, s24
	v_writelane_b32 v255, s4, 22
	s_cselect_b32 s55, s25, s45
	s_cselect_b32 s54, s24, s44
	v_writelane_b32 v255, s5, 23
	s_add_u32 s4, s2, 0x3c7c000
	s_addc_u32 s5, s97, 0
	v_writelane_b32 v255, s4, 24
	s_add_u32 s14, s2, 0x917c000
	s_addc_u32 s15, s97, 0
	v_writelane_b32 v255, s5, 25
	v_writelane_b32 v255, s54, 26
	s_cmp_lt_i32 s76, 4
	s_mov_b64 s[4:5], -1
	v_writelane_b32 v255, s55, 27
	s_cbranch_scc1 .LBB0_341
	s_and_b64 s[4:5], s[56:57], exec
	s_movk_i32 s4, 0x4400
	s_cselect_b32 s12, s4, 0x4000
	s_mul_i32 s4, s88, 5
	s_mul_i32 s5, s88, 0x1e000
	s_mul_hi_i32 s4, s4, 0x6000
	s_add_u32 s16, s0, s5
	s_addc_u32 s17, s1, s4
	s_add_u32 s13, s2, 0x1200000
	s_addc_u32 s69, s97, 0
	s_add_u32 s4, s2, 0xb37c000
	s_addc_u32 s5, s97, 0
	s_cmp_lt_i32 s76, 6
	s_mov_b64 s[18:19], -1
	s_cbranch_scc1 .LBB0_210
	s_mov_b32 s87, s33
	s_cmp_lt_i32 s76, 7
	s_cbranch_scc1 .LBB0_192
	v_writelane_b32 v255, s56, 28
	s_cmp_lt_i32 s76, 8
	s_nop 0
	v_writelane_b32 v255, s57, 29
	s_cbranch_scc1 .LBB0_157
	s_cmp_eq_u32 s76, 8
	s_cbranch_scc0 .LBB0_156
	s_and_b64 vcc, exec, s[42:43]
	s_cbranch_vccz .LBB0_107
	s_branch .LBB0_106

; __device__ __forceinline__ void convert_WA(const Ctx& F, int l) { convert_weights<false>(F, l); }
; __global__ void __launch_bounds__(512, 2) fwd_kernel(Params prm) {
;     ...
;         case 8: { if (!lastl) { convert_WA(F, l + 1);
;                       norm_phase<true, true>(F, MT, prm.out, ctxres, Fb, Fb + (size_t)MT * 1024, prm.in[9] + l * 1024, modl, 5120, prm.out, ctxres, prm.in[6] + (l + 1) * 1024, MOD + (size_t)(l + 1) * 5 * 6144, 1024, 0, RX); }
;                   else norm_phase<true, false>(F, ML, prm.out, ctxres, Fb, nullptr, prm.in[9] + l * 1024, modl, 5120, prm.out, ctxres, nullptr, nullptr, 0, 0, nullptr); } break;
.LBB0_140:
	v_readlane_b32 s52, v255, 5
	s_cmpk_gt_i32 s20, 0x43ff
	v_readlane_b32 s56, v255, 9
	v_readlane_b32 s57, v255, 10
	v_readlane_b32 s53, v255, 6
	v_readlane_b32 s54, v255, 7
	v_readlane_b32 s55, v255, 8
	v_readlane_b32 s58, v255, 11
	v_readlane_b32 s59, v255, 12
	s_branch .LBB0_156

; __device__ __forceinline__ void convert_WF(const Ctx& F, int l) { convert_weights<true>(F, l); }
; __global__ void __launch_bounds__(512, 2) fwd_kernel(Params prm) {
;     ...
;         case 5: { convert_WF(F, l);
;                   norm_phase<true, true>(F, Mg, xres_lat, xres_ctx, Mx, lastl ? nullptr : Mx + (size_t)MT * 1024, prm.in[7] + l * 1024, modl, 2048, prm.out, ctxres, prm.in[8] + l * 1024, modl, 4096, 3072, H2); } break;
.LBB0_236:
	v_readlane_b32 s78, v255, 1
	v_readlane_b32 s54, v255, 26
	s_cmp_ge_i32 s20, s12
	v_readlane_b32 s79, v255, 2
	s_movk_i32 s39, 0x4000
	v_readlane_b32 s55, v255, 27
	s_mov_b64 s[56:57], s[84:85]
	s_branch .LBB0_252

; #define LAS __attribute__((address_space(3)))
; __global__ void __launch_bounds__(512, 2) fwd_kernel(Params prm) {
;     extern __shared__ __attribute__((aligned(16))) unsigned char shm[];
;     Ctx F; F.p = &prm; F.lds = (LAS unsigned char*)shm; F.ldsg = (char*)shm;
;     F.G = gridDim.x; F.bid = blockIdx.x;
;     const int wave0 = __builtin_amdgcn_readfirstlane(threadIdx.x >> 6);
	.amdhsa_kernel _Z10fwd_kernel6Params
		.amdhsa_group_segment_fixed_size 0
		.amdhsa_private_segment_fixed_size 0
		.amdhsa_kernarg_size 472
		.amdhsa_user_sgpr_count 2
		.amdhsa_user_sgpr_dispatch_ptr 0
		.amdhsa_user_sgpr_queue_ptr 0
		.amdhsa_user_sgpr_kernarg_segment_ptr 1
		.amdhsa_user_sgpr_dispatch_id 0
		.amdhsa_user_sgpr_kernarg_preload_length 0
		.amdhsa_user_sgpr_kernarg_preload_offset 0
		.amdhsa_user_sgpr_private_segment_size 0
		.amdhsa_uses_dynamic_stack 0
		.amdhsa_enable_private_segment 0
		.amdhsa_system_sgpr_workgroup_id_x 1
		.amdhsa_system_sgpr_workgroup_id_y 0
		.amdhsa_system_sgpr_workgroup_id_z 0
		.amdhsa_system_sgpr_workgroup_info 0
		.amdhsa_system_vgpr_workitem_id 2
		.amdhsa_next_free_vgpr 256
		.amdhsa_next_free_sgpr 102
		.amdhsa_accum_offset 256
		.amdhsa_reserve_vcc 1
		.amdhsa_float_round_mode_32 0
		.amdhsa_float_round_mode_16_64 0
		.amdhsa_float_denorm_mode_32 3
		.amdhsa_float_denorm_mode_16_64 3
		.amdhsa_dx10_clamp 1
		.amdhsa_ieee_mode 1
		.amdhsa_fp16_overflow 0
		.amdhsa_tg_split 0
		.amdhsa_exception_fp_ieee_invalid_op 0
		.amdhsa_exception_fp_denorm_src 0
		.amdhsa_exception_fp_ieee_div_zero 0
		.amdhsa_exception_fp_ieee_overflow 0
		.amdhsa_exception_fp_ieee_underflow 0
		.amdhsa_exception_fp_ieee_inexact 0
		.amdhsa_exception_int_div_zero 0
	.end_amdhsa_kernel

; #define LAS __attribute__((address_space(3)))
; __global__ void __launch_bounds__(512, 2) fwd_kernel(Params prm) {
;     extern __shared__ __attribute__((aligned(16))) unsigned char shm[];
;     Ctx F; F.p = &prm; F.lds = (LAS unsigned char*)shm; F.ldsg = (char*)shm;
;     F.G = gridDim.x; F.bid = blockIdx.x;
;     const int wave0 = __builtin_amdgcn_readfirstlane(threadIdx.x >> 6);
amdhsa.kernels:
  - .agpr_count:     0
    .args:
      - .offset:         0
        .size:           216
        .value_kind:     by_value
      - .offset:         216
        .size:           4
        .value_kind:     hidden_block_count_x
      - .offset:         220
        .size:           4
        .value_kind:     hidden_block_count_y
      - .offset:         224
        .size:           4
        .value_kind:     hidden_block_count_z
      - .offset:         228
        .size:           2
        .value_kind:     hidden_group_size_x
      - .offset:         230
        .size:           2
        .value_kind:     hidden_group_size_y
      - .offset:         232
        .size:           2
        .value_kind:     hidden_group_size_z
      - .offset:         234
        .size:           2
        .value_kind:     hidden_remainder_x
      - .offset:         236
        .size:           2
        .value_kind:     hidden_remainder_y
      - .offset:         238
        .size:           2
        .value_kind:     hidden_remainder_z
      - .offset:         256
        .size:           8
        .value_kind:     hidden_global_offset_x
      - .offset:         264
        .size:           8
        .value_kind:     hidden_global_offset_y
      - .offset:         272
        .size:           8
        .value_kind:     hidden_global_offset_z
      - .offset:         280
        .size:           2
        .value_kind:     hidden_grid_dims
      - .offset:         304
        .size:           8
        .value_kind:     hidden_multigrid_sync_arg
      - .offset:         336
        .size:           4
        .value_kind:     hidden_dynamic_lds_size
    .group_segment_fixed_size: 0
    .kernarg_segment_align: 8
    .kernarg_segment_size: 472
    .language:       OpenCL C
    .language_version:
      - 2
      - 0
    .max_flat_workgroup_size: 512
    .name:           _Z10fwd_kernel6Params
    .private_segment_fixed_size: 0
    .sgpr_count:     108
    .sgpr_spill_count: 233
    .symbol:         _Z10fwd_kernel6Params.kd
    .uniform_work_group_size: 1
    .uses_dynamic_stack: false
    .vgpr_count:     256
    .vgpr_spill_count: 0
    .wavefront_size: 64
